# v55 + duplicate post-barrier lgkmcnt(0) removed (first MFMA directly follows the barrier)
# speedup vs baseline: 1.1544x; 1.0022x over previous
.LBB0_261:
	s_add_u32 s0, s76, 0xfff80080
	s_addc_u32 s1, s77, -1
	s_and_b64 s[84:85], s[84:85], exec
	s_cselect_b32 vcc_hi, s22, s1
	s_cselect_b32 vcc_lo, s23, s0
	s_cselect_b32 s85, s49, s58
	s_cselect_b32 s84, s57, s51
	s_add_i32 s0, 0, 0x10000
	s_add_i32 s1, 0, 0x14000
	v_add_u32_e32 v158, s0, v176
	v_add_u32_e32 v174, s1, v176
	ds_read_b128 v[146:149], v158
	ds_read_b128 v[150:153], v158 offset:1024
	ds_read_b128 v[154:157], v158 offset:2048
	ds_read_b128 v[158:161], v158 offset:3072
	ds_read_b128 v[162:165], v174
	ds_read_b128 v[166:169], v174 offset:1024
	ds_read_b128 v[170:173], v174 offset:2048
	ds_read_b128 v[178:181], v174 offset:3072
	s_add_i32 m0, s21, 0xc000
	ds_read_b128 v[182:185], v177
	ds_read_b128 v[186:189], v177 offset:1024
	ds_read_b128 v[190:193], v177 offset:2048
	ds_read_b128 v[204:207], v177 offset:3072
	ds_read_b128 v[208:211], v177 offset:4096
	ds_read_b128 v[212:215], v177 offset:5120
	ds_read_b128 v[216:219], v177 offset:6144
	ds_read_b128 v[220:223], v177 offset:7168
	global_load_lds_dwordx4 v138, s[76:77]
	s_add_i32 m0, s21, 0xe000
	s_nop 0
	global_load_lds_dwordx4 v140, s[76:77]
	s_waitcnt vmcnt(8)
	s_waitcnt lgkmcnt(0)
	s_barrier
	v_mfma_f32_16x16x32_bf16 v[126:129], v[146:149], v[182:185], v[126:129]
	v_mfma_f32_16x16x32_bf16 v[126:129], v[150:153], v[186:189], v[126:129]
	v_mfma_f32_16x16x32_bf16 v[122:125], v[158:161], v[186:189], v[122:125]
	v_mfma_f32_16x16x32_bf16 v[122:125], v[154:157], v[182:185], v[122:125]
	v_mfma_f32_16x16x32_bf16 v[118:121], v[162:165], v[182:185], v[118:121]
	v_mfma_f32_16x16x32_bf16 v[118:121], v[166:169], v[186:189], v[118:121]
	v_mfma_f32_16x16x32_bf16 v[114:117], v[178:181], v[186:189], v[114:117]
	v_mfma_f32_16x16x32_bf16 v[114:117], v[170:173], v[182:185], v[114:117]
	v_mfma_f32_16x16x32_bf16 v[98:101], v[170:173], v[190:193], v[98:101]
	v_mfma_f32_16x16x32_bf16 v[98:101], v[178:181], v[204:207], v[98:101]
	v_mfma_f32_16x16x32_bf16 v[102:105], v[166:169], v[204:207], v[102:105]
	v_mfma_f32_16x16x32_bf16 v[102:105], v[162:165], v[190:193], v[102:105]
	v_mfma_f32_16x16x32_bf16 v[106:109], v[154:157], v[190:193], v[106:109]
	v_mfma_f32_16x16x32_bf16 v[106:109], v[158:161], v[204:207], v[106:109]
	v_mfma_f32_16x16x32_bf16 v[110:113], v[150:153], v[204:207], v[110:113]
	v_mfma_f32_16x16x32_bf16 v[110:113], v[146:149], v[190:193], v[110:113]
	v_mfma_f32_16x16x32_bf16 v[94:97], v[146:149], v[208:211], v[94:97]
	v_mfma_f32_16x16x32_bf16 v[94:97], v[150:153], v[212:215], v[94:97]
	v_mfma_f32_16x16x32_bf16 v[90:93], v[158:161], v[212:215], v[90:93]
	v_mfma_f32_16x16x32_bf16 v[90:93], v[154:157], v[208:211], v[90:93]
	v_mfma_f32_16x16x32_bf16 v[86:89], v[162:165], v[208:211], v[86:89]
	v_mfma_f32_16x16x32_bf16 v[86:89], v[166:169], v[212:215], v[86:89]
	v_mfma_f32_16x16x32_bf16 v[82:85], v[178:181], v[212:215], v[82:85]
	v_mfma_f32_16x16x32_bf16 v[82:85], v[170:173], v[208:211], v[82:85]
	v_mfma_f32_16x16x32_bf16 v[66:69], v[170:173], v[216:219], v[66:69]
	v_mfma_f32_16x16x32_bf16 v[66:69], v[178:181], v[220:223], v[66:69]
	v_mfma_f32_16x16x32_bf16 v[70:73], v[166:169], v[220:223], v[70:73]
	v_mfma_f32_16x16x32_bf16 v[70:73], v[162:165], v[216:219], v[70:73]
	v_mfma_f32_16x16x32_bf16 v[74:77], v[154:157], v[216:219], v[74:77]
	v_mfma_f32_16x16x32_bf16 v[74:77], v[158:161], v[220:223], v[74:77]
	v_mfma_f32_16x16x32_bf16 v[78:81], v[150:153], v[220:223], v[78:81]
	v_mfma_f32_16x16x32_bf16 v[78:81], v[146:149], v[216:219], v[78:81]
	s_barrier
	s_add_i32 s0, s0, s20
	s_mov_b32 m0, s0
	ds_read_b128 v[182:185], v177 offset:16384
	ds_read_b128 v[186:189], v177 offset:17408
	ds_read_b128 v[190:193], v177 offset:18432
	ds_read_b128 v[204:207], v177 offset:19456
	ds_read_b128 v[208:211], v177 offset:20480
	ds_read_b128 v[212:215], v177 offset:21504
	ds_read_b128 v[216:219], v177 offset:22528
	ds_read_b128 v[220:223], v177 offset:23552
	global_load_lds_dwordx4 v132, s[84:85]
	s_add_i32 m0, s0, 0x2000
	s_add_u32 s94, s84, 0x80000
	s_addc_u32 s95, s85, 0
	s_add_i32 s0, s1, s20
	global_load_lds_dwordx4 v130, s[84:85]
	s_mov_b32 m0, s0
	s_nop 0
	global_load_lds_dwordx4 v132, s[94:95]
	s_add_i32 m0, s0, 0x2000
	s_nop 0
	global_load_lds_dwordx4 v130, s[94:95]
	s_mov_b32 m0, s21
	s_nop 0
	global_load_lds_dwordx4 v132, vcc
	s_mov_b32 m0, s26
	s_nop 0
	global_load_lds_dwordx4 v130, vcc
	s_waitcnt vmcnt(8)
	s_waitcnt lgkmcnt(0)
	s_barrier
	v_mfma_f32_16x16x32_bf16 v[62:65], v[146:149], v[182:185], v[62:65]
	v_mfma_f32_16x16x32_bf16 v[62:65], v[150:153], v[186:189], v[62:65]
	v_mfma_f32_16x16x32_bf16 v[58:61], v[158:161], v[186:189], v[58:61]
	v_mfma_f32_16x16x32_bf16 v[58:61], v[154:157], v[182:185], v[58:61]
	v_mfma_f32_16x16x32_bf16 v[54:57], v[162:165], v[182:185], v[54:57]
	v_mfma_f32_16x16x32_bf16 v[54:57], v[166:169], v[186:189], v[54:57]
	v_mfma_f32_16x16x32_bf16 v[50:53], v[178:181], v[186:189], v[50:53]
	v_mfma_f32_16x16x32_bf16 v[50:53], v[170:173], v[182:185], v[50:53]
	v_mfma_f32_16x16x32_bf16 v[34:37], v[170:173], v[190:193], v[34:37]
	v_mfma_f32_16x16x32_bf16 v[34:37], v[178:181], v[204:207], v[34:37]
	v_mfma_f32_16x16x32_bf16 v[38:41], v[166:169], v[204:207], v[38:41]
	v_mfma_f32_16x16x32_bf16 v[38:41], v[162:165], v[190:193], v[38:41]
	v_mfma_f32_16x16x32_bf16 v[42:45], v[154:157], v[190:193], v[42:45]
	v_mfma_f32_16x16x32_bf16 v[42:45], v[158:161], v[204:207], v[42:45]
	v_mfma_f32_16x16x32_bf16 v[46:49], v[150:153], v[204:207], v[46:49]
	v_mfma_f32_16x16x32_bf16 v[46:49], v[146:149], v[190:193], v[46:49]
	v_mfma_f32_16x16x32_bf16 v[30:33], v[146:149], v[208:211], v[30:33]
	v_mfma_f32_16x16x32_bf16 v[30:33], v[150:153], v[212:215], v[30:33]
	v_mfma_f32_16x16x32_bf16 v[26:29], v[158:161], v[212:215], v[26:29]
	v_mfma_f32_16x16x32_bf16 v[26:29], v[154:157], v[208:211], v[26:29]
	v_mfma_f32_16x16x32_bf16 v[22:25], v[162:165], v[208:211], v[22:25]
	v_mfma_f32_16x16x32_bf16 v[22:25], v[166:169], v[212:215], v[22:25]
	v_mfma_f32_16x16x32_bf16 v[18:21], v[178:181], v[212:215], v[18:21]
	v_mfma_f32_16x16x32_bf16 v[18:21], v[170:173], v[208:211], v[18:21]
	v_mfma_f32_16x16x32_bf16 v[2:5], v[170:173], v[216:219], v[2:5]
	v_mfma_f32_16x16x32_bf16 v[2:5], v[178:181], v[220:223], v[2:5]
	v_mfma_f32_16x16x32_bf16 v[6:9], v[166:169], v[220:223], v[6:9]
	v_mfma_f32_16x16x32_bf16 v[6:9], v[162:165], v[216:219], v[6:9]
	v_mfma_f32_16x16x32_bf16 v[10:13], v[154:157], v[216:219], v[10:13]
	v_mfma_f32_16x16x32_bf16 v[10:13], v[158:161], v[220:223], v[10:13]
	v_mfma_f32_16x16x32_bf16 v[14:17], v[150:153], v[220:223], v[14:17]
	v_mfma_f32_16x16x32_bf16 v[14:17], v[146:149], v[216:219], v[14:17]
	s_barrier
	s_add_i32 s0, 0, 0x18000
	s_add_i32 s1, 0, 0x1c000
	v_add_u32_e32 v158, s0, v176
	v_add_u32_e32 v178, s1, v176
	ds_read_b128 v[146:149], v158
	ds_read_b128 v[150:153], v158 offset:1024
	ds_read_b128 v[154:157], v158 offset:2048
	ds_read_b128 v[158:161], v158 offset:3072
	ds_read_b128 v[162:165], v178
	ds_read_b128 v[166:169], v178 offset:1024
	ds_read_b128 v[170:173], v178 offset:2048
	ds_read_b128 v[178:181], v178 offset:3072
	s_add_u32 s94, vcc_lo, 0x80000
	s_addc_u32 s95, vcc_hi, 0
	s_mov_b32 m0, s27
	ds_read_b128 v[182:185], v177 offset:32768
	ds_read_b128 v[186:189], v177 offset:33792
	ds_read_b128 v[190:193], v177 offset:34816
	ds_read_b128 v[204:207], v177 offset:35840
	ds_read_b128 v[208:211], v177 offset:36864
	ds_read_b128 v[212:215], v177 offset:37888
	ds_read_b128 v[216:219], v177 offset:38912
	ds_read_b128 v[220:223], v177 offset:39936
	global_load_lds_dwordx4 v132, s[94:95]
	s_mov_b32 m0, s29
	s_nop 0
	global_load_lds_dwordx4 v130, s[94:95]
	s_waitcnt vmcnt(8)
	s_waitcnt lgkmcnt(0)
	s_barrier
	v_mfma_f32_16x16x32_bf16 v[126:129], v[146:149], v[182:185], v[126:129]
	v_mfma_f32_16x16x32_bf16 v[126:129], v[150:153], v[186:189], v[126:129]
	v_mfma_f32_16x16x32_bf16 v[122:125], v[158:161], v[186:189], v[122:125]
	v_mfma_f32_16x16x32_bf16 v[122:125], v[154:157], v[182:185], v[122:125]
	v_mfma_f32_16x16x32_bf16 v[118:121], v[162:165], v[182:185], v[118:121]
	v_mfma_f32_16x16x32_bf16 v[118:121], v[166:169], v[186:189], v[118:121]
	v_mfma_f32_16x16x32_bf16 v[114:117], v[178:181], v[186:189], v[114:117]
	v_mfma_f32_16x16x32_bf16 v[114:117], v[170:173], v[182:185], v[114:117]
	v_mfma_f32_16x16x32_bf16 v[98:101], v[170:173], v[190:193], v[98:101]
	v_mfma_f32_16x16x32_bf16 v[98:101], v[178:181], v[204:207], v[98:101]
	v_mfma_f32_16x16x32_bf16 v[102:105], v[166:169], v[204:207], v[102:105]
	v_mfma_f32_16x16x32_bf16 v[102:105], v[162:165], v[190:193], v[102:105]
	v_mfma_f32_16x16x32_bf16 v[106:109], v[154:157], v[190:193], v[106:109]
	v_mfma_f32_16x16x32_bf16 v[106:109], v[158:161], v[204:207], v[106:109]
	v_mfma_f32_16x16x32_bf16 v[110:113], v[150:153], v[204:207], v[110:113]
	v_mfma_f32_16x16x32_bf16 v[110:113], v[146:149], v[190:193], v[110:113]
	v_mfma_f32_16x16x32_bf16 v[94:97], v[146:149], v[208:211], v[94:97]
	v_mfma_f32_16x16x32_bf16 v[94:97], v[150:153], v[212:215], v[94:97]
	v_mfma_f32_16x16x32_bf16 v[90:93], v[158:161], v[212:215], v[90:93]
	v_mfma_f32_16x16x32_bf16 v[90:93], v[154:157], v[208:211], v[90:93]
	v_mfma_f32_16x16x32_bf16 v[86:89], v[162:165], v[208:211], v[86:89]
	v_mfma_f32_16x16x32_bf16 v[86:89], v[166:169], v[212:215], v[86:89]
	v_mfma_f32_16x16x32_bf16 v[82:85], v[178:181], v[212:215], v[82:85]
	v_mfma_f32_16x16x32_bf16 v[82:85], v[170:173], v[208:211], v[82:85]
	v_mfma_f32_16x16x32_bf16 v[66:69], v[170:173], v[216:219], v[66:69]
	v_mfma_f32_16x16x32_bf16 v[66:69], v[178:181], v[220:223], v[66:69]
	v_mfma_f32_16x16x32_bf16 v[70:73], v[166:169], v[220:223], v[70:73]
	v_mfma_f32_16x16x32_bf16 v[70:73], v[162:165], v[216:219], v[70:73]
	v_mfma_f32_16x16x32_bf16 v[74:77], v[154:157], v[216:219], v[74:77]
	v_mfma_f32_16x16x32_bf16 v[74:77], v[158:161], v[220:223], v[74:77]
	v_mfma_f32_16x16x32_bf16 v[78:81], v[150:153], v[220:223], v[78:81]
	v_mfma_f32_16x16x32_bf16 v[78:81], v[146:149], v[216:219], v[78:81]
	s_barrier
	s_add_u32 s98, s84, 0x80
	s_addc_u32 s99, s85, 0
	s_add_u32 s100, vcc_lo, 0x80
	s_addc_u32 s101, vcc_hi, 0
	s_add_i32 s0, s0, s20
	s_mov_b32 m0, s0
	ds_read_b128 v[182:185], v177 offset:49152
	ds_read_b128 v[186:189], v177 offset:50176
	ds_read_b128 v[190:193], v177 offset:51200
	ds_read_b128 v[204:207], v177 offset:52224
	ds_read_b128 v[208:211], v177 offset:53248
	ds_read_b128 v[212:215], v177 offset:54272
	ds_read_b128 v[216:219], v177 offset:55296
	ds_read_b128 v[220:223], v177 offset:56320
	global_load_lds_dwordx4 v132, s[98:99]
	s_add_i32 m0, s0, 0x2000
	s_add_u32 s84, s84, 0x80080
	s_addc_u32 s85, s85, 0
	s_add_i32 s0, s1, s20
	global_load_lds_dwordx4 v130, s[98:99]
	s_mov_b32 m0, s0
	s_nop 0
	global_load_lds_dwordx4 v132, s[84:85]
	s_add_i32 m0, s0, 0x2000
	s_nop 0
	global_load_lds_dwordx4 v130, s[84:85]
	s_mov_b32 m0, s40
	s_nop 0
	global_load_lds_dwordx4 v132, s[100:101]
	s_mov_b32 m0, s41
	s_nop 0
	global_load_lds_dwordx4 v130, s[100:101]
	s_waitcnt vmcnt(8)
	s_waitcnt lgkmcnt(0)
	s_barrier
	v_mfma_f32_16x16x32_bf16 v[62:65], v[146:149], v[182:185], v[62:65]
	v_mfma_f32_16x16x32_bf16 v[62:65], v[150:153], v[186:189], v[62:65]
	v_mfma_f32_16x16x32_bf16 v[58:61], v[158:161], v[186:189], v[58:61]
	v_mfma_f32_16x16x32_bf16 v[58:61], v[154:157], v[182:185], v[58:61]
	v_mfma_f32_16x16x32_bf16 v[54:57], v[162:165], v[182:185], v[54:57]
	v_mfma_f32_16x16x32_bf16 v[54:57], v[166:169], v[186:189], v[54:57]
	v_mfma_f32_16x16x32_bf16 v[50:53], v[178:181], v[186:189], v[50:53]
	v_mfma_f32_16x16x32_bf16 v[50:53], v[170:173], v[182:185], v[50:53]
	v_mfma_f32_16x16x32_bf16 v[34:37], v[170:173], v[190:193], v[34:37]
	v_mfma_f32_16x16x32_bf16 v[34:37], v[178:181], v[204:207], v[34:37]
	v_mfma_f32_16x16x32_bf16 v[38:41], v[166:169], v[204:207], v[38:41]
	v_mfma_f32_16x16x32_bf16 v[38:41], v[162:165], v[190:193], v[38:41]
	v_mfma_f32_16x16x32_bf16 v[42:45], v[154:157], v[190:193], v[42:45]
	v_mfma_f32_16x16x32_bf16 v[42:45], v[158:161], v[204:207], v[42:45]
	v_mfma_f32_16x16x32_bf16 v[46:49], v[150:153], v[204:207], v[46:49]
	v_mfma_f32_16x16x32_bf16 v[46:49], v[146:149], v[190:193], v[46:49]
	v_mfma_f32_16x16x32_bf16 v[30:33], v[146:149], v[208:211], v[30:33]
	v_mfma_f32_16x16x32_bf16 v[30:33], v[150:153], v[212:215], v[30:33]
	v_mfma_f32_16x16x32_bf16 v[26:29], v[158:161], v[212:215], v[26:29]
	v_mfma_f32_16x16x32_bf16 v[26:29], v[154:157], v[208:211], v[26:29]
	v_mfma_f32_16x16x32_bf16 v[22:25], v[162:165], v[208:211], v[22:25]
	v_mfma_f32_16x16x32_bf16 v[22:25], v[166:169], v[212:215], v[22:25]
	v_mfma_f32_16x16x32_bf16 v[18:21], v[178:181], v[212:215], v[18:21]
	v_mfma_f32_16x16x32_bf16 v[18:21], v[170:173], v[208:211], v[18:21]
	v_mfma_f32_16x16x32_bf16 v[2:5], v[170:173], v[216:219], v[2:5]
	v_mfma_f32_16x16x32_bf16 v[2:5], v[178:181], v[220:223], v[2:5]
	v_mfma_f32_16x16x32_bf16 v[6:9], v[166:169], v[220:223], v[6:9]
	v_mfma_f32_16x16x32_bf16 v[6:9], v[162:165], v[216:219], v[6:9]
	v_mfma_f32_16x16x32_bf16 v[10:13], v[154:157], v[216:219], v[10:13]
	v_mfma_f32_16x16x32_bf16 v[10:13], v[158:161], v[220:223], v[10:13]
	v_mfma_f32_16x16x32_bf16 v[14:17], v[150:153], v[220:223], v[14:17]
	v_mfma_f32_16x16x32_bf16 v[14:17], v[146:149], v[216:219], v[14:17]
	s_barrier
	s_add_i32 s65, s65, 2
	s_add_u32 s76, s76, 0x100
	s_addc_u32 s77, s77, 0
	s_add_u32 s51, s51, 0x100
	s_addc_u32 s58, s58, 0
	s_cmp_gt_u32 s65, 29
	s_cbranch_scc1 .LBB0_264

.Lpeel_disp_ine:
	s_cmp_lg_u32 s65, -2
	s_cbranch_scc1 .LBB0_261
	s_add_u32 s0, s76, 0xfff80080
	s_addc_u32 s1, s77, -1
	s_and_b64 s[84:85], s[84:85], exec
	s_cselect_b32 vcc_hi, s22, s1
	s_cselect_b32 vcc_lo, s23, s0
	s_cselect_b32 s85, s49, s58
	s_cselect_b32 s84, s57, s51
	s_add_i32 s0, 0, 0x10000
	s_add_i32 s1, 0, 0x14000
	v_add_u32_e32 v158, s0, v176
	v_add_u32_e32 v174, s1, v176
	ds_read_b128 v[146:149], v158
	ds_read_b128 v[150:153], v158 offset:1024
	ds_read_b128 v[154:157], v158 offset:2048
	ds_read_b128 v[158:161], v158 offset:3072
	ds_read_b128 v[162:165], v174
	ds_read_b128 v[166:169], v174 offset:1024
	ds_read_b128 v[170:173], v174 offset:2048
	ds_read_b128 v[178:181], v174 offset:3072
	s_add_i32 m0, s21, 0xc000
	ds_read_b128 v[182:185], v177
	ds_read_b128 v[186:189], v177 offset:1024
	ds_read_b128 v[190:193], v177 offset:2048
	ds_read_b128 v[204:207], v177 offset:3072
	ds_read_b128 v[208:211], v177 offset:4096
	ds_read_b128 v[212:215], v177 offset:5120
	ds_read_b128 v[216:219], v177 offset:6144
	ds_read_b128 v[220:223], v177 offset:7168
	global_load_lds_dwordx4 v138, s[76:77]
	s_add_i32 m0, s21, 0xe000
	s_nop 0
	global_load_lds_dwordx4 v140, s[76:77]
	s_waitcnt vmcnt(8)
	s_waitcnt lgkmcnt(0)
	s_barrier
	v_mfma_f32_16x16x32_bf16 v[126:129], v[146:149], v[182:185], 0
	v_mfma_f32_16x16x32_bf16 v[126:129], v[150:153], v[186:189], v[126:129]
	v_mfma_f32_16x16x32_bf16 v[122:125], v[158:161], v[186:189], 0
	v_mfma_f32_16x16x32_bf16 v[122:125], v[154:157], v[182:185], v[122:125]
	v_mfma_f32_16x16x32_bf16 v[118:121], v[162:165], v[182:185], 0
	v_mfma_f32_16x16x32_bf16 v[118:121], v[166:169], v[186:189], v[118:121]
	v_mfma_f32_16x16x32_bf16 v[114:117], v[178:181], v[186:189], 0
	v_mfma_f32_16x16x32_bf16 v[114:117], v[170:173], v[182:185], v[114:117]
	v_mfma_f32_16x16x32_bf16 v[98:101], v[170:173], v[190:193], 0
	v_mfma_f32_16x16x32_bf16 v[98:101], v[178:181], v[204:207], v[98:101]
	v_mfma_f32_16x16x32_bf16 v[102:105], v[166:169], v[204:207], 0
	v_mfma_f32_16x16x32_bf16 v[102:105], v[162:165], v[190:193], v[102:105]
	v_mfma_f32_16x16x32_bf16 v[106:109], v[154:157], v[190:193], 0
	v_mfma_f32_16x16x32_bf16 v[106:109], v[158:161], v[204:207], v[106:109]
	v_mfma_f32_16x16x32_bf16 v[110:113], v[150:153], v[204:207], 0
	v_mfma_f32_16x16x32_bf16 v[110:113], v[146:149], v[190:193], v[110:113]
	v_mfma_f32_16x16x32_bf16 v[94:97], v[146:149], v[208:211], 0
	v_mfma_f32_16x16x32_bf16 v[94:97], v[150:153], v[212:215], v[94:97]
	v_mfma_f32_16x16x32_bf16 v[90:93], v[158:161], v[212:215], 0
	v_mfma_f32_16x16x32_bf16 v[90:93], v[154:157], v[208:211], v[90:93]
	v_mfma_f32_16x16x32_bf16 v[86:89], v[162:165], v[208:211], 0
	v_mfma_f32_16x16x32_bf16 v[86:89], v[166:169], v[212:215], v[86:89]
	v_mfma_f32_16x16x32_bf16 v[82:85], v[178:181], v[212:215], 0
	v_mfma_f32_16x16x32_bf16 v[82:85], v[170:173], v[208:211], v[82:85]
	v_mfma_f32_16x16x32_bf16 v[66:69], v[170:173], v[216:219], 0
	v_mfma_f32_16x16x32_bf16 v[66:69], v[178:181], v[220:223], v[66:69]
	v_mfma_f32_16x16x32_bf16 v[70:73], v[166:169], v[220:223], 0
	v_mfma_f32_16x16x32_bf16 v[70:73], v[162:165], v[216:219], v[70:73]
	v_mfma_f32_16x16x32_bf16 v[74:77], v[154:157], v[216:219], 0
	v_mfma_f32_16x16x32_bf16 v[74:77], v[158:161], v[220:223], v[74:77]
	v_mfma_f32_16x16x32_bf16 v[78:81], v[150:153], v[220:223], 0
	v_mfma_f32_16x16x32_bf16 v[78:81], v[146:149], v[216:219], v[78:81]
	s_barrier
	s_add_i32 s0, s0, s20
	s_mov_b32 m0, s0
	ds_read_b128 v[182:185], v177 offset:16384
	ds_read_b128 v[186:189], v177 offset:17408
	ds_read_b128 v[190:193], v177 offset:18432
	ds_read_b128 v[204:207], v177 offset:19456
	ds_read_b128 v[208:211], v177 offset:20480
	ds_read_b128 v[212:215], v177 offset:21504
	ds_read_b128 v[216:219], v177 offset:22528
	ds_read_b128 v[220:223], v177 offset:23552
	global_load_lds_dwordx4 v132, s[84:85]
	s_add_i32 m0, s0, 0x2000
	s_add_u32 s94, s84, 0x80000
	s_addc_u32 s95, s85, 0
	s_add_i32 s0, s1, s20
	global_load_lds_dwordx4 v130, s[84:85]
	s_mov_b32 m0, s0
	s_nop 0
	global_load_lds_dwordx4 v132, s[94:95]
	s_add_i32 m0, s0, 0x2000
	s_nop 0
	global_load_lds_dwordx4 v130, s[94:95]
	s_mov_b32 m0, s21
	s_nop 0
	global_load_lds_dwordx4 v132, vcc
	s_mov_b32 m0, s26
	s_nop 0
	global_load_lds_dwordx4 v130, vcc
	s_waitcnt vmcnt(8)
	s_waitcnt lgkmcnt(0)
	s_barrier
	v_mfma_f32_16x16x32_bf16 v[62:65], v[146:149], v[182:185], 0
	v_mfma_f32_16x16x32_bf16 v[62:65], v[150:153], v[186:189], v[62:65]
	v_mfma_f32_16x16x32_bf16 v[58:61], v[158:161], v[186:189], 0
	v_mfma_f32_16x16x32_bf16 v[58:61], v[154:157], v[182:185], v[58:61]
	v_mfma_f32_16x16x32_bf16 v[54:57], v[162:165], v[182:185], 0
	v_mfma_f32_16x16x32_bf16 v[54:57], v[166:169], v[186:189], v[54:57]
	v_mfma_f32_16x16x32_bf16 v[50:53], v[178:181], v[186:189], 0
	v_mfma_f32_16x16x32_bf16 v[50:53], v[170:173], v[182:185], v[50:53]
	v_mfma_f32_16x16x32_bf16 v[34:37], v[170:173], v[190:193], 0
	v_mfma_f32_16x16x32_bf16 v[34:37], v[178:181], v[204:207], v[34:37]
	v_mfma_f32_16x16x32_bf16 v[38:41], v[166:169], v[204:207], 0
	v_mfma_f32_16x16x32_bf16 v[38:41], v[162:165], v[190:193], v[38:41]
	v_mfma_f32_16x16x32_bf16 v[42:45], v[154:157], v[190:193], 0
	v_mfma_f32_16x16x32_bf16 v[42:45], v[158:161], v[204:207], v[42:45]
	v_mfma_f32_16x16x32_bf16 v[46:49], v[150:153], v[204:207], 0
	v_mfma_f32_16x16x32_bf16 v[46:49], v[146:149], v[190:193], v[46:49]
	v_mfma_f32_16x16x32_bf16 v[30:33], v[146:149], v[208:211], 0
	v_mfma_f32_16x16x32_bf16 v[30:33], v[150:153], v[212:215], v[30:33]
	v_mfma_f32_16x16x32_bf16 v[26:29], v[158:161], v[212:215], 0
	v_mfma_f32_16x16x32_bf16 v[26:29], v[154:157], v[208:211], v[26:29]
	v_mfma_f32_16x16x32_bf16 v[22:25], v[162:165], v[208:211], 0
	v_mfma_f32_16x16x32_bf16 v[22:25], v[166:169], v[212:215], v[22:25]
	v_mfma_f32_16x16x32_bf16 v[18:21], v[178:181], v[212:215], 0
	v_mfma_f32_16x16x32_bf16 v[18:21], v[170:173], v[208:211], v[18:21]
	v_mfma_f32_16x16x32_bf16 v[2:5], v[170:173], v[216:219], 0
	v_mfma_f32_16x16x32_bf16 v[2:5], v[178:181], v[220:223], v[2:5]
	v_mfma_f32_16x16x32_bf16 v[6:9], v[166:169], v[220:223], 0
	v_mfma_f32_16x16x32_bf16 v[6:9], v[162:165], v[216:219], v[6:9]
	v_mfma_f32_16x16x32_bf16 v[10:13], v[154:157], v[216:219], 0
	v_mfma_f32_16x16x32_bf16 v[10:13], v[158:161], v[220:223], v[10:13]
	v_mfma_f32_16x16x32_bf16 v[14:17], v[150:153], v[220:223], 0
	v_mfma_f32_16x16x32_bf16 v[14:17], v[146:149], v[216:219], v[14:17]
	s_barrier
	s_add_i32 s0, 0, 0x18000
	s_add_i32 s1, 0, 0x1c000
	v_add_u32_e32 v158, s0, v176
	v_add_u32_e32 v178, s1, v176
	ds_read_b128 v[146:149], v158
	ds_read_b128 v[150:153], v158 offset:1024
	ds_read_b128 v[154:157], v158 offset:2048
	ds_read_b128 v[158:161], v158 offset:3072
	ds_read_b128 v[162:165], v178
	ds_read_b128 v[166:169], v178 offset:1024
	ds_read_b128 v[170:173], v178 offset:2048
	ds_read_b128 v[178:181], v178 offset:3072
	s_add_u32 s94, vcc_lo, 0x80000
	s_addc_u32 s95, vcc_hi, 0
	s_mov_b32 m0, s27
	ds_read_b128 v[182:185], v177 offset:32768
	ds_read_b128 v[186:189], v177 offset:33792
	ds_read_b128 v[190:193], v177 offset:34816
	ds_read_b128 v[204:207], v177 offset:35840
	ds_read_b128 v[208:211], v177 offset:36864
	ds_read_b128 v[212:215], v177 offset:37888
	ds_read_b128 v[216:219], v177 offset:38912
	ds_read_b128 v[220:223], v177 offset:39936
	global_load_lds_dwordx4 v132, s[94:95]
	s_mov_b32 m0, s29
	s_nop 0
	global_load_lds_dwordx4 v130, s[94:95]
	s_waitcnt vmcnt(8)
	s_waitcnt lgkmcnt(0)
	s_barrier
	v_mfma_f32_16x16x32_bf16 v[126:129], v[146:149], v[182:185], v[126:129]
	v_mfma_f32_16x16x32_bf16 v[126:129], v[150:153], v[186:189], v[126:129]
	v_mfma_f32_16x16x32_bf16 v[122:125], v[158:161], v[186:189], v[122:125]
	v_mfma_f32_16x16x32_bf16 v[122:125], v[154:157], v[182:185], v[122:125]
	v_mfma_f32_16x16x32_bf16 v[118:121], v[162:165], v[182:185], v[118:121]
	v_mfma_f32_16x16x32_bf16 v[118:121], v[166:169], v[186:189], v[118:121]
	v_mfma_f32_16x16x32_bf16 v[114:117], v[178:181], v[186:189], v[114:117]
	v_mfma_f32_16x16x32_bf16 v[114:117], v[170:173], v[182:185], v[114:117]
	v_mfma_f32_16x16x32_bf16 v[98:101], v[170:173], v[190:193], v[98:101]
	v_mfma_f32_16x16x32_bf16 v[98:101], v[178:181], v[204:207], v[98:101]
	v_mfma_f32_16x16x32_bf16 v[102:105], v[166:169], v[204:207], v[102:105]
	v_mfma_f32_16x16x32_bf16 v[102:105], v[162:165], v[190:193], v[102:105]
	v_mfma_f32_16x16x32_bf16 v[106:109], v[154:157], v[190:193], v[106:109]
	v_mfma_f32_16x16x32_bf16 v[106:109], v[158:161], v[204:207], v[106:109]
	v_mfma_f32_16x16x32_bf16 v[110:113], v[150:153], v[204:207], v[110:113]
	v_mfma_f32_16x16x32_bf16 v[110:113], v[146:149], v[190:193], v[110:113]
	v_mfma_f32_16x16x32_bf16 v[94:97], v[146:149], v[208:211], v[94:97]
	v_mfma_f32_16x16x32_bf16 v[94:97], v[150:153], v[212:215], v[94:97]
	v_mfma_f32_16x16x32_bf16 v[90:93], v[158:161], v[212:215], v[90:93]
	v_mfma_f32_16x16x32_bf16 v[90:93], v[154:157], v[208:211], v[90:93]
	v_mfma_f32_16x16x32_bf16 v[86:89], v[162:165], v[208:211], v[86:89]
	v_mfma_f32_16x16x32_bf16 v[86:89], v[166:169], v[212:215], v[86:89]
	v_mfma_f32_16x16x32_bf16 v[82:85], v[178:181], v[212:215], v[82:85]
	v_mfma_f32_16x16x32_bf16 v[82:85], v[170:173], v[208:211], v[82:85]
	v_mfma_f32_16x16x32_bf16 v[66:69], v[170:173], v[216:219], v[66:69]
	v_mfma_f32_16x16x32_bf16 v[66:69], v[178:181], v[220:223], v[66:69]
	v_mfma_f32_16x16x32_bf16 v[70:73], v[166:169], v[220:223], v[70:73]
	v_mfma_f32_16x16x32_bf16 v[70:73], v[162:165], v[216:219], v[70:73]
	v_mfma_f32_16x16x32_bf16 v[74:77], v[154:157], v[216:219], v[74:77]
	v_mfma_f32_16x16x32_bf16 v[74:77], v[158:161], v[220:223], v[74:77]
	v_mfma_f32_16x16x32_bf16 v[78:81], v[150:153], v[220:223], v[78:81]
	v_mfma_f32_16x16x32_bf16 v[78:81], v[146:149], v[216:219], v[78:81]
	s_barrier
	s_add_u32 s98, s84, 0x80
	s_addc_u32 s99, s85, 0
	s_add_u32 s100, vcc_lo, 0x80
	s_addc_u32 s101, vcc_hi, 0
	s_add_i32 s0, s0, s20
	s_mov_b32 m0, s0
	ds_read_b128 v[182:185], v177 offset:49152
	ds_read_b128 v[186:189], v177 offset:50176
	ds_read_b128 v[190:193], v177 offset:51200
	ds_read_b128 v[204:207], v177 offset:52224
	ds_read_b128 v[208:211], v177 offset:53248
	ds_read_b128 v[212:215], v177 offset:54272
	ds_read_b128 v[216:219], v177 offset:55296
	ds_read_b128 v[220:223], v177 offset:56320
	global_load_lds_dwordx4 v132, s[98:99]
	s_add_i32 m0, s0, 0x2000
	s_add_u32 s84, s84, 0x80080
	s_addc_u32 s85, s85, 0
	s_add_i32 s0, s1, s20
	global_load_lds_dwordx4 v130, s[98:99]
	s_mov_b32 m0, s0
	s_nop 0
	global_load_lds_dwordx4 v132, s[84:85]
	s_add_i32 m0, s0, 0x2000
	s_nop 0
	global_load_lds_dwordx4 v130, s[84:85]
	s_mov_b32 m0, s40
	s_nop 0
	global_load_lds_dwordx4 v132, s[100:101]
	s_mov_b32 m0, s41
	s_nop 0
	global_load_lds_dwordx4 v130, s[100:101]
	s_waitcnt vmcnt(8)
	s_waitcnt lgkmcnt(0)
	s_barrier
	v_mfma_f32_16x16x32_bf16 v[62:65], v[146:149], v[182:185], v[62:65]
	v_mfma_f32_16x16x32_bf16 v[62:65], v[150:153], v[186:189], v[62:65]
	v_mfma_f32_16x16x32_bf16 v[58:61], v[158:161], v[186:189], v[58:61]
	v_mfma_f32_16x16x32_bf16 v[58:61], v[154:157], v[182:185], v[58:61]
	v_mfma_f32_16x16x32_bf16 v[54:57], v[162:165], v[182:185], v[54:57]
	v_mfma_f32_16x16x32_bf16 v[54:57], v[166:169], v[186:189], v[54:57]
	v_mfma_f32_16x16x32_bf16 v[50:53], v[178:181], v[186:189], v[50:53]
	v_mfma_f32_16x16x32_bf16 v[50:53], v[170:173], v[182:185], v[50:53]
	v_mfma_f32_16x16x32_bf16 v[34:37], v[170:173], v[190:193], v[34:37]
	v_mfma_f32_16x16x32_bf16 v[34:37], v[178:181], v[204:207], v[34:37]
	v_mfma_f32_16x16x32_bf16 v[38:41], v[166:169], v[204:207], v[38:41]
	v_mfma_f32_16x16x32_bf16 v[38:41], v[162:165], v[190:193], v[38:41]
	v_mfma_f32_16x16x32_bf16 v[42:45], v[154:157], v[190:193], v[42:45]
	v_mfma_f32_16x16x32_bf16 v[42:45], v[158:161], v[204:207], v[42:45]
	v_mfma_f32_16x16x32_bf16 v[46:49], v[150:153], v[204:207], v[46:49]
	v_mfma_f32_16x16x32_bf16 v[46:49], v[146:149], v[190:193], v[46:49]
	v_mfma_f32_16x16x32_bf16 v[30:33], v[146:149], v[208:211], v[30:33]
	v_mfma_f32_16x16x32_bf16 v[30:33], v[150:153], v[212:215], v[30:33]
	v_mfma_f32_16x16x32_bf16 v[26:29], v[158:161], v[212:215], v[26:29]
	v_mfma_f32_16x16x32_bf16 v[26:29], v[154:157], v[208:211], v[26:29]
	v_mfma_f32_16x16x32_bf16 v[22:25], v[162:165], v[208:211], v[22:25]
	v_mfma_f32_16x16x32_bf16 v[22:25], v[166:169], v[212:215], v[22:25]
	v_mfma_f32_16x16x32_bf16 v[18:21], v[178:181], v[212:215], v[18:21]
	v_mfma_f32_16x16x32_bf16 v[18:21], v[170:173], v[208:211], v[18:21]
	v_mfma_f32_16x16x32_bf16 v[2:5], v[170:173], v[216:219], v[2:5]
	v_mfma_f32_16x16x32_bf16 v[2:5], v[178:181], v[220:223], v[2:5]
	v_mfma_f32_16x16x32_bf16 v[6:9], v[166:169], v[220:223], v[6:9]
	v_mfma_f32_16x16x32_bf16 v[6:9], v[162:165], v[216:219], v[6:9]
	v_mfma_f32_16x16x32_bf16 v[10:13], v[154:157], v[216:219], v[10:13]
	v_mfma_f32_16x16x32_bf16 v[10:13], v[158:161], v[220:223], v[10:13]
	v_mfma_f32_16x16x32_bf16 v[14:17], v[150:153], v[220:223], v[14:17]
	v_mfma_f32_16x16x32_bf16 v[14:17], v[146:149], v[216:219], v[14:17]
	s_barrier
	s_add_i32 s65, s65, 2
	s_add_u32 s76, s76, 0x100
	s_addc_u32 s77, s77, 0
	s_add_u32 s51, s51, 0x100
	s_addc_u32 s58, s58, 0
	s_cmp_gt_u32 s65, 29
	s_cbranch_scc1 .LBB0_264
	s_branch .LBB0_262

.LBB0_285:
	s_add_u32 s0, s76, 0xfff80080
	s_addc_u32 s1, s77, -1
	s_and_b64 s[70:71], s[70:71], exec
	s_cselect_b32 vcc_hi, s21, s1
	s_cselect_b32 vcc_lo, s22, s0
	s_cselect_b32 s71, s23, s41
	s_cselect_b32 s70, s39, s7
	s_add_i32 s0, 0, 0x10000
	s_add_i32 s1, 0, 0x14000
	v_add_u32_e32 v146, s0, v1
	v_add_u32_e32 v174, s1, v1
	ds_read_b128 v[134:137], v146
	ds_read_b128 v[138:141], v146 offset:1024
	ds_read_b128 v[142:145], v146 offset:2048
	ds_read_b128 v[146:149], v146 offset:3072
	ds_read_b128 v[150:153], v174
	ds_read_b128 v[154:157], v174 offset:1024
	ds_read_b128 v[158:161], v174 offset:2048
	ds_read_b128 v[174:177], v174 offset:3072
	s_add_i32 m0, s67, 0xc000
	ds_read_b128 v[178:181], v222
	ds_read_b128 v[182:185], v222 offset:1024
	ds_read_b128 v[186:189], v222 offset:2048
	ds_read_b128 v[190:193], v222 offset:3072
	ds_read_b128 v[204:207], v222 offset:4096
	ds_read_b128 v[208:211], v222 offset:5120
	ds_read_b128 v[212:215], v222 offset:6144
	ds_read_b128 v[216:219], v222 offset:7168
	global_load_lds_dwordx4 v170, s[76:77]
	s_add_i32 m0, s67, 0xe000
	s_nop 0
	global_load_lds_dwordx4 v172, s[76:77]
	s_waitcnt vmcnt(8)
	s_waitcnt lgkmcnt(0)
	s_barrier
	v_mfma_f32_16x16x32_bf16 v[126:129], v[134:137], v[178:181], v[126:129]
	v_mfma_f32_16x16x32_bf16 v[126:129], v[138:141], v[182:185], v[126:129]
	v_mfma_f32_16x16x32_bf16 v[122:125], v[146:149], v[182:185], v[122:125]
	v_mfma_f32_16x16x32_bf16 v[122:125], v[142:145], v[178:181], v[122:125]
	v_mfma_f32_16x16x32_bf16 v[118:121], v[150:153], v[178:181], v[118:121]
	v_mfma_f32_16x16x32_bf16 v[118:121], v[154:157], v[182:185], v[118:121]
	v_mfma_f32_16x16x32_bf16 v[114:117], v[174:177], v[182:185], v[114:117]
	v_mfma_f32_16x16x32_bf16 v[114:117], v[158:161], v[178:181], v[114:117]
	v_mfma_f32_16x16x32_bf16 v[98:101], v[158:161], v[186:189], v[98:101]
	v_mfma_f32_16x16x32_bf16 v[98:101], v[174:177], v[190:193], v[98:101]
	v_mfma_f32_16x16x32_bf16 v[102:105], v[154:157], v[190:193], v[102:105]
	v_mfma_f32_16x16x32_bf16 v[102:105], v[150:153], v[186:189], v[102:105]
	v_mfma_f32_16x16x32_bf16 v[106:109], v[142:145], v[186:189], v[106:109]
	v_mfma_f32_16x16x32_bf16 v[106:109], v[146:149], v[190:193], v[106:109]
	v_mfma_f32_16x16x32_bf16 v[110:113], v[138:141], v[190:193], v[110:113]
	v_mfma_f32_16x16x32_bf16 v[110:113], v[134:137], v[186:189], v[110:113]
	v_mfma_f32_16x16x32_bf16 v[94:97], v[134:137], v[204:207], v[94:97]
	v_mfma_f32_16x16x32_bf16 v[94:97], v[138:141], v[208:211], v[94:97]
	v_mfma_f32_16x16x32_bf16 v[90:93], v[146:149], v[208:211], v[90:93]
	v_mfma_f32_16x16x32_bf16 v[90:93], v[142:145], v[204:207], v[90:93]
	v_mfma_f32_16x16x32_bf16 v[86:89], v[150:153], v[204:207], v[86:89]
	v_mfma_f32_16x16x32_bf16 v[86:89], v[154:157], v[208:211], v[86:89]
	v_mfma_f32_16x16x32_bf16 v[82:85], v[174:177], v[208:211], v[82:85]
	v_mfma_f32_16x16x32_bf16 v[82:85], v[158:161], v[204:207], v[82:85]
	v_mfma_f32_16x16x32_bf16 v[66:69], v[158:161], v[212:215], v[66:69]
	v_mfma_f32_16x16x32_bf16 v[66:69], v[174:177], v[216:219], v[66:69]
	v_mfma_f32_16x16x32_bf16 v[70:73], v[154:157], v[216:219], v[70:73]
	v_mfma_f32_16x16x32_bf16 v[70:73], v[150:153], v[212:215], v[70:73]
	v_mfma_f32_16x16x32_bf16 v[74:77], v[142:145], v[212:215], v[74:77]
	v_mfma_f32_16x16x32_bf16 v[74:77], v[146:149], v[216:219], v[74:77]
	v_mfma_f32_16x16x32_bf16 v[78:81], v[138:141], v[216:219], v[78:81]
	v_mfma_f32_16x16x32_bf16 v[78:81], v[134:137], v[212:215], v[78:81]
	s_barrier
	s_add_i32 s0, s0, s54
	s_mov_b32 m0, s0
	ds_read_b128 v[178:181], v222 offset:16384
	ds_read_b128 v[182:185], v222 offset:17408
	ds_read_b128 v[186:189], v222 offset:18432
	ds_read_b128 v[190:193], v222 offset:19456
	ds_read_b128 v[204:207], v222 offset:20480
	ds_read_b128 v[208:211], v222 offset:21504
	ds_read_b128 v[212:215], v222 offset:22528
	ds_read_b128 v[216:219], v222 offset:23552
	global_load_lds_dwordx4 v164, s[70:71]
	s_add_i32 m0, s0, 0x2000
	s_add_u32 s44, s70, 0x80000
	s_addc_u32 s45, s71, 0
	s_add_i32 s0, s1, s54
	global_load_lds_dwordx4 v162, s[70:71]
	s_mov_b32 m0, s0
	s_nop 0
	global_load_lds_dwordx4 v164, s[44:45]
	s_add_i32 m0, s0, 0x2000
	s_nop 0
	global_load_lds_dwordx4 v162, s[44:45]
	s_mov_b32 m0, s67
	s_nop 0
	global_load_lds_dwordx4 v164, vcc
	s_mov_b32 m0, s68
	s_nop 0
	global_load_lds_dwordx4 v162, vcc
	s_waitcnt vmcnt(8)
	s_waitcnt lgkmcnt(0)
	s_barrier
	v_mfma_f32_16x16x32_bf16 v[62:65], v[134:137], v[178:181], v[62:65]
	v_mfma_f32_16x16x32_bf16 v[62:65], v[138:141], v[182:185], v[62:65]
	v_mfma_f32_16x16x32_bf16 v[58:61], v[146:149], v[182:185], v[58:61]
	v_mfma_f32_16x16x32_bf16 v[58:61], v[142:145], v[178:181], v[58:61]
	v_mfma_f32_16x16x32_bf16 v[54:57], v[150:153], v[178:181], v[54:57]
	v_mfma_f32_16x16x32_bf16 v[54:57], v[154:157], v[182:185], v[54:57]
	v_mfma_f32_16x16x32_bf16 v[50:53], v[174:177], v[182:185], v[50:53]
	v_mfma_f32_16x16x32_bf16 v[50:53], v[158:161], v[178:181], v[50:53]
	v_mfma_f32_16x16x32_bf16 v[34:37], v[158:161], v[186:189], v[34:37]
	v_mfma_f32_16x16x32_bf16 v[34:37], v[174:177], v[190:193], v[34:37]
	v_mfma_f32_16x16x32_bf16 v[38:41], v[154:157], v[190:193], v[38:41]
	v_mfma_f32_16x16x32_bf16 v[38:41], v[150:153], v[186:189], v[38:41]
	v_mfma_f32_16x16x32_bf16 v[42:45], v[142:145], v[186:189], v[42:45]
	v_mfma_f32_16x16x32_bf16 v[42:45], v[146:149], v[190:193], v[42:45]
	v_mfma_f32_16x16x32_bf16 v[46:49], v[138:141], v[190:193], v[46:49]
	v_mfma_f32_16x16x32_bf16 v[46:49], v[134:137], v[186:189], v[46:49]
	v_mfma_f32_16x16x32_bf16 v[30:33], v[134:137], v[204:207], v[30:33]
	v_mfma_f32_16x16x32_bf16 v[30:33], v[138:141], v[208:211], v[30:33]
	v_mfma_f32_16x16x32_bf16 v[26:29], v[146:149], v[208:211], v[26:29]
	v_mfma_f32_16x16x32_bf16 v[26:29], v[142:145], v[204:207], v[26:29]
	v_mfma_f32_16x16x32_bf16 v[22:25], v[150:153], v[204:207], v[22:25]
	v_mfma_f32_16x16x32_bf16 v[22:25], v[154:157], v[208:211], v[22:25]
	v_mfma_f32_16x16x32_bf16 v[18:21], v[174:177], v[208:211], v[18:21]
	v_mfma_f32_16x16x32_bf16 v[18:21], v[158:161], v[204:207], v[18:21]
	v_mfma_f32_16x16x32_bf16 v[2:5], v[158:161], v[212:215], v[2:5]
	v_mfma_f32_16x16x32_bf16 v[2:5], v[174:177], v[216:219], v[2:5]
	v_mfma_f32_16x16x32_bf16 v[6:9], v[154:157], v[216:219], v[6:9]
	v_mfma_f32_16x16x32_bf16 v[6:9], v[150:153], v[212:215], v[6:9]
	v_mfma_f32_16x16x32_bf16 v[10:13], v[142:145], v[212:215], v[10:13]
	v_mfma_f32_16x16x32_bf16 v[10:13], v[146:149], v[216:219], v[10:13]
	v_mfma_f32_16x16x32_bf16 v[14:17], v[138:141], v[216:219], v[14:17]
	v_mfma_f32_16x16x32_bf16 v[14:17], v[134:137], v[212:215], v[14:17]
	s_barrier
	s_add_i32 s0, 0, 0x18000
	s_add_i32 s1, 0, 0x1c000
	v_add_u32_e32 v146, s0, v1
	v_add_u32_e32 v174, s1, v1
	ds_read_b128 v[134:137], v146
	ds_read_b128 v[138:141], v146 offset:1024
	ds_read_b128 v[142:145], v146 offset:2048
	ds_read_b128 v[146:149], v146 offset:3072
	ds_read_b128 v[150:153], v174
	ds_read_b128 v[154:157], v174 offset:1024
	ds_read_b128 v[158:161], v174 offset:2048
	ds_read_b128 v[174:177], v174 offset:3072
	s_add_u32 s44, vcc_lo, 0x80000
	s_addc_u32 s45, vcc_hi, 0
	s_mov_b32 m0, s8
	ds_read_b128 v[178:181], v222 offset:32768
	ds_read_b128 v[182:185], v222 offset:33792
	ds_read_b128 v[186:189], v222 offset:34816
	ds_read_b128 v[190:193], v222 offset:35840
	ds_read_b128 v[204:207], v222 offset:36864
	ds_read_b128 v[208:211], v222 offset:37888
	ds_read_b128 v[212:215], v222 offset:38912
	ds_read_b128 v[216:219], v222 offset:39936
	global_load_lds_dwordx4 v164, s[44:45]
	s_mov_b32 m0, s9
	s_nop 0
	global_load_lds_dwordx4 v162, s[44:45]
	s_waitcnt vmcnt(8)
	s_waitcnt lgkmcnt(0)
	s_barrier
	v_mfma_f32_16x16x32_bf16 v[126:129], v[134:137], v[178:181], v[126:129]
	v_mfma_f32_16x16x32_bf16 v[126:129], v[138:141], v[182:185], v[126:129]
	v_mfma_f32_16x16x32_bf16 v[122:125], v[146:149], v[182:185], v[122:125]
	v_mfma_f32_16x16x32_bf16 v[122:125], v[142:145], v[178:181], v[122:125]
	v_mfma_f32_16x16x32_bf16 v[118:121], v[150:153], v[178:181], v[118:121]
	v_mfma_f32_16x16x32_bf16 v[118:121], v[154:157], v[182:185], v[118:121]
	v_mfma_f32_16x16x32_bf16 v[114:117], v[174:177], v[182:185], v[114:117]
	v_mfma_f32_16x16x32_bf16 v[114:117], v[158:161], v[178:181], v[114:117]
	v_mfma_f32_16x16x32_bf16 v[98:101], v[158:161], v[186:189], v[98:101]
	v_mfma_f32_16x16x32_bf16 v[98:101], v[174:177], v[190:193], v[98:101]
	v_mfma_f32_16x16x32_bf16 v[102:105], v[154:157], v[190:193], v[102:105]
	v_mfma_f32_16x16x32_bf16 v[102:105], v[150:153], v[186:189], v[102:105]
	v_mfma_f32_16x16x32_bf16 v[106:109], v[142:145], v[186:189], v[106:109]
	v_mfma_f32_16x16x32_bf16 v[106:109], v[146:149], v[190:193], v[106:109]
	v_mfma_f32_16x16x32_bf16 v[110:113], v[138:141], v[190:193], v[110:113]
	v_mfma_f32_16x16x32_bf16 v[110:113], v[134:137], v[186:189], v[110:113]
	v_mfma_f32_16x16x32_bf16 v[94:97], v[134:137], v[204:207], v[94:97]
	v_mfma_f32_16x16x32_bf16 v[94:97], v[138:141], v[208:211], v[94:97]
	v_mfma_f32_16x16x32_bf16 v[90:93], v[146:149], v[208:211], v[90:93]
	v_mfma_f32_16x16x32_bf16 v[90:93], v[142:145], v[204:207], v[90:93]
	v_mfma_f32_16x16x32_bf16 v[86:89], v[150:153], v[204:207], v[86:89]
	v_mfma_f32_16x16x32_bf16 v[86:89], v[154:157], v[208:211], v[86:89]
	v_mfma_f32_16x16x32_bf16 v[82:85], v[174:177], v[208:211], v[82:85]
	v_mfma_f32_16x16x32_bf16 v[82:85], v[158:161], v[204:207], v[82:85]
	v_mfma_f32_16x16x32_bf16 v[66:69], v[158:161], v[212:215], v[66:69]
	v_mfma_f32_16x16x32_bf16 v[66:69], v[174:177], v[216:219], v[66:69]
	v_mfma_f32_16x16x32_bf16 v[70:73], v[154:157], v[216:219], v[70:73]
	v_mfma_f32_16x16x32_bf16 v[70:73], v[150:153], v[212:215], v[70:73]
	v_mfma_f32_16x16x32_bf16 v[74:77], v[142:145], v[212:215], v[74:77]
	v_mfma_f32_16x16x32_bf16 v[74:77], v[146:149], v[216:219], v[74:77]
	v_mfma_f32_16x16x32_bf16 v[78:81], v[138:141], v[216:219], v[78:81]
	v_mfma_f32_16x16x32_bf16 v[78:81], v[134:137], v[212:215], v[78:81]
	s_barrier
	s_add_u32 s98, s70, 0x80
	s_addc_u32 s99, s71, 0
	s_add_u32 s100, vcc_lo, 0x80
	s_addc_u32 s101, vcc_hi, 0
	s_add_i32 s0, s0, s54
	s_mov_b32 m0, s0
	ds_read_b128 v[178:181], v222 offset:49152
	ds_read_b128 v[182:185], v222 offset:50176
	ds_read_b128 v[186:189], v222 offset:51200
	ds_read_b128 v[190:193], v222 offset:52224
	ds_read_b128 v[204:207], v222 offset:53248
	ds_read_b128 v[208:211], v222 offset:54272
	ds_read_b128 v[212:215], v222 offset:55296
	ds_read_b128 v[216:219], v222 offset:56320
	global_load_lds_dwordx4 v164, s[98:99]
	s_add_i32 m0, s0, 0x2000
	s_add_u32 s44, s70, 0x80080
	s_addc_u32 s45, s71, 0
	s_add_i32 s0, s1, s54
	global_load_lds_dwordx4 v162, s[98:99]
	s_mov_b32 m0, s0
	s_nop 0
	global_load_lds_dwordx4 v164, s[44:45]
	s_add_i32 m0, s0, 0x2000
	s_nop 0
	global_load_lds_dwordx4 v162, s[44:45]
	s_mov_b32 m0, s27
	s_nop 0
	global_load_lds_dwordx4 v164, s[100:101]
	s_mov_b32 m0, s26
	s_nop 0
	global_load_lds_dwordx4 v162, s[100:101]
	s_waitcnt vmcnt(8)
	s_waitcnt lgkmcnt(0)
	s_barrier
	v_mfma_f32_16x16x32_bf16 v[62:65], v[134:137], v[178:181], v[62:65]
	v_mfma_f32_16x16x32_bf16 v[62:65], v[138:141], v[182:185], v[62:65]
	v_mfma_f32_16x16x32_bf16 v[58:61], v[146:149], v[182:185], v[58:61]
	v_mfma_f32_16x16x32_bf16 v[58:61], v[142:145], v[178:181], v[58:61]
	v_mfma_f32_16x16x32_bf16 v[54:57], v[150:153], v[178:181], v[54:57]
	v_mfma_f32_16x16x32_bf16 v[54:57], v[154:157], v[182:185], v[54:57]
	v_mfma_f32_16x16x32_bf16 v[50:53], v[174:177], v[182:185], v[50:53]
	v_mfma_f32_16x16x32_bf16 v[50:53], v[158:161], v[178:181], v[50:53]
	v_mfma_f32_16x16x32_bf16 v[34:37], v[158:161], v[186:189], v[34:37]
	v_mfma_f32_16x16x32_bf16 v[34:37], v[174:177], v[190:193], v[34:37]
	v_mfma_f32_16x16x32_bf16 v[38:41], v[154:157], v[190:193], v[38:41]
	v_mfma_f32_16x16x32_bf16 v[38:41], v[150:153], v[186:189], v[38:41]
	v_mfma_f32_16x16x32_bf16 v[42:45], v[142:145], v[186:189], v[42:45]
	v_mfma_f32_16x16x32_bf16 v[42:45], v[146:149], v[190:193], v[42:45]
	v_mfma_f32_16x16x32_bf16 v[46:49], v[138:141], v[190:193], v[46:49]
	v_mfma_f32_16x16x32_bf16 v[46:49], v[134:137], v[186:189], v[46:49]
	v_mfma_f32_16x16x32_bf16 v[30:33], v[134:137], v[204:207], v[30:33]
	v_mfma_f32_16x16x32_bf16 v[30:33], v[138:141], v[208:211], v[30:33]
	v_mfma_f32_16x16x32_bf16 v[26:29], v[146:149], v[208:211], v[26:29]
	v_mfma_f32_16x16x32_bf16 v[26:29], v[142:145], v[204:207], v[26:29]
	v_mfma_f32_16x16x32_bf16 v[22:25], v[150:153], v[204:207], v[22:25]
	v_mfma_f32_16x16x32_bf16 v[22:25], v[154:157], v[208:211], v[22:25]
	v_mfma_f32_16x16x32_bf16 v[18:21], v[174:177], v[208:211], v[18:21]
	v_mfma_f32_16x16x32_bf16 v[18:21], v[158:161], v[204:207], v[18:21]
	v_mfma_f32_16x16x32_bf16 v[2:5], v[158:161], v[212:215], v[2:5]
	v_mfma_f32_16x16x32_bf16 v[2:5], v[174:177], v[216:219], v[2:5]
	v_mfma_f32_16x16x32_bf16 v[6:9], v[154:157], v[216:219], v[6:9]
	v_mfma_f32_16x16x32_bf16 v[6:9], v[150:153], v[212:215], v[6:9]
	v_mfma_f32_16x16x32_bf16 v[10:13], v[142:145], v[212:215], v[10:13]
	v_mfma_f32_16x16x32_bf16 v[10:13], v[146:149], v[216:219], v[10:13]
	v_mfma_f32_16x16x32_bf16 v[14:17], v[138:141], v[216:219], v[14:17]
	v_mfma_f32_16x16x32_bf16 v[14:17], v[134:137], v[212:215], v[14:17]
	s_barrier
	s_add_i32 s43, s43, 2
	s_add_u32 s76, s76, 0x100
	s_addc_u32 s77, s77, 0
	s_add_u32 s7, s7, 0x100
	s_addc_u32 s41, s41, 0
	s_cmp_gt_u32 s43, 29
	s_cbranch_scc1 .LBB0_288

.Lpeel_disp_ino:
	s_cmp_lg_u32 s43, -2
	s_cbranch_scc1 .LBB0_285
	s_add_u32 s0, s76, 0xfff80080
	s_addc_u32 s1, s77, -1
	s_and_b64 s[70:71], s[70:71], exec
	s_cselect_b32 vcc_hi, s21, s1
	s_cselect_b32 vcc_lo, s22, s0
	s_cselect_b32 s71, s23, s41
	s_cselect_b32 s70, s39, s7
	s_add_i32 s0, 0, 0x10000
	s_add_i32 s1, 0, 0x14000
	v_add_u32_e32 v146, s0, v1
	v_add_u32_e32 v174, s1, v1
	ds_read_b128 v[134:137], v146
	ds_read_b128 v[138:141], v146 offset:1024
	ds_read_b128 v[142:145], v146 offset:2048
	ds_read_b128 v[146:149], v146 offset:3072
	ds_read_b128 v[150:153], v174
	ds_read_b128 v[154:157], v174 offset:1024
	ds_read_b128 v[158:161], v174 offset:2048
	ds_read_b128 v[174:177], v174 offset:3072
	s_add_i32 m0, s67, 0xc000
	ds_read_b128 v[178:181], v222
	ds_read_b128 v[182:185], v222 offset:1024
	ds_read_b128 v[186:189], v222 offset:2048
	ds_read_b128 v[190:193], v222 offset:3072
	ds_read_b128 v[204:207], v222 offset:4096
	ds_read_b128 v[208:211], v222 offset:5120
	ds_read_b128 v[212:215], v222 offset:6144
	ds_read_b128 v[216:219], v222 offset:7168
	global_load_lds_dwordx4 v170, s[76:77]
	s_add_i32 m0, s67, 0xe000
	s_nop 0
	global_load_lds_dwordx4 v172, s[76:77]
	s_waitcnt vmcnt(8)
	s_waitcnt lgkmcnt(0)
	s_barrier
	v_mfma_f32_16x16x32_bf16 v[126:129], v[134:137], v[178:181], 0
	v_mfma_f32_16x16x32_bf16 v[126:129], v[138:141], v[182:185], v[126:129]
	v_mfma_f32_16x16x32_bf16 v[122:125], v[146:149], v[182:185], 0
	v_mfma_f32_16x16x32_bf16 v[122:125], v[142:145], v[178:181], v[122:125]
	v_mfma_f32_16x16x32_bf16 v[118:121], v[150:153], v[178:181], 0
	v_mfma_f32_16x16x32_bf16 v[118:121], v[154:157], v[182:185], v[118:121]
	v_mfma_f32_16x16x32_bf16 v[114:117], v[174:177], v[182:185], 0
	v_mfma_f32_16x16x32_bf16 v[114:117], v[158:161], v[178:181], v[114:117]
	v_mfma_f32_16x16x32_bf16 v[98:101], v[158:161], v[186:189], 0
	v_mfma_f32_16x16x32_bf16 v[98:101], v[174:177], v[190:193], v[98:101]
	v_mfma_f32_16x16x32_bf16 v[102:105], v[154:157], v[190:193], 0
	v_mfma_f32_16x16x32_bf16 v[102:105], v[150:153], v[186:189], v[102:105]
	v_mfma_f32_16x16x32_bf16 v[106:109], v[142:145], v[186:189], 0
	v_mfma_f32_16x16x32_bf16 v[106:109], v[146:149], v[190:193], v[106:109]
	v_mfma_f32_16x16x32_bf16 v[110:113], v[138:141], v[190:193], 0
	v_mfma_f32_16x16x32_bf16 v[110:113], v[134:137], v[186:189], v[110:113]
	v_mfma_f32_16x16x32_bf16 v[94:97], v[134:137], v[204:207], 0
	v_mfma_f32_16x16x32_bf16 v[94:97], v[138:141], v[208:211], v[94:97]
	v_mfma_f32_16x16x32_bf16 v[90:93], v[146:149], v[208:211], 0
	v_mfma_f32_16x16x32_bf16 v[90:93], v[142:145], v[204:207], v[90:93]
	v_mfma_f32_16x16x32_bf16 v[86:89], v[150:153], v[204:207], 0
	v_mfma_f32_16x16x32_bf16 v[86:89], v[154:157], v[208:211], v[86:89]
	v_mfma_f32_16x16x32_bf16 v[82:85], v[174:177], v[208:211], 0
	v_mfma_f32_16x16x32_bf16 v[82:85], v[158:161], v[204:207], v[82:85]
	v_mfma_f32_16x16x32_bf16 v[66:69], v[158:161], v[212:215], 0
	v_mfma_f32_16x16x32_bf16 v[66:69], v[174:177], v[216:219], v[66:69]
	v_mfma_f32_16x16x32_bf16 v[70:73], v[154:157], v[216:219], 0
	v_mfma_f32_16x16x32_bf16 v[70:73], v[150:153], v[212:215], v[70:73]
	v_mfma_f32_16x16x32_bf16 v[74:77], v[142:145], v[212:215], 0
	v_mfma_f32_16x16x32_bf16 v[74:77], v[146:149], v[216:219], v[74:77]
	v_mfma_f32_16x16x32_bf16 v[78:81], v[138:141], v[216:219], 0
	v_mfma_f32_16x16x32_bf16 v[78:81], v[134:137], v[212:215], v[78:81]
	s_barrier
	s_add_i32 s0, s0, s54
	s_mov_b32 m0, s0
	ds_read_b128 v[178:181], v222 offset:16384
	ds_read_b128 v[182:185], v222 offset:17408
	ds_read_b128 v[186:189], v222 offset:18432
	ds_read_b128 v[190:193], v222 offset:19456
	ds_read_b128 v[204:207], v222 offset:20480
	ds_read_b128 v[208:211], v222 offset:21504
	ds_read_b128 v[212:215], v222 offset:22528
	ds_read_b128 v[216:219], v222 offset:23552
	global_load_lds_dwordx4 v164, s[70:71]
	s_add_i32 m0, s0, 0x2000
	s_add_u32 s44, s70, 0x80000
	s_addc_u32 s45, s71, 0
	s_add_i32 s0, s1, s54
	global_load_lds_dwordx4 v162, s[70:71]
	s_mov_b32 m0, s0
	s_nop 0
	global_load_lds_dwordx4 v164, s[44:45]
	s_add_i32 m0, s0, 0x2000
	s_nop 0
	global_load_lds_dwordx4 v162, s[44:45]
	s_mov_b32 m0, s67
	s_nop 0
	global_load_lds_dwordx4 v164, vcc
	s_mov_b32 m0, s68
	s_nop 0
	global_load_lds_dwordx4 v162, vcc
	s_waitcnt vmcnt(8)
	s_waitcnt lgkmcnt(0)
	s_barrier
	v_mfma_f32_16x16x32_bf16 v[62:65], v[134:137], v[178:181], 0
	v_mfma_f32_16x16x32_bf16 v[62:65], v[138:141], v[182:185], v[62:65]
	v_mfma_f32_16x16x32_bf16 v[58:61], v[146:149], v[182:185], 0
	v_mfma_f32_16x16x32_bf16 v[58:61], v[142:145], v[178:181], v[58:61]
	v_mfma_f32_16x16x32_bf16 v[54:57], v[150:153], v[178:181], 0
	v_mfma_f32_16x16x32_bf16 v[54:57], v[154:157], v[182:185], v[54:57]
	v_mfma_f32_16x16x32_bf16 v[50:53], v[174:177], v[182:185], 0
	v_mfma_f32_16x16x32_bf16 v[50:53], v[158:161], v[178:181], v[50:53]
	v_mfma_f32_16x16x32_bf16 v[34:37], v[158:161], v[186:189], 0
	v_mfma_f32_16x16x32_bf16 v[34:37], v[174:177], v[190:193], v[34:37]
	v_mfma_f32_16x16x32_bf16 v[38:41], v[154:157], v[190:193], 0
	v_mfma_f32_16x16x32_bf16 v[38:41], v[150:153], v[186:189], v[38:41]
	v_mfma_f32_16x16x32_bf16 v[42:45], v[142:145], v[186:189], 0
	v_mfma_f32_16x16x32_bf16 v[42:45], v[146:149], v[190:193], v[42:45]
	v_mfma_f32_16x16x32_bf16 v[46:49], v[138:141], v[190:193], 0
	v_mfma_f32_16x16x32_bf16 v[46:49], v[134:137], v[186:189], v[46:49]
	v_mfma_f32_16x16x32_bf16 v[30:33], v[134:137], v[204:207], 0
	v_mfma_f32_16x16x32_bf16 v[30:33], v[138:141], v[208:211], v[30:33]
	v_mfma_f32_16x16x32_bf16 v[26:29], v[146:149], v[208:211], 0
	v_mfma_f32_16x16x32_bf16 v[26:29], v[142:145], v[204:207], v[26:29]
	v_mfma_f32_16x16x32_bf16 v[22:25], v[150:153], v[204:207], 0
	v_mfma_f32_16x16x32_bf16 v[22:25], v[154:157], v[208:211], v[22:25]
	v_mfma_f32_16x16x32_bf16 v[18:21], v[174:177], v[208:211], 0
	v_mfma_f32_16x16x32_bf16 v[18:21], v[158:161], v[204:207], v[18:21]
	v_mfma_f32_16x16x32_bf16 v[2:5], v[158:161], v[212:215], 0
	v_mfma_f32_16x16x32_bf16 v[2:5], v[174:177], v[216:219], v[2:5]
	v_mfma_f32_16x16x32_bf16 v[6:9], v[154:157], v[216:219], 0
	v_mfma_f32_16x16x32_bf16 v[6:9], v[150:153], v[212:215], v[6:9]
	v_mfma_f32_16x16x32_bf16 v[10:13], v[142:145], v[212:215], 0
	v_mfma_f32_16x16x32_bf16 v[10:13], v[146:149], v[216:219], v[10:13]
	v_mfma_f32_16x16x32_bf16 v[14:17], v[138:141], v[216:219], 0
	v_mfma_f32_16x16x32_bf16 v[14:17], v[134:137], v[212:215], v[14:17]
	s_barrier
	s_add_i32 s0, 0, 0x18000
	s_add_i32 s1, 0, 0x1c000
	v_add_u32_e32 v146, s0, v1
	v_add_u32_e32 v174, s1, v1
	ds_read_b128 v[134:137], v146
	ds_read_b128 v[138:141], v146 offset:1024
	ds_read_b128 v[142:145], v146 offset:2048
	ds_read_b128 v[146:149], v146 offset:3072
	ds_read_b128 v[150:153], v174
	ds_read_b128 v[154:157], v174 offset:1024
	ds_read_b128 v[158:161], v174 offset:2048
	ds_read_b128 v[174:177], v174 offset:3072
	s_add_u32 s44, vcc_lo, 0x80000
	s_addc_u32 s45, vcc_hi, 0
	s_mov_b32 m0, s8
	ds_read_b128 v[178:181], v222 offset:32768
	ds_read_b128 v[182:185], v222 offset:33792
	ds_read_b128 v[186:189], v222 offset:34816
	ds_read_b128 v[190:193], v222 offset:35840
	ds_read_b128 v[204:207], v222 offset:36864
	ds_read_b128 v[208:211], v222 offset:37888
	ds_read_b128 v[212:215], v222 offset:38912
	ds_read_b128 v[216:219], v222 offset:39936
	global_load_lds_dwordx4 v164, s[44:45]
	s_mov_b32 m0, s9
	s_nop 0
	global_load_lds_dwordx4 v162, s[44:45]
	s_waitcnt vmcnt(8)
	s_waitcnt lgkmcnt(0)
	s_barrier
	v_mfma_f32_16x16x32_bf16 v[126:129], v[134:137], v[178:181], v[126:129]
	v_mfma_f32_16x16x32_bf16 v[126:129], v[138:141], v[182:185], v[126:129]
	v_mfma_f32_16x16x32_bf16 v[122:125], v[146:149], v[182:185], v[122:125]
	v_mfma_f32_16x16x32_bf16 v[122:125], v[142:145], v[178:181], v[122:125]
	v_mfma_f32_16x16x32_bf16 v[118:121], v[150:153], v[178:181], v[118:121]
	v_mfma_f32_16x16x32_bf16 v[118:121], v[154:157], v[182:185], v[118:121]
	v_mfma_f32_16x16x32_bf16 v[114:117], v[174:177], v[182:185], v[114:117]
	v_mfma_f32_16x16x32_bf16 v[114:117], v[158:161], v[178:181], v[114:117]
	v_mfma_f32_16x16x32_bf16 v[98:101], v[158:161], v[186:189], v[98:101]
	v_mfma_f32_16x16x32_bf16 v[98:101], v[174:177], v[190:193], v[98:101]
	v_mfma_f32_16x16x32_bf16 v[102:105], v[154:157], v[190:193], v[102:105]
	v_mfma_f32_16x16x32_bf16 v[102:105], v[150:153], v[186:189], v[102:105]
	v_mfma_f32_16x16x32_bf16 v[106:109], v[142:145], v[186:189], v[106:109]
	v_mfma_f32_16x16x32_bf16 v[106:109], v[146:149], v[190:193], v[106:109]
	v_mfma_f32_16x16x32_bf16 v[110:113], v[138:141], v[190:193], v[110:113]
	v_mfma_f32_16x16x32_bf16 v[110:113], v[134:137], v[186:189], v[110:113]
	v_mfma_f32_16x16x32_bf16 v[94:97], v[134:137], v[204:207], v[94:97]
	v_mfma_f32_16x16x32_bf16 v[94:97], v[138:141], v[208:211], v[94:97]
	v_mfma_f32_16x16x32_bf16 v[90:93], v[146:149], v[208:211], v[90:93]
	v_mfma_f32_16x16x32_bf16 v[90:93], v[142:145], v[204:207], v[90:93]
	v_mfma_f32_16x16x32_bf16 v[86:89], v[150:153], v[204:207], v[86:89]
	v_mfma_f32_16x16x32_bf16 v[86:89], v[154:157], v[208:211], v[86:89]
	v_mfma_f32_16x16x32_bf16 v[82:85], v[174:177], v[208:211], v[82:85]
	v_mfma_f32_16x16x32_bf16 v[82:85], v[158:161], v[204:207], v[82:85]
	v_mfma_f32_16x16x32_bf16 v[66:69], v[158:161], v[212:215], v[66:69]
	v_mfma_f32_16x16x32_bf16 v[66:69], v[174:177], v[216:219], v[66:69]
	v_mfma_f32_16x16x32_bf16 v[70:73], v[154:157], v[216:219], v[70:73]
	v_mfma_f32_16x16x32_bf16 v[70:73], v[150:153], v[212:215], v[70:73]
	v_mfma_f32_16x16x32_bf16 v[74:77], v[142:145], v[212:215], v[74:77]
	v_mfma_f32_16x16x32_bf16 v[74:77], v[146:149], v[216:219], v[74:77]
	v_mfma_f32_16x16x32_bf16 v[78:81], v[138:141], v[216:219], v[78:81]
	v_mfma_f32_16x16x32_bf16 v[78:81], v[134:137], v[212:215], v[78:81]
	s_barrier
	s_add_u32 s98, s70, 0x80
	s_addc_u32 s99, s71, 0
	s_add_u32 s100, vcc_lo, 0x80
	s_addc_u32 s101, vcc_hi, 0
	s_add_i32 s0, s0, s54
	s_mov_b32 m0, s0
	ds_read_b128 v[178:181], v222 offset:49152
	ds_read_b128 v[182:185], v222 offset:50176
	ds_read_b128 v[186:189], v222 offset:51200
	ds_read_b128 v[190:193], v222 offset:52224
	ds_read_b128 v[204:207], v222 offset:53248
	ds_read_b128 v[208:211], v222 offset:54272
	ds_read_b128 v[212:215], v222 offset:55296
	ds_read_b128 v[216:219], v222 offset:56320
	global_load_lds_dwordx4 v164, s[98:99]
	s_add_i32 m0, s0, 0x2000
	s_add_u32 s44, s70, 0x80080
	s_addc_u32 s45, s71, 0
	s_add_i32 s0, s1, s54
	global_load_lds_dwordx4 v162, s[98:99]
	s_mov_b32 m0, s0
	s_nop 0
	global_load_lds_dwordx4 v164, s[44:45]
	s_add_i32 m0, s0, 0x2000
	s_nop 0
	global_load_lds_dwordx4 v162, s[44:45]
	s_mov_b32 m0, s27
	s_nop 0
	global_load_lds_dwordx4 v164, s[100:101]
	s_mov_b32 m0, s26
	s_nop 0
	global_load_lds_dwordx4 v162, s[100:101]
	s_waitcnt vmcnt(8)
	s_waitcnt lgkmcnt(0)
	s_barrier
	v_mfma_f32_16x16x32_bf16 v[62:65], v[134:137], v[178:181], v[62:65]
	v_mfma_f32_16x16x32_bf16 v[62:65], v[138:141], v[182:185], v[62:65]
	v_mfma_f32_16x16x32_bf16 v[58:61], v[146:149], v[182:185], v[58:61]
	v_mfma_f32_16x16x32_bf16 v[58:61], v[142:145], v[178:181], v[58:61]
	v_mfma_f32_16x16x32_bf16 v[54:57], v[150:153], v[178:181], v[54:57]
	v_mfma_f32_16x16x32_bf16 v[54:57], v[154:157], v[182:185], v[54:57]
	v_mfma_f32_16x16x32_bf16 v[50:53], v[174:177], v[182:185], v[50:53]
	v_mfma_f32_16x16x32_bf16 v[50:53], v[158:161], v[178:181], v[50:53]
	v_mfma_f32_16x16x32_bf16 v[34:37], v[158:161], v[186:189], v[34:37]
	v_mfma_f32_16x16x32_bf16 v[34:37], v[174:177], v[190:193], v[34:37]
	v_mfma_f32_16x16x32_bf16 v[38:41], v[154:157], v[190:193], v[38:41]
	v_mfma_f32_16x16x32_bf16 v[38:41], v[150:153], v[186:189], v[38:41]
	v_mfma_f32_16x16x32_bf16 v[42:45], v[142:145], v[186:189], v[42:45]
	v_mfma_f32_16x16x32_bf16 v[42:45], v[146:149], v[190:193], v[42:45]
	v_mfma_f32_16x16x32_bf16 v[46:49], v[138:141], v[190:193], v[46:49]
	v_mfma_f32_16x16x32_bf16 v[46:49], v[134:137], v[186:189], v[46:49]
	v_mfma_f32_16x16x32_bf16 v[30:33], v[134:137], v[204:207], v[30:33]
	v_mfma_f32_16x16x32_bf16 v[30:33], v[138:141], v[208:211], v[30:33]
	v_mfma_f32_16x16x32_bf16 v[26:29], v[146:149], v[208:211], v[26:29]
	v_mfma_f32_16x16x32_bf16 v[26:29], v[142:145], v[204:207], v[26:29]
	v_mfma_f32_16x16x32_bf16 v[22:25], v[150:153], v[204:207], v[22:25]
	v_mfma_f32_16x16x32_bf16 v[22:25], v[154:157], v[208:211], v[22:25]
	v_mfma_f32_16x16x32_bf16 v[18:21], v[174:177], v[208:211], v[18:21]
	v_mfma_f32_16x16x32_bf16 v[18:21], v[158:161], v[204:207], v[18:21]
	v_mfma_f32_16x16x32_bf16 v[2:5], v[158:161], v[212:215], v[2:5]
	v_mfma_f32_16x16x32_bf16 v[2:5], v[174:177], v[216:219], v[2:5]
	v_mfma_f32_16x16x32_bf16 v[6:9], v[154:157], v[216:219], v[6:9]
	v_mfma_f32_16x16x32_bf16 v[6:9], v[150:153], v[212:215], v[6:9]
	v_mfma_f32_16x16x32_bf16 v[10:13], v[142:145], v[212:215], v[10:13]
	v_mfma_f32_16x16x32_bf16 v[10:13], v[146:149], v[216:219], v[10:13]
	v_mfma_f32_16x16x32_bf16 v[14:17], v[138:141], v[216:219], v[14:17]
	v_mfma_f32_16x16x32_bf16 v[14:17], v[134:137], v[212:215], v[14:17]
	s_barrier
	s_add_i32 s43, s43, 2
	s_add_u32 s76, s76, 0x100
	s_addc_u32 s77, s77, 0
	s_add_u32 s7, s7, 0x100
	s_addc_u32 s41, s41, 0
	s_cmp_gt_u32 s43, 29
	s_cbranch_scc1 .LBB0_288
	s_branch .LBB0_286

.LBB0_509:
	s_add_u32 s90, s76, 0x100
	s_addc_u32 s91, s77, 0
	s_and_b64 s[0:1], s[70:71], exec
	s_cselect_b32 vcc_hi, s22, s91
	s_cselect_b32 vcc_lo, s23, s90
	s_cselect_b32 s71, s41, s53
	s_cselect_b32 s70, s44, s51
	s_add_i32 s0, 0, 0x10000
	s_add_i32 s18, 0, 0x14000
	v_add_u32_e32 v114, s0, v1
	v_add_u32_e32 v154, s18, v1
	ds_read_b128 v[78:81], v114
	ds_read_b128 v[90:93], v114 offset:1024
	ds_read_b128 v[102:105], v114 offset:2048
	ds_read_b128 v[114:117], v114 offset:3072
	ds_read_b128 v[126:129], v154
	ds_read_b128 v[134:137], v154 offset:1024
	ds_read_b128 v[142:145], v154 offset:2048
	ds_read_b128 v[154:157], v154 offset:3072
	s_add_i32 m0, s29, 0xc000
	ds_read_b128 v[158:161], v237
	ds_read_b128 v[162:165], v237 offset:1024
	ds_read_b128 v[166:169], v237 offset:2048
	ds_read_b128 v[178:181], v237 offset:3072
	ds_read_b128 v[182:185], v237 offset:4096
	ds_read_b128 v[186:189], v237 offset:5120
	ds_read_b128 v[190:193], v237 offset:6144
	ds_read_b128 v[214:217], v237 offset:7168
	global_load_lds_dwordx4 v210, s[76:77]
	s_add_i32 m0, s29, 0xe000
	s_nop 0
	global_load_lds_dwordx4 v212, s[76:77]
	s_waitcnt vmcnt(8)
	s_waitcnt lgkmcnt(0)
	s_barrier
	v_mfma_f32_16x16x32_bf16 v[174:177], v[78:81], v[158:161], v[174:177]
	v_mfma_f32_16x16x32_bf16 v[174:177], v[90:93], v[162:165], v[174:177]
	v_mfma_f32_16x16x32_bf16 v[170:173], v[114:117], v[162:165], v[170:173]
	v_mfma_f32_16x16x32_bf16 v[170:173], v[102:105], v[158:161], v[170:173]
	v_mfma_f32_16x16x32_bf16 v[150:153], v[126:129], v[158:161], v[150:153]
	v_mfma_f32_16x16x32_bf16 v[150:153], v[134:137], v[162:165], v[150:153]
	v_mfma_f32_16x16x32_bf16 v[146:149], v[154:157], v[162:165], v[146:149]
	v_mfma_f32_16x16x32_bf16 v[146:149], v[142:145], v[158:161], v[146:149]
	v_mfma_f32_16x16x32_bf16 v[118:121], v[142:145], v[166:169], v[118:121]
	v_mfma_f32_16x16x32_bf16 v[118:121], v[154:157], v[178:181], v[118:121]
	v_mfma_f32_16x16x32_bf16 v[122:125], v[134:137], v[178:181], v[122:125]
	v_mfma_f32_16x16x32_bf16 v[122:125], v[126:129], v[166:169], v[122:125]
	v_mfma_f32_16x16x32_bf16 v[130:133], v[102:105], v[166:169], v[130:133]
	v_mfma_f32_16x16x32_bf16 v[130:133], v[114:117], v[178:181], v[130:133]
	v_mfma_f32_16x16x32_bf16 v[138:141], v[90:93], v[178:181], v[138:141]
	v_mfma_f32_16x16x32_bf16 v[138:141], v[78:81], v[166:169], v[138:141]
	v_mfma_f32_16x16x32_bf16 v[110:113], v[78:81], v[182:185], v[110:113]
	v_mfma_f32_16x16x32_bf16 v[110:113], v[90:93], v[186:189], v[110:113]
	v_mfma_f32_16x16x32_bf16 v[106:109], v[114:117], v[186:189], v[106:109]
	v_mfma_f32_16x16x32_bf16 v[106:109], v[102:105], v[182:185], v[106:109]
	v_mfma_f32_16x16x32_bf16 v[98:101], v[126:129], v[182:185], v[98:101]
	v_mfma_f32_16x16x32_bf16 v[98:101], v[134:137], v[186:189], v[98:101]
	v_mfma_f32_16x16x32_bf16 v[94:97], v[154:157], v[186:189], v[94:97]
	v_mfma_f32_16x16x32_bf16 v[94:97], v[142:145], v[182:185], v[94:97]
	v_mfma_f32_16x16x32_bf16 v[66:69], v[142:145], v[190:193], v[66:69]
	v_mfma_f32_16x16x32_bf16 v[66:69], v[154:157], v[214:217], v[66:69]
	v_mfma_f32_16x16x32_bf16 v[74:77], v[134:137], v[214:217], v[74:77]
	v_mfma_f32_16x16x32_bf16 v[74:77], v[126:129], v[190:193], v[74:77]
	v_mfma_f32_16x16x32_bf16 v[82:85], v[102:105], v[190:193], v[82:85]
	v_mfma_f32_16x16x32_bf16 v[82:85], v[114:117], v[214:217], v[82:85]
	v_mfma_f32_16x16x32_bf16 v[86:89], v[90:93], v[214:217], v[86:89]
	v_mfma_f32_16x16x32_bf16 v[86:89], v[78:81], v[190:193], v[86:89]
	s_barrier
	s_add_i32 s0, s0, s28
	s_mov_b32 m0, s0
	ds_read_b128 v[158:161], v237 offset:16384
	ds_read_b128 v[162:165], v237 offset:17408
	ds_read_b128 v[166:169], v237 offset:18432
	ds_read_b128 v[178:181], v237 offset:19456
	ds_read_b128 v[182:185], v237 offset:20480
	ds_read_b128 v[186:189], v237 offset:21504
	ds_read_b128 v[190:193], v237 offset:22528
	ds_read_b128 v[214:217], v237 offset:23552
	global_load_lds_dwordx4 v194, s[70:71]
	s_add_i32 m0, s0, 0x2000
	s_add_u32 s0, s70, 0x80000
	s_addc_u32 s1, s71, 0
	s_add_i32 s18, s18, s28
	global_load_lds_dwordx4 v204, s[70:71]
	s_mov_b32 m0, s18
	s_nop 0
	global_load_lds_dwordx4 v194, s[0:1]
	s_add_i32 m0, s18, 0x2000
	s_nop 0
	global_load_lds_dwordx4 v204, s[0:1]
	s_mov_b32 m0, s29
	s_nop 0
	global_load_lds_dwordx4 v194, vcc
	s_mov_b32 m0, s31
	s_nop 0
	global_load_lds_dwordx4 v204, vcc
	s_waitcnt vmcnt(8)
	s_waitcnt lgkmcnt(0)
	s_barrier
	v_mfma_f32_16x16x32_bf16 v[62:65], v[78:81], v[158:161], v[62:65]
	v_mfma_f32_16x16x32_bf16 v[62:65], v[90:93], v[162:165], v[62:65]
	v_mfma_f32_16x16x32_bf16 v[58:61], v[114:117], v[162:165], v[58:61]
	v_mfma_f32_16x16x32_bf16 v[58:61], v[102:105], v[158:161], v[58:61]
	v_mfma_f32_16x16x32_bf16 v[54:57], v[126:129], v[158:161], v[54:57]
	v_mfma_f32_16x16x32_bf16 v[54:57], v[134:137], v[162:165], v[54:57]
	v_mfma_f32_16x16x32_bf16 v[50:53], v[154:157], v[162:165], v[50:53]
	v_mfma_f32_16x16x32_bf16 v[50:53], v[142:145], v[158:161], v[50:53]
	v_mfma_f32_16x16x32_bf16 v[34:37], v[142:145], v[166:169], v[34:37]
	v_mfma_f32_16x16x32_bf16 v[34:37], v[154:157], v[178:181], v[34:37]
	v_mfma_f32_16x16x32_bf16 v[38:41], v[134:137], v[178:181], v[38:41]
	v_mfma_f32_16x16x32_bf16 v[38:41], v[126:129], v[166:169], v[38:41]
	v_mfma_f32_16x16x32_bf16 v[42:45], v[102:105], v[166:169], v[42:45]
	v_mfma_f32_16x16x32_bf16 v[42:45], v[114:117], v[178:181], v[42:45]
	v_mfma_f32_16x16x32_bf16 v[46:49], v[90:93], v[178:181], v[46:49]
	v_mfma_f32_16x16x32_bf16 v[46:49], v[78:81], v[166:169], v[46:49]
	v_mfma_f32_16x16x32_bf16 v[30:33], v[78:81], v[182:185], v[30:33]
	v_mfma_f32_16x16x32_bf16 v[30:33], v[90:93], v[186:189], v[30:33]
	v_mfma_f32_16x16x32_bf16 v[26:29], v[114:117], v[186:189], v[26:29]
	v_mfma_f32_16x16x32_bf16 v[26:29], v[102:105], v[182:185], v[26:29]
	v_mfma_f32_16x16x32_bf16 v[22:25], v[126:129], v[182:185], v[22:25]
	v_mfma_f32_16x16x32_bf16 v[22:25], v[134:137], v[186:189], v[22:25]
	v_mfma_f32_16x16x32_bf16 v[18:21], v[154:157], v[186:189], v[18:21]
	v_mfma_f32_16x16x32_bf16 v[18:21], v[142:145], v[182:185], v[18:21]
	v_mfma_f32_16x16x32_bf16 v[2:5], v[142:145], v[190:193], v[2:5]
	v_mfma_f32_16x16x32_bf16 v[2:5], v[154:157], v[214:217], v[2:5]
	v_mfma_f32_16x16x32_bf16 v[6:9], v[134:137], v[214:217], v[6:9]
	v_mfma_f32_16x16x32_bf16 v[6:9], v[126:129], v[190:193], v[6:9]
	v_mfma_f32_16x16x32_bf16 v[10:13], v[102:105], v[190:193], v[10:13]
	v_mfma_f32_16x16x32_bf16 v[10:13], v[114:117], v[214:217], v[10:13]
	v_mfma_f32_16x16x32_bf16 v[14:17], v[90:93], v[214:217], v[14:17]
	v_mfma_f32_16x16x32_bf16 v[14:17], v[78:81], v[190:193], v[14:17]
	s_barrier
	s_add_i32 s18, 0, 0x18000
	s_add_i32 s19, 0, 0x1c000
	v_add_u32_e32 v114, s18, v1
	v_add_u32_e32 v154, s19, v1
	ds_read_b128 v[78:81], v114
	ds_read_b128 v[90:93], v114 offset:1024
	ds_read_b128 v[102:105], v114 offset:2048
	ds_read_b128 v[114:117], v114 offset:3072
	ds_read_b128 v[126:129], v154
	ds_read_b128 v[134:137], v154 offset:1024
	ds_read_b128 v[142:145], v154 offset:2048
	ds_read_b128 v[154:157], v154 offset:3072
	s_add_u32 s0, vcc_lo, 0x80000
	s_addc_u32 s1, vcc_hi, 0
	s_mov_b32 m0, s33
	ds_read_b128 v[158:161], v237 offset:32768
	ds_read_b128 v[162:165], v237 offset:33792
	ds_read_b128 v[166:169], v237 offset:34816
	ds_read_b128 v[178:181], v237 offset:35840
	ds_read_b128 v[182:185], v237 offset:36864
	ds_read_b128 v[186:189], v237 offset:37888
	ds_read_b128 v[190:193], v237 offset:38912
	ds_read_b128 v[214:217], v237 offset:39936
	global_load_lds_dwordx4 v194, s[0:1]
	s_mov_b32 m0, s43
	s_nop 0
	global_load_lds_dwordx4 v204, s[0:1]
	s_waitcnt vmcnt(8)
	s_waitcnt lgkmcnt(0)
	s_barrier
	v_mfma_f32_16x16x32_bf16 v[174:177], v[78:81], v[158:161], v[174:177]
	v_mfma_f32_16x16x32_bf16 v[174:177], v[90:93], v[162:165], v[174:177]
	v_mfma_f32_16x16x32_bf16 v[170:173], v[114:117], v[162:165], v[170:173]
	v_mfma_f32_16x16x32_bf16 v[170:173], v[102:105], v[158:161], v[170:173]
	v_mfma_f32_16x16x32_bf16 v[150:153], v[126:129], v[158:161], v[150:153]
	v_mfma_f32_16x16x32_bf16 v[150:153], v[134:137], v[162:165], v[150:153]
	v_mfma_f32_16x16x32_bf16 v[146:149], v[154:157], v[162:165], v[146:149]
	v_mfma_f32_16x16x32_bf16 v[146:149], v[142:145], v[158:161], v[146:149]
	v_mfma_f32_16x16x32_bf16 v[118:121], v[142:145], v[166:169], v[118:121]
	v_mfma_f32_16x16x32_bf16 v[118:121], v[154:157], v[178:181], v[118:121]
	v_mfma_f32_16x16x32_bf16 v[122:125], v[134:137], v[178:181], v[122:125]
	v_mfma_f32_16x16x32_bf16 v[122:125], v[126:129], v[166:169], v[122:125]
	v_mfma_f32_16x16x32_bf16 v[130:133], v[102:105], v[166:169], v[130:133]
	v_mfma_f32_16x16x32_bf16 v[130:133], v[114:117], v[178:181], v[130:133]
	v_mfma_f32_16x16x32_bf16 v[138:141], v[90:93], v[178:181], v[138:141]
	v_mfma_f32_16x16x32_bf16 v[138:141], v[78:81], v[166:169], v[138:141]
	v_mfma_f32_16x16x32_bf16 v[110:113], v[78:81], v[182:185], v[110:113]
	v_mfma_f32_16x16x32_bf16 v[110:113], v[90:93], v[186:189], v[110:113]
	v_mfma_f32_16x16x32_bf16 v[106:109], v[114:117], v[186:189], v[106:109]
	v_mfma_f32_16x16x32_bf16 v[106:109], v[102:105], v[182:185], v[106:109]
	v_mfma_f32_16x16x32_bf16 v[98:101], v[126:129], v[182:185], v[98:101]
	v_mfma_f32_16x16x32_bf16 v[98:101], v[134:137], v[186:189], v[98:101]
	v_mfma_f32_16x16x32_bf16 v[94:97], v[154:157], v[186:189], v[94:97]
	v_mfma_f32_16x16x32_bf16 v[94:97], v[142:145], v[182:185], v[94:97]
	v_mfma_f32_16x16x32_bf16 v[66:69], v[142:145], v[190:193], v[66:69]
	v_mfma_f32_16x16x32_bf16 v[66:69], v[154:157], v[214:217], v[66:69]
	v_mfma_f32_16x16x32_bf16 v[74:77], v[134:137], v[214:217], v[74:77]
	v_mfma_f32_16x16x32_bf16 v[74:77], v[126:129], v[190:193], v[74:77]
	v_mfma_f32_16x16x32_bf16 v[82:85], v[102:105], v[190:193], v[82:85]
	v_mfma_f32_16x16x32_bf16 v[82:85], v[114:117], v[214:217], v[82:85]
	v_mfma_f32_16x16x32_bf16 v[86:89], v[90:93], v[214:217], v[86:89]
	v_mfma_f32_16x16x32_bf16 v[86:89], v[78:81], v[190:193], v[86:89]
	s_barrier
	s_add_u32 s98, s70, 0x80
	s_addc_u32 s99, s71, 0
	s_add_u32 s100, vcc_lo, 0x80
	s_addc_u32 s101, vcc_hi, 0
	s_add_i32 s0, s18, s28
	s_mov_b32 m0, s0
	ds_read_b128 v[158:161], v237 offset:49152
	ds_read_b128 v[162:165], v237 offset:50176
	ds_read_b128 v[166:169], v237 offset:51200
	ds_read_b128 v[178:181], v237 offset:52224
	ds_read_b128 v[182:185], v237 offset:53248
	ds_read_b128 v[186:189], v237 offset:54272
	ds_read_b128 v[190:193], v237 offset:55296
	ds_read_b128 v[214:217], v237 offset:56320
	global_load_lds_dwordx4 v194, s[98:99]
	s_add_i32 m0, s0, 0x2000
	s_add_u32 s0, s70, 0x80080
	s_addc_u32 s1, s71, 0
	s_add_i32 s18, s19, s28
	global_load_lds_dwordx4 v204, s[98:99]
	s_mov_b32 m0, s18
	s_nop 0
	global_load_lds_dwordx4 v194, s[0:1]
	s_add_i32 m0, s18, 0x2000
	s_nop 0
	global_load_lds_dwordx4 v204, s[0:1]
	s_mov_b32 m0, s68
	s_nop 0
	global_load_lds_dwordx4 v194, s[100:101]
	s_mov_b32 m0, s79
	s_nop 0
	global_load_lds_dwordx4 v204, s[100:101]
	s_waitcnt vmcnt(8)
	s_waitcnt lgkmcnt(0)
	s_barrier
	v_mfma_f32_16x16x32_bf16 v[62:65], v[78:81], v[158:161], v[62:65]
	v_mfma_f32_16x16x32_bf16 v[62:65], v[90:93], v[162:165], v[62:65]
	v_mfma_f32_16x16x32_bf16 v[58:61], v[114:117], v[162:165], v[58:61]
	v_mfma_f32_16x16x32_bf16 v[58:61], v[102:105], v[158:161], v[58:61]
	v_mfma_f32_16x16x32_bf16 v[54:57], v[126:129], v[158:161], v[54:57]
	v_mfma_f32_16x16x32_bf16 v[54:57], v[134:137], v[162:165], v[54:57]
	v_mfma_f32_16x16x32_bf16 v[50:53], v[154:157], v[162:165], v[50:53]
	v_mfma_f32_16x16x32_bf16 v[50:53], v[142:145], v[158:161], v[50:53]
	v_mfma_f32_16x16x32_bf16 v[34:37], v[142:145], v[166:169], v[34:37]
	v_mfma_f32_16x16x32_bf16 v[34:37], v[154:157], v[178:181], v[34:37]
	v_mfma_f32_16x16x32_bf16 v[38:41], v[134:137], v[178:181], v[38:41]
	v_mfma_f32_16x16x32_bf16 v[38:41], v[126:129], v[166:169], v[38:41]
	v_mfma_f32_16x16x32_bf16 v[42:45], v[102:105], v[166:169], v[42:45]
	v_mfma_f32_16x16x32_bf16 v[42:45], v[114:117], v[178:181], v[42:45]
	v_mfma_f32_16x16x32_bf16 v[46:49], v[90:93], v[178:181], v[46:49]
	v_mfma_f32_16x16x32_bf16 v[46:49], v[78:81], v[166:169], v[46:49]
	v_mfma_f32_16x16x32_bf16 v[30:33], v[78:81], v[182:185], v[30:33]
	v_mfma_f32_16x16x32_bf16 v[30:33], v[90:93], v[186:189], v[30:33]
	v_mfma_f32_16x16x32_bf16 v[26:29], v[114:117], v[186:189], v[26:29]
	v_mfma_f32_16x16x32_bf16 v[26:29], v[102:105], v[182:185], v[26:29]
	v_mfma_f32_16x16x32_bf16 v[22:25], v[126:129], v[182:185], v[22:25]
	v_mfma_f32_16x16x32_bf16 v[22:25], v[134:137], v[186:189], v[22:25]
	v_mfma_f32_16x16x32_bf16 v[18:21], v[154:157], v[186:189], v[18:21]
	v_mfma_f32_16x16x32_bf16 v[18:21], v[142:145], v[182:185], v[18:21]
	v_mfma_f32_16x16x32_bf16 v[2:5], v[142:145], v[190:193], v[2:5]
	v_mfma_f32_16x16x32_bf16 v[2:5], v[154:157], v[214:217], v[2:5]
	v_mfma_f32_16x16x32_bf16 v[6:9], v[134:137], v[214:217], v[6:9]
	v_mfma_f32_16x16x32_bf16 v[6:9], v[126:129], v[190:193], v[6:9]
	v_mfma_f32_16x16x32_bf16 v[10:13], v[102:105], v[190:193], v[10:13]
	v_mfma_f32_16x16x32_bf16 v[10:13], v[114:117], v[214:217], v[10:13]
	v_mfma_f32_16x16x32_bf16 v[14:17], v[90:93], v[214:217], v[14:17]
	v_mfma_f32_16x16x32_bf16 v[14:17], v[78:81], v[190:193], v[14:17]
	s_barrier
	s_add_i32 s57, s57, 2
	s_add_u32 s51, s51, 0x100
	s_addc_u32 s53, s53, 0
	s_cmp_gt_u32 s57, 29
	s_mov_b64 s[76:77], s[90:91]
	s_cbranch_scc1 .LBB0_512

.Lpeel_disp_out:
	s_cmp_lg_u32 s57, -2
	s_cbranch_scc1 .LBB0_509
	s_add_u32 s90, s76, 0x100
	s_addc_u32 s91, s77, 0
	s_and_b64 s[0:1], s[70:71], exec
	s_cselect_b32 vcc_hi, s22, s91
	s_cselect_b32 vcc_lo, s23, s90
	s_cselect_b32 s71, s41, s53
	s_cselect_b32 s70, s44, s51
	s_add_i32 s0, 0, 0x10000
	s_add_i32 s18, 0, 0x14000
	v_add_u32_e32 v114, s0, v1
	v_add_u32_e32 v154, s18, v1
	ds_read_b128 v[78:81], v114
	ds_read_b128 v[90:93], v114 offset:1024
	ds_read_b128 v[102:105], v114 offset:2048
	ds_read_b128 v[114:117], v114 offset:3072
	ds_read_b128 v[126:129], v154
	ds_read_b128 v[134:137], v154 offset:1024
	ds_read_b128 v[142:145], v154 offset:2048
	ds_read_b128 v[154:157], v154 offset:3072
	s_add_i32 m0, s29, 0xc000
	ds_read_b128 v[158:161], v237
	ds_read_b128 v[162:165], v237 offset:1024
	ds_read_b128 v[166:169], v237 offset:2048
	ds_read_b128 v[178:181], v237 offset:3072
	ds_read_b128 v[182:185], v237 offset:4096
	ds_read_b128 v[186:189], v237 offset:5120
	ds_read_b128 v[190:193], v237 offset:6144
	ds_read_b128 v[214:217], v237 offset:7168
	global_load_lds_dwordx4 v210, s[76:77]
	s_add_i32 m0, s29, 0xe000
	s_nop 0
	global_load_lds_dwordx4 v212, s[76:77]
	s_waitcnt vmcnt(8)
	s_waitcnt lgkmcnt(0)
	s_barrier
	v_mfma_f32_16x16x32_bf16 v[174:177], v[78:81], v[158:161], 0
	v_mfma_f32_16x16x32_bf16 v[174:177], v[90:93], v[162:165], v[174:177]
	v_mfma_f32_16x16x32_bf16 v[170:173], v[114:117], v[162:165], 0
	v_mfma_f32_16x16x32_bf16 v[170:173], v[102:105], v[158:161], v[170:173]
	v_mfma_f32_16x16x32_bf16 v[150:153], v[126:129], v[158:161], 0
	v_mfma_f32_16x16x32_bf16 v[150:153], v[134:137], v[162:165], v[150:153]
	v_mfma_f32_16x16x32_bf16 v[146:149], v[154:157], v[162:165], 0
	v_mfma_f32_16x16x32_bf16 v[146:149], v[142:145], v[158:161], v[146:149]
	v_mfma_f32_16x16x32_bf16 v[118:121], v[142:145], v[166:169], 0
	v_mfma_f32_16x16x32_bf16 v[118:121], v[154:157], v[178:181], v[118:121]
	v_mfma_f32_16x16x32_bf16 v[122:125], v[134:137], v[178:181], 0
	v_mfma_f32_16x16x32_bf16 v[122:125], v[126:129], v[166:169], v[122:125]
	v_mfma_f32_16x16x32_bf16 v[130:133], v[102:105], v[166:169], 0
	v_mfma_f32_16x16x32_bf16 v[130:133], v[114:117], v[178:181], v[130:133]
	v_mfma_f32_16x16x32_bf16 v[138:141], v[90:93], v[178:181], 0
	v_mfma_f32_16x16x32_bf16 v[138:141], v[78:81], v[166:169], v[138:141]
	v_mfma_f32_16x16x32_bf16 v[110:113], v[78:81], v[182:185], 0
	v_mfma_f32_16x16x32_bf16 v[110:113], v[90:93], v[186:189], v[110:113]
	v_mfma_f32_16x16x32_bf16 v[106:109], v[114:117], v[186:189], 0
	v_mfma_f32_16x16x32_bf16 v[106:109], v[102:105], v[182:185], v[106:109]
	v_mfma_f32_16x16x32_bf16 v[98:101], v[126:129], v[182:185], 0
	v_mfma_f32_16x16x32_bf16 v[98:101], v[134:137], v[186:189], v[98:101]
	v_mfma_f32_16x16x32_bf16 v[94:97], v[154:157], v[186:189], 0
	v_mfma_f32_16x16x32_bf16 v[94:97], v[142:145], v[182:185], v[94:97]
	v_mfma_f32_16x16x32_bf16 v[66:69], v[142:145], v[190:193], 0
	v_mfma_f32_16x16x32_bf16 v[66:69], v[154:157], v[214:217], v[66:69]
	v_mfma_f32_16x16x32_bf16 v[74:77], v[134:137], v[214:217], 0
	v_mfma_f32_16x16x32_bf16 v[74:77], v[126:129], v[190:193], v[74:77]
	v_mfma_f32_16x16x32_bf16 v[82:85], v[102:105], v[190:193], 0
	v_mfma_f32_16x16x32_bf16 v[82:85], v[114:117], v[214:217], v[82:85]
	v_mfma_f32_16x16x32_bf16 v[86:89], v[90:93], v[214:217], 0
	v_mfma_f32_16x16x32_bf16 v[86:89], v[78:81], v[190:193], v[86:89]
	s_barrier
	s_add_i32 s0, s0, s28
	s_mov_b32 m0, s0
	ds_read_b128 v[158:161], v237 offset:16384
	ds_read_b128 v[162:165], v237 offset:17408
	ds_read_b128 v[166:169], v237 offset:18432
	ds_read_b128 v[178:181], v237 offset:19456
	ds_read_b128 v[182:185], v237 offset:20480
	ds_read_b128 v[186:189], v237 offset:21504
	ds_read_b128 v[190:193], v237 offset:22528
	ds_read_b128 v[214:217], v237 offset:23552
	global_load_lds_dwordx4 v194, s[70:71]
	s_add_i32 m0, s0, 0x2000
	s_add_u32 s0, s70, 0x80000
	s_addc_u32 s1, s71, 0
	s_add_i32 s18, s18, s28
	global_load_lds_dwordx4 v204, s[70:71]
	s_mov_b32 m0, s18
	s_nop 0
	global_load_lds_dwordx4 v194, s[0:1]
	s_add_i32 m0, s18, 0x2000
	s_nop 0
	global_load_lds_dwordx4 v204, s[0:1]
	s_mov_b32 m0, s29
	s_nop 0
	global_load_lds_dwordx4 v194, vcc
	s_mov_b32 m0, s31
	s_nop 0
	global_load_lds_dwordx4 v204, vcc
	s_waitcnt vmcnt(8)
	s_waitcnt lgkmcnt(0)
	s_barrier
	v_mfma_f32_16x16x32_bf16 v[62:65], v[78:81], v[158:161], 0
	v_mfma_f32_16x16x32_bf16 v[62:65], v[90:93], v[162:165], v[62:65]
	v_mfma_f32_16x16x32_bf16 v[58:61], v[114:117], v[162:165], 0
	v_mfma_f32_16x16x32_bf16 v[58:61], v[102:105], v[158:161], v[58:61]
	v_mfma_f32_16x16x32_bf16 v[54:57], v[126:129], v[158:161], 0
	v_mfma_f32_16x16x32_bf16 v[54:57], v[134:137], v[162:165], v[54:57]
	v_mfma_f32_16x16x32_bf16 v[50:53], v[154:157], v[162:165], 0
	v_mfma_f32_16x16x32_bf16 v[50:53], v[142:145], v[158:161], v[50:53]
	v_mfma_f32_16x16x32_bf16 v[34:37], v[142:145], v[166:169], 0
	v_mfma_f32_16x16x32_bf16 v[34:37], v[154:157], v[178:181], v[34:37]
	v_mfma_f32_16x16x32_bf16 v[38:41], v[134:137], v[178:181], 0
	v_mfma_f32_16x16x32_bf16 v[38:41], v[126:129], v[166:169], v[38:41]
	v_mfma_f32_16x16x32_bf16 v[42:45], v[102:105], v[166:169], 0
	v_mfma_f32_16x16x32_bf16 v[42:45], v[114:117], v[178:181], v[42:45]
	v_mfma_f32_16x16x32_bf16 v[46:49], v[90:93], v[178:181], 0
	v_mfma_f32_16x16x32_bf16 v[46:49], v[78:81], v[166:169], v[46:49]
	v_mfma_f32_16x16x32_bf16 v[30:33], v[78:81], v[182:185], 0
	v_mfma_f32_16x16x32_bf16 v[30:33], v[90:93], v[186:189], v[30:33]
	v_mfma_f32_16x16x32_bf16 v[26:29], v[114:117], v[186:189], 0
	v_mfma_f32_16x16x32_bf16 v[26:29], v[102:105], v[182:185], v[26:29]
	v_mfma_f32_16x16x32_bf16 v[22:25], v[126:129], v[182:185], 0
	v_mfma_f32_16x16x32_bf16 v[22:25], v[134:137], v[186:189], v[22:25]
	v_mfma_f32_16x16x32_bf16 v[18:21], v[154:157], v[186:189], 0
	v_mfma_f32_16x16x32_bf16 v[18:21], v[142:145], v[182:185], v[18:21]
	v_mfma_f32_16x16x32_bf16 v[2:5], v[142:145], v[190:193], 0
	v_mfma_f32_16x16x32_bf16 v[2:5], v[154:157], v[214:217], v[2:5]
	v_mfma_f32_16x16x32_bf16 v[6:9], v[134:137], v[214:217], 0
	v_mfma_f32_16x16x32_bf16 v[6:9], v[126:129], v[190:193], v[6:9]
	v_mfma_f32_16x16x32_bf16 v[10:13], v[102:105], v[190:193], 0
	v_mfma_f32_16x16x32_bf16 v[10:13], v[114:117], v[214:217], v[10:13]
	v_mfma_f32_16x16x32_bf16 v[14:17], v[90:93], v[214:217], 0
	v_mfma_f32_16x16x32_bf16 v[14:17], v[78:81], v[190:193], v[14:17]
	s_barrier
	s_add_i32 s18, 0, 0x18000
	s_add_i32 s19, 0, 0x1c000
	v_add_u32_e32 v114, s18, v1
	v_add_u32_e32 v154, s19, v1
	ds_read_b128 v[78:81], v114
	ds_read_b128 v[90:93], v114 offset:1024
	ds_read_b128 v[102:105], v114 offset:2048
	ds_read_b128 v[114:117], v114 offset:3072
	ds_read_b128 v[126:129], v154
	ds_read_b128 v[134:137], v154 offset:1024
	ds_read_b128 v[142:145], v154 offset:2048
	ds_read_b128 v[154:157], v154 offset:3072
	s_add_u32 s0, vcc_lo, 0x80000
	s_addc_u32 s1, vcc_hi, 0
	s_mov_b32 m0, s33
	ds_read_b128 v[158:161], v237 offset:32768
	ds_read_b128 v[162:165], v237 offset:33792
	ds_read_b128 v[166:169], v237 offset:34816
	ds_read_b128 v[178:181], v237 offset:35840
	ds_read_b128 v[182:185], v237 offset:36864
	ds_read_b128 v[186:189], v237 offset:37888
	ds_read_b128 v[190:193], v237 offset:38912
	ds_read_b128 v[214:217], v237 offset:39936
	global_load_lds_dwordx4 v194, s[0:1]
	s_mov_b32 m0, s43
	s_nop 0
	global_load_lds_dwordx4 v204, s[0:1]
	s_waitcnt vmcnt(8)
	s_waitcnt lgkmcnt(0)
	s_barrier
	v_mfma_f32_16x16x32_bf16 v[174:177], v[78:81], v[158:161], v[174:177]
	v_mfma_f32_16x16x32_bf16 v[174:177], v[90:93], v[162:165], v[174:177]
	v_mfma_f32_16x16x32_bf16 v[170:173], v[114:117], v[162:165], v[170:173]
	v_mfma_f32_16x16x32_bf16 v[170:173], v[102:105], v[158:161], v[170:173]
	v_mfma_f32_16x16x32_bf16 v[150:153], v[126:129], v[158:161], v[150:153]
	v_mfma_f32_16x16x32_bf16 v[150:153], v[134:137], v[162:165], v[150:153]
	v_mfma_f32_16x16x32_bf16 v[146:149], v[154:157], v[162:165], v[146:149]
	v_mfma_f32_16x16x32_bf16 v[146:149], v[142:145], v[158:161], v[146:149]
	v_mfma_f32_16x16x32_bf16 v[118:121], v[142:145], v[166:169], v[118:121]
	v_mfma_f32_16x16x32_bf16 v[118:121], v[154:157], v[178:181], v[118:121]
	v_mfma_f32_16x16x32_bf16 v[122:125], v[134:137], v[178:181], v[122:125]
	v_mfma_f32_16x16x32_bf16 v[122:125], v[126:129], v[166:169], v[122:125]
	v_mfma_f32_16x16x32_bf16 v[130:133], v[102:105], v[166:169], v[130:133]
	v_mfma_f32_16x16x32_bf16 v[130:133], v[114:117], v[178:181], v[130:133]
	v_mfma_f32_16x16x32_bf16 v[138:141], v[90:93], v[178:181], v[138:141]
	v_mfma_f32_16x16x32_bf16 v[138:141], v[78:81], v[166:169], v[138:141]
	v_mfma_f32_16x16x32_bf16 v[110:113], v[78:81], v[182:185], v[110:113]
	v_mfma_f32_16x16x32_bf16 v[110:113], v[90:93], v[186:189], v[110:113]
	v_mfma_f32_16x16x32_bf16 v[106:109], v[114:117], v[186:189], v[106:109]
	v_mfma_f32_16x16x32_bf16 v[106:109], v[102:105], v[182:185], v[106:109]
	v_mfma_f32_16x16x32_bf16 v[98:101], v[126:129], v[182:185], v[98:101]
	v_mfma_f32_16x16x32_bf16 v[98:101], v[134:137], v[186:189], v[98:101]
	v_mfma_f32_16x16x32_bf16 v[94:97], v[154:157], v[186:189], v[94:97]
	v_mfma_f32_16x16x32_bf16 v[94:97], v[142:145], v[182:185], v[94:97]
	v_mfma_f32_16x16x32_bf16 v[66:69], v[142:145], v[190:193], v[66:69]
	v_mfma_f32_16x16x32_bf16 v[66:69], v[154:157], v[214:217], v[66:69]
	v_mfma_f32_16x16x32_bf16 v[74:77], v[134:137], v[214:217], v[74:77]
	v_mfma_f32_16x16x32_bf16 v[74:77], v[126:129], v[190:193], v[74:77]
	v_mfma_f32_16x16x32_bf16 v[82:85], v[102:105], v[190:193], v[82:85]
	v_mfma_f32_16x16x32_bf16 v[82:85], v[114:117], v[214:217], v[82:85]
	v_mfma_f32_16x16x32_bf16 v[86:89], v[90:93], v[214:217], v[86:89]
	v_mfma_f32_16x16x32_bf16 v[86:89], v[78:81], v[190:193], v[86:89]
	s_barrier
	s_add_u32 s98, s70, 0x80
	s_addc_u32 s99, s71, 0
	s_add_u32 s100, vcc_lo, 0x80
	s_addc_u32 s101, vcc_hi, 0
	s_add_i32 s0, s18, s28
	s_mov_b32 m0, s0
	ds_read_b128 v[158:161], v237 offset:49152
	ds_read_b128 v[162:165], v237 offset:50176
	ds_read_b128 v[166:169], v237 offset:51200
	ds_read_b128 v[178:181], v237 offset:52224
	ds_read_b128 v[182:185], v237 offset:53248
	ds_read_b128 v[186:189], v237 offset:54272
	ds_read_b128 v[190:193], v237 offset:55296
	ds_read_b128 v[214:217], v237 offset:56320
	global_load_lds_dwordx4 v194, s[98:99]
	s_add_i32 m0, s0, 0x2000
	s_add_u32 s0, s70, 0x80080
	s_addc_u32 s1, s71, 0
	s_add_i32 s18, s19, s28
	global_load_lds_dwordx4 v204, s[98:99]
	s_mov_b32 m0, s18
	s_nop 0
	global_load_lds_dwordx4 v194, s[0:1]
	s_add_i32 m0, s18, 0x2000
	s_nop 0
	global_load_lds_dwordx4 v204, s[0:1]
	s_mov_b32 m0, s68
	s_nop 0
	global_load_lds_dwordx4 v194, s[100:101]
	s_mov_b32 m0, s79
	s_nop 0
	global_load_lds_dwordx4 v204, s[100:101]
	s_waitcnt vmcnt(8)
	s_waitcnt lgkmcnt(0)
	s_barrier
	v_mfma_f32_16x16x32_bf16 v[62:65], v[78:81], v[158:161], v[62:65]
	v_mfma_f32_16x16x32_bf16 v[62:65], v[90:93], v[162:165], v[62:65]
	v_mfma_f32_16x16x32_bf16 v[58:61], v[114:117], v[162:165], v[58:61]
	v_mfma_f32_16x16x32_bf16 v[58:61], v[102:105], v[158:161], v[58:61]
	v_mfma_f32_16x16x32_bf16 v[54:57], v[126:129], v[158:161], v[54:57]
	v_mfma_f32_16x16x32_bf16 v[54:57], v[134:137], v[162:165], v[54:57]
	v_mfma_f32_16x16x32_bf16 v[50:53], v[154:157], v[162:165], v[50:53]
	v_mfma_f32_16x16x32_bf16 v[50:53], v[142:145], v[158:161], v[50:53]
	v_mfma_f32_16x16x32_bf16 v[34:37], v[142:145], v[166:169], v[34:37]
	v_mfma_f32_16x16x32_bf16 v[34:37], v[154:157], v[178:181], v[34:37]
	v_mfma_f32_16x16x32_bf16 v[38:41], v[134:137], v[178:181], v[38:41]
	v_mfma_f32_16x16x32_bf16 v[38:41], v[126:129], v[166:169], v[38:41]
	v_mfma_f32_16x16x32_bf16 v[42:45], v[102:105], v[166:169], v[42:45]
	v_mfma_f32_16x16x32_bf16 v[42:45], v[114:117], v[178:181], v[42:45]
	v_mfma_f32_16x16x32_bf16 v[46:49], v[90:93], v[178:181], v[46:49]
	v_mfma_f32_16x16x32_bf16 v[46:49], v[78:81], v[166:169], v[46:49]
	v_mfma_f32_16x16x32_bf16 v[30:33], v[78:81], v[182:185], v[30:33]
	v_mfma_f32_16x16x32_bf16 v[30:33], v[90:93], v[186:189], v[30:33]
	v_mfma_f32_16x16x32_bf16 v[26:29], v[114:117], v[186:189], v[26:29]
	v_mfma_f32_16x16x32_bf16 v[26:29], v[102:105], v[182:185], v[26:29]
	v_mfma_f32_16x16x32_bf16 v[22:25], v[126:129], v[182:185], v[22:25]
	v_mfma_f32_16x16x32_bf16 v[22:25], v[134:137], v[186:189], v[22:25]
	v_mfma_f32_16x16x32_bf16 v[18:21], v[154:157], v[186:189], v[18:21]
	v_mfma_f32_16x16x32_bf16 v[18:21], v[142:145], v[182:185], v[18:21]
	v_mfma_f32_16x16x32_bf16 v[2:5], v[142:145], v[190:193], v[2:5]
	v_mfma_f32_16x16x32_bf16 v[2:5], v[154:157], v[214:217], v[2:5]
	v_mfma_f32_16x16x32_bf16 v[6:9], v[134:137], v[214:217], v[6:9]
	v_mfma_f32_16x16x32_bf16 v[6:9], v[126:129], v[190:193], v[6:9]
	v_mfma_f32_16x16x32_bf16 v[10:13], v[102:105], v[190:193], v[10:13]
	v_mfma_f32_16x16x32_bf16 v[10:13], v[114:117], v[214:217], v[10:13]
	v_mfma_f32_16x16x32_bf16 v[14:17], v[90:93], v[214:217], v[14:17]
	v_mfma_f32_16x16x32_bf16 v[14:17], v[78:81], v[190:193], v[14:17]
	s_barrier
	s_add_i32 s57, s57, 2
	s_add_u32 s51, s51, 0x100
	s_addc_u32 s53, s53, 0
	s_cmp_gt_u32 s57, 29
	s_mov_b64 s[76:77], s[90:91]
	s_cbranch_scc1 .LBB0_512
	s_branch .LBB0_510

.LBB0_581:
	s_add_u32 s18, s62, 0xfff80080
	s_addc_u32 s19, s63, -1
	s_and_b64 s[0:1], s[64:65], exec
	s_cselect_b32 s71, s22, s19
	s_cselect_b32 s70, s23, s18
	s_cselect_b32 s65, s39, s58
	s_cselect_b32 s64, s47, s53
	s_add_i32 s0, 0, 0x10000
	v_add_u32_e32 v153, s0, v1
	s_add_i32 s18, 0, 0x14000
	ds_read_b128 v[144:147], v153
	ds_read_b128 v[148:151], v153 offset:1024
	ds_read_b128 v[154:157], v153 offset:2048
	ds_read_b128 v[158:161], v153 offset:3072
	v_add_u32_e32 v153, s18, v1
	ds_read_b128 v[162:165], v153
	ds_read_b128 v[166:169], v153 offset:1024
	ds_read_b128 v[170:173], v153 offset:2048
	ds_read_b128 v[174:177], v153 offset:3072
	s_add_i32 m0, s29, 0xc000
	ds_read_b128 v[178:181], v152
	ds_read_b128 v[182:185], v152 offset:1024
	ds_read_b128 v[186:189], v152 offset:2048
	ds_read_b128 v[190:193], v152 offset:3072
	ds_read_b128 v[204:207], v152 offset:4096
	ds_read_b128 v[208:211], v152 offset:5120
	ds_read_b128 v[212:215], v152 offset:6144
	ds_read_b128 v[216:219], v152 offset:7168
	global_load_lds_dwordx4 v136, s[62:63]
	s_add_i32 m0, s29, 0xe000
	s_nop 0
	global_load_lds_dwordx4 v138, s[62:63]
	s_waitcnt vmcnt(8)
	s_waitcnt lgkmcnt(0)
	s_barrier
	v_mfma_f32_16x16x32_bf16 v[126:129], v[144:147], v[178:181], v[126:129]
	v_mfma_f32_16x16x32_bf16 v[126:129], v[148:151], v[182:185], v[126:129]
	v_mfma_f32_16x16x32_bf16 v[122:125], v[158:161], v[182:185], v[122:125]
	v_mfma_f32_16x16x32_bf16 v[122:125], v[154:157], v[178:181], v[122:125]
	v_mfma_f32_16x16x32_bf16 v[118:121], v[162:165], v[178:181], v[118:121]
	v_mfma_f32_16x16x32_bf16 v[118:121], v[166:169], v[182:185], v[118:121]
	v_mfma_f32_16x16x32_bf16 v[114:117], v[174:177], v[182:185], v[114:117]
	v_mfma_f32_16x16x32_bf16 v[114:117], v[170:173], v[178:181], v[114:117]
	v_mfma_f32_16x16x32_bf16 v[98:101], v[170:173], v[186:189], v[98:101]
	v_mfma_f32_16x16x32_bf16 v[98:101], v[174:177], v[190:193], v[98:101]
	v_mfma_f32_16x16x32_bf16 v[102:105], v[166:169], v[190:193], v[102:105]
	v_mfma_f32_16x16x32_bf16 v[102:105], v[162:165], v[186:189], v[102:105]
	v_mfma_f32_16x16x32_bf16 v[106:109], v[154:157], v[186:189], v[106:109]
	v_mfma_f32_16x16x32_bf16 v[106:109], v[158:161], v[190:193], v[106:109]
	v_mfma_f32_16x16x32_bf16 v[110:113], v[148:151], v[190:193], v[110:113]
	v_mfma_f32_16x16x32_bf16 v[110:113], v[144:147], v[186:189], v[110:113]
	v_mfma_f32_16x16x32_bf16 v[94:97], v[144:147], v[204:207], v[94:97]
	v_mfma_f32_16x16x32_bf16 v[94:97], v[148:151], v[208:211], v[94:97]
	v_mfma_f32_16x16x32_bf16 v[90:93], v[158:161], v[208:211], v[90:93]
	v_mfma_f32_16x16x32_bf16 v[90:93], v[154:157], v[204:207], v[90:93]
	v_mfma_f32_16x16x32_bf16 v[86:89], v[162:165], v[204:207], v[86:89]
	v_mfma_f32_16x16x32_bf16 v[86:89], v[166:169], v[208:211], v[86:89]
	v_mfma_f32_16x16x32_bf16 v[82:85], v[174:177], v[208:211], v[82:85]
	v_mfma_f32_16x16x32_bf16 v[82:85], v[170:173], v[204:207], v[82:85]
	v_mfma_f32_16x16x32_bf16 v[66:69], v[170:173], v[212:215], v[66:69]
	v_mfma_f32_16x16x32_bf16 v[66:69], v[174:177], v[216:219], v[66:69]
	v_mfma_f32_16x16x32_bf16 v[70:73], v[166:169], v[216:219], v[70:73]
	v_mfma_f32_16x16x32_bf16 v[70:73], v[162:165], v[212:215], v[70:73]
	v_mfma_f32_16x16x32_bf16 v[74:77], v[154:157], v[212:215], v[74:77]
	v_mfma_f32_16x16x32_bf16 v[74:77], v[158:161], v[216:219], v[74:77]
	v_mfma_f32_16x16x32_bf16 v[78:81], v[148:151], v[216:219], v[78:81]
	v_mfma_f32_16x16x32_bf16 v[78:81], v[144:147], v[212:215], v[78:81]
	s_barrier
	s_add_i32 s0, s0, s28
	s_mov_b32 m0, s0
	ds_read_b128 v[178:181], v152 offset:16384
	ds_read_b128 v[182:185], v152 offset:17408
	ds_read_b128 v[186:189], v152 offset:18432
	ds_read_b128 v[190:193], v152 offset:19456
	ds_read_b128 v[204:207], v152 offset:20480
	ds_read_b128 v[208:211], v152 offset:21504
	ds_read_b128 v[212:215], v152 offset:22528
	ds_read_b128 v[216:219], v152 offset:23552
	global_load_lds_dwordx4 v194, s[64:65]
	s_add_i32 m0, s0, 0x2000
	s_add_u32 s0, s64, 0x80000
	s_addc_u32 s1, s65, 0
	s_add_i32 s18, s18, s28
	global_load_lds_dwordx4 v130, s[64:65]
	s_mov_b32 m0, s18
	s_nop 0
	global_load_lds_dwordx4 v194, s[0:1]
	s_add_i32 m0, s18, 0x2000
	s_nop 0
	global_load_lds_dwordx4 v130, s[0:1]
	s_mov_b32 m0, s29
	s_nop 0
	global_load_lds_dwordx4 v194, s[70:71]
	s_mov_b32 m0, s31
	s_nop 0
	global_load_lds_dwordx4 v130, s[70:71]
	s_waitcnt vmcnt(8)
	s_waitcnt lgkmcnt(0)
	s_barrier
	v_mfma_f32_16x16x32_bf16 v[62:65], v[144:147], v[178:181], v[62:65]
	v_mfma_f32_16x16x32_bf16 v[62:65], v[148:151], v[182:185], v[62:65]
	v_mfma_f32_16x16x32_bf16 v[58:61], v[158:161], v[182:185], v[58:61]
	v_mfma_f32_16x16x32_bf16 v[58:61], v[154:157], v[178:181], v[58:61]
	v_mfma_f32_16x16x32_bf16 v[54:57], v[162:165], v[178:181], v[54:57]
	v_mfma_f32_16x16x32_bf16 v[54:57], v[166:169], v[182:185], v[54:57]
	v_mfma_f32_16x16x32_bf16 v[50:53], v[174:177], v[182:185], v[50:53]
	v_mfma_f32_16x16x32_bf16 v[50:53], v[170:173], v[178:181], v[50:53]
	v_mfma_f32_16x16x32_bf16 v[34:37], v[170:173], v[186:189], v[34:37]
	v_mfma_f32_16x16x32_bf16 v[34:37], v[174:177], v[190:193], v[34:37]
	v_mfma_f32_16x16x32_bf16 v[38:41], v[166:169], v[190:193], v[38:41]
	v_mfma_f32_16x16x32_bf16 v[38:41], v[162:165], v[186:189], v[38:41]
	v_mfma_f32_16x16x32_bf16 v[42:45], v[154:157], v[186:189], v[42:45]
	v_mfma_f32_16x16x32_bf16 v[42:45], v[158:161], v[190:193], v[42:45]
	v_mfma_f32_16x16x32_bf16 v[46:49], v[148:151], v[190:193], v[46:49]
	v_mfma_f32_16x16x32_bf16 v[46:49], v[144:147], v[186:189], v[46:49]
	v_mfma_f32_16x16x32_bf16 v[30:33], v[144:147], v[204:207], v[30:33]
	v_mfma_f32_16x16x32_bf16 v[30:33], v[148:151], v[208:211], v[30:33]
	v_mfma_f32_16x16x32_bf16 v[26:29], v[158:161], v[208:211], v[26:29]
	v_mfma_f32_16x16x32_bf16 v[26:29], v[154:157], v[204:207], v[26:29]
	v_mfma_f32_16x16x32_bf16 v[22:25], v[162:165], v[204:207], v[22:25]
	v_mfma_f32_16x16x32_bf16 v[22:25], v[166:169], v[208:211], v[22:25]
	v_mfma_f32_16x16x32_bf16 v[18:21], v[174:177], v[208:211], v[18:21]
	v_mfma_f32_16x16x32_bf16 v[18:21], v[170:173], v[204:207], v[18:21]
	v_mfma_f32_16x16x32_bf16 v[2:5], v[170:173], v[212:215], v[2:5]
	v_mfma_f32_16x16x32_bf16 v[2:5], v[174:177], v[216:219], v[2:5]
	v_mfma_f32_16x16x32_bf16 v[6:9], v[166:169], v[216:219], v[6:9]
	v_mfma_f32_16x16x32_bf16 v[6:9], v[162:165], v[212:215], v[6:9]
	v_mfma_f32_16x16x32_bf16 v[10:13], v[154:157], v[212:215], v[10:13]
	v_mfma_f32_16x16x32_bf16 v[10:13], v[158:161], v[216:219], v[10:13]
	v_mfma_f32_16x16x32_bf16 v[14:17], v[148:151], v[216:219], v[14:17]
	v_mfma_f32_16x16x32_bf16 v[14:17], v[144:147], v[212:215], v[14:17]
	s_barrier
	s_add_i32 s18, 0, 0x18000
	v_add_u32_e32 v153, s18, v1
	s_add_i32 s19, 0, 0x1c000
	ds_read_b128 v[144:147], v153
	ds_read_b128 v[148:151], v153 offset:1024
	ds_read_b128 v[154:157], v153 offset:2048
	ds_read_b128 v[158:161], v153 offset:3072
	v_add_u32_e32 v153, s19, v1
	ds_read_b128 v[162:165], v153
	ds_read_b128 v[166:169], v153 offset:1024
	ds_read_b128 v[170:173], v153 offset:2048
	ds_read_b128 v[174:177], v153 offset:3072
	s_add_u32 s0, s70, 0x80000
	s_addc_u32 s1, s71, 0
	s_mov_b32 m0, s33
	ds_read_b128 v[178:181], v152 offset:32768
	ds_read_b128 v[182:185], v152 offset:33792
	ds_read_b128 v[186:189], v152 offset:34816
	ds_read_b128 v[190:193], v152 offset:35840
	ds_read_b128 v[204:207], v152 offset:36864
	ds_read_b128 v[208:211], v152 offset:37888
	ds_read_b128 v[212:215], v152 offset:38912
	ds_read_b128 v[216:219], v152 offset:39936
	global_load_lds_dwordx4 v194, s[0:1]
	s_mov_b32 m0, s40
	s_nop 0
	global_load_lds_dwordx4 v130, s[0:1]
	s_waitcnt vmcnt(8)
	s_waitcnt lgkmcnt(0)
	s_barrier
	v_mfma_f32_16x16x32_bf16 v[126:129], v[144:147], v[178:181], v[126:129]
	v_mfma_f32_16x16x32_bf16 v[126:129], v[148:151], v[182:185], v[126:129]
	v_mfma_f32_16x16x32_bf16 v[122:125], v[158:161], v[182:185], v[122:125]
	v_mfma_f32_16x16x32_bf16 v[122:125], v[154:157], v[178:181], v[122:125]
	v_mfma_f32_16x16x32_bf16 v[118:121], v[162:165], v[178:181], v[118:121]
	v_mfma_f32_16x16x32_bf16 v[118:121], v[166:169], v[182:185], v[118:121]
	v_mfma_f32_16x16x32_bf16 v[114:117], v[174:177], v[182:185], v[114:117]
	v_mfma_f32_16x16x32_bf16 v[114:117], v[170:173], v[178:181], v[114:117]
	v_mfma_f32_16x16x32_bf16 v[98:101], v[170:173], v[186:189], v[98:101]
	v_mfma_f32_16x16x32_bf16 v[98:101], v[174:177], v[190:193], v[98:101]
	v_mfma_f32_16x16x32_bf16 v[102:105], v[166:169], v[190:193], v[102:105]
	v_mfma_f32_16x16x32_bf16 v[102:105], v[162:165], v[186:189], v[102:105]
	v_mfma_f32_16x16x32_bf16 v[106:109], v[154:157], v[186:189], v[106:109]
	v_mfma_f32_16x16x32_bf16 v[106:109], v[158:161], v[190:193], v[106:109]
	v_mfma_f32_16x16x32_bf16 v[110:113], v[148:151], v[190:193], v[110:113]
	v_mfma_f32_16x16x32_bf16 v[110:113], v[144:147], v[186:189], v[110:113]
	v_mfma_f32_16x16x32_bf16 v[94:97], v[144:147], v[204:207], v[94:97]
	v_mfma_f32_16x16x32_bf16 v[94:97], v[148:151], v[208:211], v[94:97]
	v_mfma_f32_16x16x32_bf16 v[90:93], v[158:161], v[208:211], v[90:93]
	v_mfma_f32_16x16x32_bf16 v[90:93], v[154:157], v[204:207], v[90:93]
	v_mfma_f32_16x16x32_bf16 v[86:89], v[162:165], v[204:207], v[86:89]
	v_mfma_f32_16x16x32_bf16 v[86:89], v[166:169], v[208:211], v[86:89]
	v_mfma_f32_16x16x32_bf16 v[82:85], v[174:177], v[208:211], v[82:85]
	v_mfma_f32_16x16x32_bf16 v[82:85], v[170:173], v[204:207], v[82:85]
	v_mfma_f32_16x16x32_bf16 v[66:69], v[170:173], v[212:215], v[66:69]
	v_mfma_f32_16x16x32_bf16 v[66:69], v[174:177], v[216:219], v[66:69]
	v_mfma_f32_16x16x32_bf16 v[70:73], v[166:169], v[216:219], v[70:73]
	v_mfma_f32_16x16x32_bf16 v[70:73], v[162:165], v[212:215], v[70:73]
	v_mfma_f32_16x16x32_bf16 v[74:77], v[154:157], v[212:215], v[74:77]
	v_mfma_f32_16x16x32_bf16 v[74:77], v[158:161], v[216:219], v[74:77]
	v_mfma_f32_16x16x32_bf16 v[78:81], v[148:151], v[216:219], v[78:81]
	v_mfma_f32_16x16x32_bf16 v[78:81], v[144:147], v[212:215], v[78:81]
	s_barrier
	s_add_u32 s98, s64, 0x80
	s_addc_u32 s99, s65, 0
	s_add_u32 s100, s70, 0x80
	s_addc_u32 s101, s71, 0
	s_add_i32 s0, s18, s28
	s_mov_b32 m0, s0
	ds_read_b128 v[178:181], v152 offset:49152
	ds_read_b128 v[182:185], v152 offset:50176
	ds_read_b128 v[186:189], v152 offset:51200
	ds_read_b128 v[190:193], v152 offset:52224
	ds_read_b128 v[204:207], v152 offset:53248
	ds_read_b128 v[208:211], v152 offset:54272
	ds_read_b128 v[212:215], v152 offset:55296
	ds_read_b128 v[216:219], v152 offset:56320
	global_load_lds_dwordx4 v194, s[98:99]
	s_add_i32 m0, s0, 0x2000
	s_add_u32 s0, s64, 0x80080
	s_addc_u32 s1, s65, 0
	s_add_i32 s18, s19, s28
	global_load_lds_dwordx4 v130, s[98:99]
	s_mov_b32 m0, s18
	s_nop 0
	global_load_lds_dwordx4 v194, s[0:1]
	s_add_i32 m0, s18, 0x2000
	s_nop 0
	global_load_lds_dwordx4 v130, s[0:1]
	s_mov_b32 m0, s54
	s_nop 0
	global_load_lds_dwordx4 v194, s[100:101]
	s_mov_b32 m0, s57
	s_nop 0
	global_load_lds_dwordx4 v130, s[100:101]
	s_waitcnt vmcnt(8)
	s_waitcnt lgkmcnt(0)
	s_barrier
	v_mfma_f32_16x16x32_bf16 v[62:65], v[144:147], v[178:181], v[62:65]
	v_mfma_f32_16x16x32_bf16 v[62:65], v[148:151], v[182:185], v[62:65]
	v_mfma_f32_16x16x32_bf16 v[58:61], v[158:161], v[182:185], v[58:61]
	v_mfma_f32_16x16x32_bf16 v[58:61], v[154:157], v[178:181], v[58:61]
	v_mfma_f32_16x16x32_bf16 v[54:57], v[162:165], v[178:181], v[54:57]
	v_mfma_f32_16x16x32_bf16 v[54:57], v[166:169], v[182:185], v[54:57]
	v_mfma_f32_16x16x32_bf16 v[50:53], v[174:177], v[182:185], v[50:53]
	v_mfma_f32_16x16x32_bf16 v[50:53], v[170:173], v[178:181], v[50:53]
	v_mfma_f32_16x16x32_bf16 v[34:37], v[170:173], v[186:189], v[34:37]
	v_mfma_f32_16x16x32_bf16 v[34:37], v[174:177], v[190:193], v[34:37]
	v_mfma_f32_16x16x32_bf16 v[38:41], v[166:169], v[190:193], v[38:41]
	v_mfma_f32_16x16x32_bf16 v[38:41], v[162:165], v[186:189], v[38:41]
	v_mfma_f32_16x16x32_bf16 v[42:45], v[154:157], v[186:189], v[42:45]
	v_mfma_f32_16x16x32_bf16 v[42:45], v[158:161], v[190:193], v[42:45]
	v_mfma_f32_16x16x32_bf16 v[46:49], v[148:151], v[190:193], v[46:49]
	v_mfma_f32_16x16x32_bf16 v[46:49], v[144:147], v[186:189], v[46:49]
	v_mfma_f32_16x16x32_bf16 v[30:33], v[144:147], v[204:207], v[30:33]
	v_mfma_f32_16x16x32_bf16 v[30:33], v[148:151], v[208:211], v[30:33]
	v_mfma_f32_16x16x32_bf16 v[26:29], v[158:161], v[208:211], v[26:29]
	v_mfma_f32_16x16x32_bf16 v[26:29], v[154:157], v[204:207], v[26:29]
	v_mfma_f32_16x16x32_bf16 v[22:25], v[162:165], v[204:207], v[22:25]
	v_mfma_f32_16x16x32_bf16 v[22:25], v[166:169], v[208:211], v[22:25]
	v_mfma_f32_16x16x32_bf16 v[18:21], v[174:177], v[208:211], v[18:21]
	v_mfma_f32_16x16x32_bf16 v[18:21], v[170:173], v[204:207], v[18:21]
	v_mfma_f32_16x16x32_bf16 v[2:5], v[170:173], v[212:215], v[2:5]
	v_mfma_f32_16x16x32_bf16 v[2:5], v[174:177], v[216:219], v[2:5]
	v_mfma_f32_16x16x32_bf16 v[6:9], v[166:169], v[216:219], v[6:9]
	v_mfma_f32_16x16x32_bf16 v[6:9], v[162:165], v[212:215], v[6:9]
	v_mfma_f32_16x16x32_bf16 v[10:13], v[154:157], v[212:215], v[10:13]
	v_mfma_f32_16x16x32_bf16 v[10:13], v[158:161], v[216:219], v[10:13]
	v_mfma_f32_16x16x32_bf16 v[14:17], v[148:151], v[216:219], v[14:17]
	v_mfma_f32_16x16x32_bf16 v[14:17], v[144:147], v[212:215], v[14:17]
	s_barrier
	s_add_i32 s76, s76, 2
	s_add_u32 s62, s62, 0x100
	s_addc_u32 s63, s63, 0
	s_add_u32 s53, s53, 0x100
	s_addc_u32 s58, s58, 0
	s_cmp_gt_u32 s76, 29
	s_cbranch_scc1 .LBB0_584

.Lpeel_disp_gu:
	s_cmp_lg_u32 s76, -2
	s_cbranch_scc1 .LBB0_581
	s_add_u32 s18, s62, 0xfff80080
	s_addc_u32 s19, s63, -1
	s_and_b64 s[0:1], s[64:65], exec
	s_cselect_b32 s71, s22, s19
	s_cselect_b32 s70, s23, s18
	s_cselect_b32 s65, s39, s58
	s_cselect_b32 s64, s47, s53
	s_add_i32 s0, 0, 0x10000
	v_add_u32_e32 v153, s0, v1
	s_add_i32 s18, 0, 0x14000
	ds_read_b128 v[144:147], v153
	ds_read_b128 v[148:151], v153 offset:1024
	ds_read_b128 v[154:157], v153 offset:2048
	ds_read_b128 v[158:161], v153 offset:3072
	v_add_u32_e32 v153, s18, v1
	ds_read_b128 v[162:165], v153
	ds_read_b128 v[166:169], v153 offset:1024
	ds_read_b128 v[170:173], v153 offset:2048
	ds_read_b128 v[174:177], v153 offset:3072
	s_add_i32 m0, s29, 0xc000
	ds_read_b128 v[178:181], v152
	ds_read_b128 v[182:185], v152 offset:1024
	ds_read_b128 v[186:189], v152 offset:2048
	ds_read_b128 v[190:193], v152 offset:3072
	ds_read_b128 v[204:207], v152 offset:4096
	ds_read_b128 v[208:211], v152 offset:5120
	ds_read_b128 v[212:215], v152 offset:6144
	ds_read_b128 v[216:219], v152 offset:7168
	global_load_lds_dwordx4 v136, s[62:63]
	s_add_i32 m0, s29, 0xe000
	s_nop 0
	global_load_lds_dwordx4 v138, s[62:63]
	s_waitcnt vmcnt(8)
	s_waitcnt lgkmcnt(0)
	s_barrier
	v_mfma_f32_16x16x32_bf16 v[126:129], v[144:147], v[178:181], 0
	v_mfma_f32_16x16x32_bf16 v[126:129], v[148:151], v[182:185], v[126:129]
	v_mfma_f32_16x16x32_bf16 v[122:125], v[158:161], v[182:185], 0
	v_mfma_f32_16x16x32_bf16 v[122:125], v[154:157], v[178:181], v[122:125]
	v_mfma_f32_16x16x32_bf16 v[118:121], v[162:165], v[178:181], 0
	v_mfma_f32_16x16x32_bf16 v[118:121], v[166:169], v[182:185], v[118:121]
	v_mfma_f32_16x16x32_bf16 v[114:117], v[174:177], v[182:185], 0
	v_mfma_f32_16x16x32_bf16 v[114:117], v[170:173], v[178:181], v[114:117]
	v_mfma_f32_16x16x32_bf16 v[98:101], v[170:173], v[186:189], 0
	v_mfma_f32_16x16x32_bf16 v[98:101], v[174:177], v[190:193], v[98:101]
	v_mfma_f32_16x16x32_bf16 v[102:105], v[166:169], v[190:193], 0
	v_mfma_f32_16x16x32_bf16 v[102:105], v[162:165], v[186:189], v[102:105]
	v_mfma_f32_16x16x32_bf16 v[106:109], v[154:157], v[186:189], 0
	v_mfma_f32_16x16x32_bf16 v[106:109], v[158:161], v[190:193], v[106:109]
	v_mfma_f32_16x16x32_bf16 v[110:113], v[148:151], v[190:193], 0
	v_mfma_f32_16x16x32_bf16 v[110:113], v[144:147], v[186:189], v[110:113]
	v_mfma_f32_16x16x32_bf16 v[94:97], v[144:147], v[204:207], 0
	v_mfma_f32_16x16x32_bf16 v[94:97], v[148:151], v[208:211], v[94:97]
	v_mfma_f32_16x16x32_bf16 v[90:93], v[158:161], v[208:211], 0
	v_mfma_f32_16x16x32_bf16 v[90:93], v[154:157], v[204:207], v[90:93]
	v_mfma_f32_16x16x32_bf16 v[86:89], v[162:165], v[204:207], 0
	v_mfma_f32_16x16x32_bf16 v[86:89], v[166:169], v[208:211], v[86:89]
	v_mfma_f32_16x16x32_bf16 v[82:85], v[174:177], v[208:211], 0
	v_mfma_f32_16x16x32_bf16 v[82:85], v[170:173], v[204:207], v[82:85]
	v_mfma_f32_16x16x32_bf16 v[66:69], v[170:173], v[212:215], 0
	v_mfma_f32_16x16x32_bf16 v[66:69], v[174:177], v[216:219], v[66:69]
	v_mfma_f32_16x16x32_bf16 v[70:73], v[166:169], v[216:219], 0
	v_mfma_f32_16x16x32_bf16 v[70:73], v[162:165], v[212:215], v[70:73]
	v_mfma_f32_16x16x32_bf16 v[74:77], v[154:157], v[212:215], 0
	v_mfma_f32_16x16x32_bf16 v[74:77], v[158:161], v[216:219], v[74:77]
	v_mfma_f32_16x16x32_bf16 v[78:81], v[148:151], v[216:219], 0
	v_mfma_f32_16x16x32_bf16 v[78:81], v[144:147], v[212:215], v[78:81]
	s_barrier
	s_add_i32 s0, s0, s28
	s_mov_b32 m0, s0
	ds_read_b128 v[178:181], v152 offset:16384
	ds_read_b128 v[182:185], v152 offset:17408
	ds_read_b128 v[186:189], v152 offset:18432
	ds_read_b128 v[190:193], v152 offset:19456
	ds_read_b128 v[204:207], v152 offset:20480
	ds_read_b128 v[208:211], v152 offset:21504
	ds_read_b128 v[212:215], v152 offset:22528
	ds_read_b128 v[216:219], v152 offset:23552
	global_load_lds_dwordx4 v194, s[64:65]
	s_add_i32 m0, s0, 0x2000
	s_add_u32 s0, s64, 0x80000
	s_addc_u32 s1, s65, 0
	s_add_i32 s18, s18, s28
	global_load_lds_dwordx4 v130, s[64:65]
	s_mov_b32 m0, s18
	s_nop 0
	global_load_lds_dwordx4 v194, s[0:1]
	s_add_i32 m0, s18, 0x2000
	s_nop 0
	global_load_lds_dwordx4 v130, s[0:1]
	s_mov_b32 m0, s29
	s_nop 0
	global_load_lds_dwordx4 v194, s[70:71]
	s_mov_b32 m0, s31
	s_nop 0
	global_load_lds_dwordx4 v130, s[70:71]
	s_waitcnt vmcnt(8)
	s_waitcnt lgkmcnt(0)
	s_barrier
	v_mfma_f32_16x16x32_bf16 v[62:65], v[144:147], v[178:181], 0
	v_mfma_f32_16x16x32_bf16 v[62:65], v[148:151], v[182:185], v[62:65]
	v_mfma_f32_16x16x32_bf16 v[58:61], v[158:161], v[182:185], 0
	v_mfma_f32_16x16x32_bf16 v[58:61], v[154:157], v[178:181], v[58:61]
	v_mfma_f32_16x16x32_bf16 v[54:57], v[162:165], v[178:181], 0
	v_mfma_f32_16x16x32_bf16 v[54:57], v[166:169], v[182:185], v[54:57]
	v_mfma_f32_16x16x32_bf16 v[50:53], v[174:177], v[182:185], 0
	v_mfma_f32_16x16x32_bf16 v[50:53], v[170:173], v[178:181], v[50:53]
	v_mfma_f32_16x16x32_bf16 v[34:37], v[170:173], v[186:189], 0
	v_mfma_f32_16x16x32_bf16 v[34:37], v[174:177], v[190:193], v[34:37]
	v_mfma_f32_16x16x32_bf16 v[38:41], v[166:169], v[190:193], 0
	v_mfma_f32_16x16x32_bf16 v[38:41], v[162:165], v[186:189], v[38:41]
	v_mfma_f32_16x16x32_bf16 v[42:45], v[154:157], v[186:189], 0
	v_mfma_f32_16x16x32_bf16 v[42:45], v[158:161], v[190:193], v[42:45]
	v_mfma_f32_16x16x32_bf16 v[46:49], v[148:151], v[190:193], 0
	v_mfma_f32_16x16x32_bf16 v[46:49], v[144:147], v[186:189], v[46:49]
	v_mfma_f32_16x16x32_bf16 v[30:33], v[144:147], v[204:207], 0
	v_mfma_f32_16x16x32_bf16 v[30:33], v[148:151], v[208:211], v[30:33]
	v_mfma_f32_16x16x32_bf16 v[26:29], v[158:161], v[208:211], 0
	v_mfma_f32_16x16x32_bf16 v[26:29], v[154:157], v[204:207], v[26:29]
	v_mfma_f32_16x16x32_bf16 v[22:25], v[162:165], v[204:207], 0
	v_mfma_f32_16x16x32_bf16 v[22:25], v[166:169], v[208:211], v[22:25]
	v_mfma_f32_16x16x32_bf16 v[18:21], v[174:177], v[208:211], 0
	v_mfma_f32_16x16x32_bf16 v[18:21], v[170:173], v[204:207], v[18:21]
	v_mfma_f32_16x16x32_bf16 v[2:5], v[170:173], v[212:215], 0
	v_mfma_f32_16x16x32_bf16 v[2:5], v[174:177], v[216:219], v[2:5]
	v_mfma_f32_16x16x32_bf16 v[6:9], v[166:169], v[216:219], 0
	v_mfma_f32_16x16x32_bf16 v[6:9], v[162:165], v[212:215], v[6:9]
	v_mfma_f32_16x16x32_bf16 v[10:13], v[154:157], v[212:215], 0
	v_mfma_f32_16x16x32_bf16 v[10:13], v[158:161], v[216:219], v[10:13]
	v_mfma_f32_16x16x32_bf16 v[14:17], v[148:151], v[216:219], 0
	v_mfma_f32_16x16x32_bf16 v[14:17], v[144:147], v[212:215], v[14:17]
	s_barrier
	s_add_i32 s18, 0, 0x18000
	v_add_u32_e32 v153, s18, v1
	s_add_i32 s19, 0, 0x1c000
	ds_read_b128 v[144:147], v153
	ds_read_b128 v[148:151], v153 offset:1024
	ds_read_b128 v[154:157], v153 offset:2048
	ds_read_b128 v[158:161], v153 offset:3072
	v_add_u32_e32 v153, s19, v1
	ds_read_b128 v[162:165], v153
	ds_read_b128 v[166:169], v153 offset:1024
	ds_read_b128 v[170:173], v153 offset:2048
	ds_read_b128 v[174:177], v153 offset:3072
	s_add_u32 s0, s70, 0x80000
	s_addc_u32 s1, s71, 0
	s_mov_b32 m0, s33
	ds_read_b128 v[178:181], v152 offset:32768
	ds_read_b128 v[182:185], v152 offset:33792
	ds_read_b128 v[186:189], v152 offset:34816
	ds_read_b128 v[190:193], v152 offset:35840
	ds_read_b128 v[204:207], v152 offset:36864
	ds_read_b128 v[208:211], v152 offset:37888
	ds_read_b128 v[212:215], v152 offset:38912
	ds_read_b128 v[216:219], v152 offset:39936
	global_load_lds_dwordx4 v194, s[0:1]
	s_mov_b32 m0, s40
	s_nop 0
	global_load_lds_dwordx4 v130, s[0:1]
	s_waitcnt vmcnt(8)
	s_waitcnt lgkmcnt(0)
	s_barrier
	v_mfma_f32_16x16x32_bf16 v[126:129], v[144:147], v[178:181], v[126:129]
	v_mfma_f32_16x16x32_bf16 v[126:129], v[148:151], v[182:185], v[126:129]
	v_mfma_f32_16x16x32_bf16 v[122:125], v[158:161], v[182:185], v[122:125]
	v_mfma_f32_16x16x32_bf16 v[122:125], v[154:157], v[178:181], v[122:125]
	v_mfma_f32_16x16x32_bf16 v[118:121], v[162:165], v[178:181], v[118:121]
	v_mfma_f32_16x16x32_bf16 v[118:121], v[166:169], v[182:185], v[118:121]
	v_mfma_f32_16x16x32_bf16 v[114:117], v[174:177], v[182:185], v[114:117]
	v_mfma_f32_16x16x32_bf16 v[114:117], v[170:173], v[178:181], v[114:117]
	v_mfma_f32_16x16x32_bf16 v[98:101], v[170:173], v[186:189], v[98:101]
	v_mfma_f32_16x16x32_bf16 v[98:101], v[174:177], v[190:193], v[98:101]
	v_mfma_f32_16x16x32_bf16 v[102:105], v[166:169], v[190:193], v[102:105]
	v_mfma_f32_16x16x32_bf16 v[102:105], v[162:165], v[186:189], v[102:105]
	v_mfma_f32_16x16x32_bf16 v[106:109], v[154:157], v[186:189], v[106:109]
	v_mfma_f32_16x16x32_bf16 v[106:109], v[158:161], v[190:193], v[106:109]
	v_mfma_f32_16x16x32_bf16 v[110:113], v[148:151], v[190:193], v[110:113]
	v_mfma_f32_16x16x32_bf16 v[110:113], v[144:147], v[186:189], v[110:113]
	v_mfma_f32_16x16x32_bf16 v[94:97], v[144:147], v[204:207], v[94:97]
	v_mfma_f32_16x16x32_bf16 v[94:97], v[148:151], v[208:211], v[94:97]
	v_mfma_f32_16x16x32_bf16 v[90:93], v[158:161], v[208:211], v[90:93]
	v_mfma_f32_16x16x32_bf16 v[90:93], v[154:157], v[204:207], v[90:93]
	v_mfma_f32_16x16x32_bf16 v[86:89], v[162:165], v[204:207], v[86:89]
	v_mfma_f32_16x16x32_bf16 v[86:89], v[166:169], v[208:211], v[86:89]
	v_mfma_f32_16x16x32_bf16 v[82:85], v[174:177], v[208:211], v[82:85]
	v_mfma_f32_16x16x32_bf16 v[82:85], v[170:173], v[204:207], v[82:85]
	v_mfma_f32_16x16x32_bf16 v[66:69], v[170:173], v[212:215], v[66:69]
	v_mfma_f32_16x16x32_bf16 v[66:69], v[174:177], v[216:219], v[66:69]
	v_mfma_f32_16x16x32_bf16 v[70:73], v[166:169], v[216:219], v[70:73]
	v_mfma_f32_16x16x32_bf16 v[70:73], v[162:165], v[212:215], v[70:73]
	v_mfma_f32_16x16x32_bf16 v[74:77], v[154:157], v[212:215], v[74:77]
	v_mfma_f32_16x16x32_bf16 v[74:77], v[158:161], v[216:219], v[74:77]
	v_mfma_f32_16x16x32_bf16 v[78:81], v[148:151], v[216:219], v[78:81]
	v_mfma_f32_16x16x32_bf16 v[78:81], v[144:147], v[212:215], v[78:81]
	s_barrier
	s_add_u32 s98, s64, 0x80
	s_addc_u32 s99, s65, 0
	s_add_u32 s100, s70, 0x80
	s_addc_u32 s101, s71, 0
	s_add_i32 s0, s18, s28
	s_mov_b32 m0, s0
	ds_read_b128 v[178:181], v152 offset:49152
	ds_read_b128 v[182:185], v152 offset:50176
	ds_read_b128 v[186:189], v152 offset:51200
	ds_read_b128 v[190:193], v152 offset:52224
	ds_read_b128 v[204:207], v152 offset:53248
	ds_read_b128 v[208:211], v152 offset:54272
	ds_read_b128 v[212:215], v152 offset:55296
	ds_read_b128 v[216:219], v152 offset:56320
	global_load_lds_dwordx4 v194, s[98:99]
	s_add_i32 m0, s0, 0x2000
	s_add_u32 s0, s64, 0x80080
	s_addc_u32 s1, s65, 0
	s_add_i32 s18, s19, s28
	global_load_lds_dwordx4 v130, s[98:99]
	s_mov_b32 m0, s18
	s_nop 0
	global_load_lds_dwordx4 v194, s[0:1]
	s_add_i32 m0, s18, 0x2000
	s_nop 0
	global_load_lds_dwordx4 v130, s[0:1]
	s_mov_b32 m0, s54
	s_nop 0
	global_load_lds_dwordx4 v194, s[100:101]
	s_mov_b32 m0, s57
	s_nop 0
	global_load_lds_dwordx4 v130, s[100:101]
	s_waitcnt vmcnt(8)
	s_waitcnt lgkmcnt(0)
	s_barrier
	v_mfma_f32_16x16x32_bf16 v[62:65], v[144:147], v[178:181], v[62:65]
	v_mfma_f32_16x16x32_bf16 v[62:65], v[148:151], v[182:185], v[62:65]
	v_mfma_f32_16x16x32_bf16 v[58:61], v[158:161], v[182:185], v[58:61]
	v_mfma_f32_16x16x32_bf16 v[58:61], v[154:157], v[178:181], v[58:61]
	v_mfma_f32_16x16x32_bf16 v[54:57], v[162:165], v[178:181], v[54:57]
	v_mfma_f32_16x16x32_bf16 v[54:57], v[166:169], v[182:185], v[54:57]
	v_mfma_f32_16x16x32_bf16 v[50:53], v[174:177], v[182:185], v[50:53]
	v_mfma_f32_16x16x32_bf16 v[50:53], v[170:173], v[178:181], v[50:53]
	v_mfma_f32_16x16x32_bf16 v[34:37], v[170:173], v[186:189], v[34:37]
	v_mfma_f32_16x16x32_bf16 v[34:37], v[174:177], v[190:193], v[34:37]
	v_mfma_f32_16x16x32_bf16 v[38:41], v[166:169], v[190:193], v[38:41]
	v_mfma_f32_16x16x32_bf16 v[38:41], v[162:165], v[186:189], v[38:41]
	v_mfma_f32_16x16x32_bf16 v[42:45], v[154:157], v[186:189], v[42:45]
	v_mfma_f32_16x16x32_bf16 v[42:45], v[158:161], v[190:193], v[42:45]
	v_mfma_f32_16x16x32_bf16 v[46:49], v[148:151], v[190:193], v[46:49]
	v_mfma_f32_16x16x32_bf16 v[46:49], v[144:147], v[186:189], v[46:49]
	v_mfma_f32_16x16x32_bf16 v[30:33], v[144:147], v[204:207], v[30:33]
	v_mfma_f32_16x16x32_bf16 v[30:33], v[148:151], v[208:211], v[30:33]
	v_mfma_f32_16x16x32_bf16 v[26:29], v[158:161], v[208:211], v[26:29]
	v_mfma_f32_16x16x32_bf16 v[26:29], v[154:157], v[204:207], v[26:29]
	v_mfma_f32_16x16x32_bf16 v[22:25], v[162:165], v[204:207], v[22:25]
	v_mfma_f32_16x16x32_bf16 v[22:25], v[166:169], v[208:211], v[22:25]
	v_mfma_f32_16x16x32_bf16 v[18:21], v[174:177], v[208:211], v[18:21]
	v_mfma_f32_16x16x32_bf16 v[18:21], v[170:173], v[204:207], v[18:21]
	v_mfma_f32_16x16x32_bf16 v[2:5], v[170:173], v[212:215], v[2:5]
	v_mfma_f32_16x16x32_bf16 v[2:5], v[174:177], v[216:219], v[2:5]
	v_mfma_f32_16x16x32_bf16 v[6:9], v[166:169], v[216:219], v[6:9]
	v_mfma_f32_16x16x32_bf16 v[6:9], v[162:165], v[212:215], v[6:9]
	v_mfma_f32_16x16x32_bf16 v[10:13], v[154:157], v[212:215], v[10:13]
	v_mfma_f32_16x16x32_bf16 v[10:13], v[158:161], v[216:219], v[10:13]
	v_mfma_f32_16x16x32_bf16 v[14:17], v[148:151], v[216:219], v[14:17]
	v_mfma_f32_16x16x32_bf16 v[14:17], v[144:147], v[212:215], v[14:17]
	s_barrier
	s_add_i32 s76, s76, 2
	s_add_u32 s62, s62, 0x100
	s_addc_u32 s63, s63, 0
	s_add_u32 s53, s53, 0x100
	s_addc_u32 s58, s58, 0
	s_cmp_gt_u32 s76, 29
	s_cbranch_scc1 .LBB0_584
	s_branch .LBB0_582

.LBB0_645:
	s_add_u32 s64, s8, 0x100
	s_addc_u32 s65, s9, 0
	s_and_b64 s[0:1], s[70:71], exec
	s_cselect_b32 s77, s63, s65
	s_cselect_b32 s76, s62, s64
	s_cselect_b32 s71, s85, s23
	s_cselect_b32 s70, s84, s7
	s_add_i32 s0, 0, 0x10000
	s_add_i32 s18, 0, 0x14000
	v_add_u32_e32 v106, s0, v1
	v_add_u32_e32 v154, s18, v1
	ds_read_b128 v[70:73], v106
	ds_read_b128 v[82:85], v106 offset:1024
	ds_read_b128 v[94:97], v106 offset:2048
	ds_read_b128 v[106:109], v106 offset:3072
	ds_read_b128 v[118:121], v154
	ds_read_b128 v[130:133], v154 offset:1024
	ds_read_b128 v[142:145], v154 offset:2048
	ds_read_b128 v[154:157], v154 offset:3072
	s_add_i32 m0, s29, 0xc000
	ds_read_b128 v[158:161], v237
	ds_read_b128 v[170:173], v237 offset:1024
	ds_read_b128 v[174:177], v237 offset:2048
	ds_read_b128 v[178:181], v237 offset:3072
	ds_read_b128 v[182:185], v237 offset:4096
	ds_read_b128 v[186:189], v237 offset:5120
	ds_read_b128 v[210:213], v237 offset:6144
	ds_read_b128 v[214:217], v237 offset:7168
	global_load_lds_dwordx4 v206, s[8:9]
	s_add_i32 m0, s29, 0xe000
	s_nop 0
	global_load_lds_dwordx4 v208, s[8:9]
	s_waitcnt vmcnt(8)
	s_waitcnt lgkmcnt(0)
	s_barrier
	v_mfma_f32_16x16x32_bf16 v[166:169], v[70:73], v[158:161], v[166:169]
	v_mfma_f32_16x16x32_bf16 v[166:169], v[82:85], v[170:173], v[166:169]
	v_mfma_f32_16x16x32_bf16 v[162:165], v[106:109], v[170:173], v[162:165]
	v_mfma_f32_16x16x32_bf16 v[162:165], v[94:97], v[158:161], v[162:165]
	v_mfma_f32_16x16x32_bf16 v[150:153], v[118:121], v[158:161], v[150:153]
	v_mfma_f32_16x16x32_bf16 v[150:153], v[130:133], v[170:173], v[150:153]
	v_mfma_f32_16x16x32_bf16 v[146:149], v[154:157], v[170:173], v[146:149]
	v_mfma_f32_16x16x32_bf16 v[146:149], v[142:145], v[158:161], v[146:149]
	v_mfma_f32_16x16x32_bf16 v[122:125], v[142:145], v[174:177], v[122:125]
	v_mfma_f32_16x16x32_bf16 v[122:125], v[154:157], v[178:181], v[122:125]
	v_mfma_f32_16x16x32_bf16 v[126:129], v[130:133], v[178:181], v[126:129]
	v_mfma_f32_16x16x32_bf16 v[126:129], v[118:121], v[174:177], v[126:129]
	v_mfma_f32_16x16x32_bf16 v[134:137], v[94:97], v[174:177], v[134:137]
	v_mfma_f32_16x16x32_bf16 v[134:137], v[106:109], v[178:181], v[134:137]
	v_mfma_f32_16x16x32_bf16 v[138:141], v[82:85], v[178:181], v[138:141]
	v_mfma_f32_16x16x32_bf16 v[138:141], v[70:73], v[174:177], v[138:141]
	v_mfma_f32_16x16x32_bf16 v[114:117], v[70:73], v[182:185], v[114:117]
	v_mfma_f32_16x16x32_bf16 v[114:117], v[82:85], v[186:189], v[114:117]
	v_mfma_f32_16x16x32_bf16 v[110:113], v[106:109], v[186:189], v[110:113]
	v_mfma_f32_16x16x32_bf16 v[110:113], v[94:97], v[182:185], v[110:113]
	v_mfma_f32_16x16x32_bf16 v[102:105], v[118:121], v[182:185], v[102:105]
	v_mfma_f32_16x16x32_bf16 v[102:105], v[130:133], v[186:189], v[102:105]
	v_mfma_f32_16x16x32_bf16 v[98:101], v[154:157], v[186:189], v[98:101]
	v_mfma_f32_16x16x32_bf16 v[98:101], v[142:145], v[182:185], v[98:101]
	v_mfma_f32_16x16x32_bf16 v[74:77], v[142:145], v[210:213], v[74:77]
	v_mfma_f32_16x16x32_bf16 v[74:77], v[154:157], v[214:217], v[74:77]
	v_mfma_f32_16x16x32_bf16 v[78:81], v[130:133], v[214:217], v[78:81]
	v_mfma_f32_16x16x32_bf16 v[78:81], v[118:121], v[210:213], v[78:81]
	v_mfma_f32_16x16x32_bf16 v[86:89], v[94:97], v[210:213], v[86:89]
	v_mfma_f32_16x16x32_bf16 v[86:89], v[106:109], v[214:217], v[86:89]
	v_mfma_f32_16x16x32_bf16 v[90:93], v[82:85], v[214:217], v[90:93]
	v_mfma_f32_16x16x32_bf16 v[90:93], v[70:73], v[210:213], v[90:93]
	s_barrier
	s_add_i32 s0, s0, s28
	s_mov_b32 m0, s0
	ds_read_b128 v[158:161], v237 offset:16384
	ds_read_b128 v[170:173], v237 offset:17408
	ds_read_b128 v[174:177], v237 offset:18432
	ds_read_b128 v[178:181], v237 offset:19456
	ds_read_b128 v[182:185], v237 offset:20480
	ds_read_b128 v[186:189], v237 offset:21504
	ds_read_b128 v[210:213], v237 offset:22528
	ds_read_b128 v[214:217], v237 offset:23552
	global_load_lds_dwordx4 v192, s[70:71]
	s_add_i32 m0, s0, 0x2000
	s_add_u32 s0, s70, 0x160000
	s_addc_u32 s1, s71, 0
	s_add_i32 s8, s18, s28
	global_load_lds_dwordx4 v190, s[70:71]
	s_mov_b32 m0, s8
	s_nop 0
	global_load_lds_dwordx4 v192, s[0:1]
	s_add_i32 m0, s8, 0x2000
	s_nop 0
	global_load_lds_dwordx4 v190, s[0:1]
	s_mov_b32 m0, s29
	s_nop 0
	global_load_lds_dwordx4 v192, s[76:77]
	s_mov_b32 m0, s31
	s_nop 0
	global_load_lds_dwordx4 v190, s[76:77]
	s_waitcnt vmcnt(8)
	s_waitcnt lgkmcnt(0)
	s_barrier
	v_mfma_f32_16x16x32_bf16 v[62:65], v[70:73], v[158:161], v[62:65]
	v_mfma_f32_16x16x32_bf16 v[62:65], v[82:85], v[170:173], v[62:65]
	v_mfma_f32_16x16x32_bf16 v[58:61], v[106:109], v[170:173], v[58:61]
	v_mfma_f32_16x16x32_bf16 v[58:61], v[94:97], v[158:161], v[58:61]
	v_mfma_f32_16x16x32_bf16 v[54:57], v[118:121], v[158:161], v[54:57]
	v_mfma_f32_16x16x32_bf16 v[54:57], v[130:133], v[170:173], v[54:57]
	v_mfma_f32_16x16x32_bf16 v[50:53], v[154:157], v[170:173], v[50:53]
	v_mfma_f32_16x16x32_bf16 v[50:53], v[142:145], v[158:161], v[50:53]
	v_mfma_f32_16x16x32_bf16 v[34:37], v[142:145], v[174:177], v[34:37]
	v_mfma_f32_16x16x32_bf16 v[34:37], v[154:157], v[178:181], v[34:37]
	v_mfma_f32_16x16x32_bf16 v[38:41], v[130:133], v[178:181], v[38:41]
	v_mfma_f32_16x16x32_bf16 v[38:41], v[118:121], v[174:177], v[38:41]
	v_mfma_f32_16x16x32_bf16 v[42:45], v[94:97], v[174:177], v[42:45]
	v_mfma_f32_16x16x32_bf16 v[42:45], v[106:109], v[178:181], v[42:45]
	v_mfma_f32_16x16x32_bf16 v[46:49], v[82:85], v[178:181], v[46:49]
	v_mfma_f32_16x16x32_bf16 v[46:49], v[70:73], v[174:177], v[46:49]
	v_mfma_f32_16x16x32_bf16 v[30:33], v[70:73], v[182:185], v[30:33]
	v_mfma_f32_16x16x32_bf16 v[30:33], v[82:85], v[186:189], v[30:33]
	v_mfma_f32_16x16x32_bf16 v[26:29], v[106:109], v[186:189], v[26:29]
	v_mfma_f32_16x16x32_bf16 v[26:29], v[94:97], v[182:185], v[26:29]
	v_mfma_f32_16x16x32_bf16 v[22:25], v[118:121], v[182:185], v[22:25]
	v_mfma_f32_16x16x32_bf16 v[22:25], v[130:133], v[186:189], v[22:25]
	v_mfma_f32_16x16x32_bf16 v[18:21], v[154:157], v[186:189], v[18:21]
	v_mfma_f32_16x16x32_bf16 v[18:21], v[142:145], v[182:185], v[18:21]
	v_mfma_f32_16x16x32_bf16 v[2:5], v[142:145], v[210:213], v[2:5]
	v_mfma_f32_16x16x32_bf16 v[2:5], v[154:157], v[214:217], v[2:5]
	v_mfma_f32_16x16x32_bf16 v[6:9], v[130:133], v[214:217], v[6:9]
	v_mfma_f32_16x16x32_bf16 v[6:9], v[118:121], v[210:213], v[6:9]
	v_mfma_f32_16x16x32_bf16 v[10:13], v[94:97], v[210:213], v[10:13]
	v_mfma_f32_16x16x32_bf16 v[10:13], v[106:109], v[214:217], v[10:13]
	v_mfma_f32_16x16x32_bf16 v[14:17], v[82:85], v[214:217], v[14:17]
	v_mfma_f32_16x16x32_bf16 v[14:17], v[70:73], v[210:213], v[14:17]
	s_barrier
	s_add_i32 s8, 0, 0x18000
	s_add_i32 s9, 0, 0x1c000
	v_add_u32_e32 v106, s8, v1
	v_add_u32_e32 v154, s9, v1
	ds_read_b128 v[70:73], v106
	ds_read_b128 v[82:85], v106 offset:1024
	ds_read_b128 v[94:97], v106 offset:2048
	ds_read_b128 v[106:109], v106 offset:3072
	ds_read_b128 v[118:121], v154
	ds_read_b128 v[130:133], v154 offset:1024
	ds_read_b128 v[142:145], v154 offset:2048
	ds_read_b128 v[154:157], v154 offset:3072
	s_add_u32 s0, s76, 0x160000
	s_addc_u32 s1, s77, 0
	s_mov_b32 m0, s33
	ds_read_b128 v[158:161], v237 offset:32768
	ds_read_b128 v[170:173], v237 offset:33792
	ds_read_b128 v[174:177], v237 offset:34816
	ds_read_b128 v[178:181], v237 offset:35840
	ds_read_b128 v[182:185], v237 offset:36864
	ds_read_b128 v[186:189], v237 offset:37888
	ds_read_b128 v[210:213], v237 offset:38912
	ds_read_b128 v[214:217], v237 offset:39936
	global_load_lds_dwordx4 v192, s[0:1]
	s_mov_b32 m0, s43
	s_nop 0
	global_load_lds_dwordx4 v190, s[0:1]
	s_waitcnt vmcnt(8)
	s_waitcnt lgkmcnt(0)
	s_barrier
	v_mfma_f32_16x16x32_bf16 v[166:169], v[70:73], v[158:161], v[166:169]
	v_mfma_f32_16x16x32_bf16 v[166:169], v[82:85], v[170:173], v[166:169]
	v_mfma_f32_16x16x32_bf16 v[162:165], v[106:109], v[170:173], v[162:165]
	v_mfma_f32_16x16x32_bf16 v[162:165], v[94:97], v[158:161], v[162:165]
	v_mfma_f32_16x16x32_bf16 v[150:153], v[118:121], v[158:161], v[150:153]
	v_mfma_f32_16x16x32_bf16 v[150:153], v[130:133], v[170:173], v[150:153]
	v_mfma_f32_16x16x32_bf16 v[146:149], v[154:157], v[170:173], v[146:149]
	v_mfma_f32_16x16x32_bf16 v[146:149], v[142:145], v[158:161], v[146:149]
	v_mfma_f32_16x16x32_bf16 v[122:125], v[142:145], v[174:177], v[122:125]
	v_mfma_f32_16x16x32_bf16 v[122:125], v[154:157], v[178:181], v[122:125]
	v_mfma_f32_16x16x32_bf16 v[126:129], v[130:133], v[178:181], v[126:129]
	v_mfma_f32_16x16x32_bf16 v[126:129], v[118:121], v[174:177], v[126:129]
	v_mfma_f32_16x16x32_bf16 v[134:137], v[94:97], v[174:177], v[134:137]
	v_mfma_f32_16x16x32_bf16 v[134:137], v[106:109], v[178:181], v[134:137]
	v_mfma_f32_16x16x32_bf16 v[138:141], v[82:85], v[178:181], v[138:141]
	v_mfma_f32_16x16x32_bf16 v[138:141], v[70:73], v[174:177], v[138:141]
	v_mfma_f32_16x16x32_bf16 v[114:117], v[70:73], v[182:185], v[114:117]
	v_mfma_f32_16x16x32_bf16 v[114:117], v[82:85], v[186:189], v[114:117]
	v_mfma_f32_16x16x32_bf16 v[110:113], v[106:109], v[186:189], v[110:113]
	v_mfma_f32_16x16x32_bf16 v[110:113], v[94:97], v[182:185], v[110:113]
	v_mfma_f32_16x16x32_bf16 v[102:105], v[118:121], v[182:185], v[102:105]
	v_mfma_f32_16x16x32_bf16 v[102:105], v[130:133], v[186:189], v[102:105]
	v_mfma_f32_16x16x32_bf16 v[98:101], v[154:157], v[186:189], v[98:101]
	v_mfma_f32_16x16x32_bf16 v[98:101], v[142:145], v[182:185], v[98:101]
	v_mfma_f32_16x16x32_bf16 v[74:77], v[142:145], v[210:213], v[74:77]
	v_mfma_f32_16x16x32_bf16 v[74:77], v[154:157], v[214:217], v[74:77]
	v_mfma_f32_16x16x32_bf16 v[78:81], v[130:133], v[214:217], v[78:81]
	v_mfma_f32_16x16x32_bf16 v[78:81], v[118:121], v[210:213], v[78:81]
	v_mfma_f32_16x16x32_bf16 v[86:89], v[94:97], v[210:213], v[86:89]
	v_mfma_f32_16x16x32_bf16 v[86:89], v[106:109], v[214:217], v[86:89]
	v_mfma_f32_16x16x32_bf16 v[90:93], v[82:85], v[214:217], v[90:93]
	v_mfma_f32_16x16x32_bf16 v[90:93], v[70:73], v[210:213], v[90:93]
	s_barrier
	s_add_u32 s98, s70, 0x80
	s_addc_u32 s99, s71, 0
	s_add_u32 s100, s76, 0x80
	s_addc_u32 s101, s77, 0
	s_add_i32 s0, s8, s28
	s_mov_b32 m0, s0
	ds_read_b128 v[158:161], v237 offset:49152
	ds_read_b128 v[170:173], v237 offset:50176
	ds_read_b128 v[174:177], v237 offset:51200
	ds_read_b128 v[178:181], v237 offset:52224
	ds_read_b128 v[182:185], v237 offset:53248
	ds_read_b128 v[186:189], v237 offset:54272
	ds_read_b128 v[210:213], v237 offset:55296
	ds_read_b128 v[214:217], v237 offset:56320
	global_load_lds_dwordx4 v192, s[98:99]
	s_add_i32 m0, s0, 0x2000
	s_add_u32 s0, s70, 0x160080
	s_addc_u32 s1, s71, 0
	s_add_i32 s8, s9, s28
	global_load_lds_dwordx4 v190, s[98:99]
	s_mov_b32 m0, s8
	s_nop 0
	global_load_lds_dwordx4 v192, s[0:1]
	s_add_i32 m0, s8, 0x2000
	s_nop 0
	global_load_lds_dwordx4 v190, s[0:1]
	s_mov_b32 m0, s68
	s_nop 0
	global_load_lds_dwordx4 v192, s[100:101]
	s_mov_b32 m0, s79
	s_nop 0
	global_load_lds_dwordx4 v190, s[100:101]
	s_waitcnt vmcnt(8)
	s_waitcnt lgkmcnt(0)
	s_barrier
	v_mfma_f32_16x16x32_bf16 v[62:65], v[70:73], v[158:161], v[62:65]
	v_mfma_f32_16x16x32_bf16 v[62:65], v[82:85], v[170:173], v[62:65]
	v_mfma_f32_16x16x32_bf16 v[58:61], v[106:109], v[170:173], v[58:61]
	v_mfma_f32_16x16x32_bf16 v[58:61], v[94:97], v[158:161], v[58:61]
	v_mfma_f32_16x16x32_bf16 v[54:57], v[118:121], v[158:161], v[54:57]
	v_mfma_f32_16x16x32_bf16 v[54:57], v[130:133], v[170:173], v[54:57]
	v_mfma_f32_16x16x32_bf16 v[50:53], v[154:157], v[170:173], v[50:53]
	v_mfma_f32_16x16x32_bf16 v[50:53], v[142:145], v[158:161], v[50:53]
	v_mfma_f32_16x16x32_bf16 v[34:37], v[142:145], v[174:177], v[34:37]
	v_mfma_f32_16x16x32_bf16 v[34:37], v[154:157], v[178:181], v[34:37]
	v_mfma_f32_16x16x32_bf16 v[38:41], v[130:133], v[178:181], v[38:41]
	v_mfma_f32_16x16x32_bf16 v[38:41], v[118:121], v[174:177], v[38:41]
	v_mfma_f32_16x16x32_bf16 v[42:45], v[94:97], v[174:177], v[42:45]
	v_mfma_f32_16x16x32_bf16 v[42:45], v[106:109], v[178:181], v[42:45]
	v_mfma_f32_16x16x32_bf16 v[46:49], v[82:85], v[178:181], v[46:49]
	v_mfma_f32_16x16x32_bf16 v[46:49], v[70:73], v[174:177], v[46:49]
	v_mfma_f32_16x16x32_bf16 v[30:33], v[70:73], v[182:185], v[30:33]
	v_mfma_f32_16x16x32_bf16 v[30:33], v[82:85], v[186:189], v[30:33]
	v_mfma_f32_16x16x32_bf16 v[26:29], v[106:109], v[186:189], v[26:29]
	v_mfma_f32_16x16x32_bf16 v[26:29], v[94:97], v[182:185], v[26:29]
	v_mfma_f32_16x16x32_bf16 v[22:25], v[118:121], v[182:185], v[22:25]
	v_mfma_f32_16x16x32_bf16 v[22:25], v[130:133], v[186:189], v[22:25]
	v_mfma_f32_16x16x32_bf16 v[18:21], v[154:157], v[186:189], v[18:21]
	v_mfma_f32_16x16x32_bf16 v[18:21], v[142:145], v[182:185], v[18:21]
	v_mfma_f32_16x16x32_bf16 v[2:5], v[142:145], v[210:213], v[2:5]
	v_mfma_f32_16x16x32_bf16 v[2:5], v[154:157], v[214:217], v[2:5]
	v_mfma_f32_16x16x32_bf16 v[6:9], v[130:133], v[214:217], v[6:9]
	v_mfma_f32_16x16x32_bf16 v[6:9], v[118:121], v[210:213], v[6:9]
	v_mfma_f32_16x16x32_bf16 v[10:13], v[94:97], v[210:213], v[10:13]
	v_mfma_f32_16x16x32_bf16 v[10:13], v[106:109], v[214:217], v[10:13]
	v_mfma_f32_16x16x32_bf16 v[14:17], v[82:85], v[214:217], v[14:17]
	v_mfma_f32_16x16x32_bf16 v[14:17], v[70:73], v[210:213], v[14:17]
	s_barrier
	s_add_i32 s41, s41, 2
	s_add_u32 s7, s7, 0x100
	s_addc_u32 s23, s23, 0
	s_cmpk_gt_u32 s41, 0x55
	s_mov_b64 s[8:9], s[64:65]
	s_cbranch_scc1 .LBB0_648

.Lpeel_disp_down:
	s_cmp_lg_u32 s41, -2
	s_cbranch_scc1 .LBB0_645
	s_add_u32 s64, s8, 0x100
	s_addc_u32 s65, s9, 0
	s_and_b64 s[0:1], s[70:71], exec
	s_cselect_b32 s77, s63, s65
	s_cselect_b32 s76, s62, s64
	s_cselect_b32 s71, s85, s23
	s_cselect_b32 s70, s84, s7
	s_add_i32 s0, 0, 0x10000
	s_add_i32 s18, 0, 0x14000
	v_add_u32_e32 v106, s0, v1
	v_add_u32_e32 v154, s18, v1
	ds_read_b128 v[70:73], v106
	ds_read_b128 v[82:85], v106 offset:1024
	ds_read_b128 v[94:97], v106 offset:2048
	ds_read_b128 v[106:109], v106 offset:3072
	ds_read_b128 v[118:121], v154
	ds_read_b128 v[130:133], v154 offset:1024
	ds_read_b128 v[142:145], v154 offset:2048
	ds_read_b128 v[154:157], v154 offset:3072
	s_add_i32 m0, s29, 0xc000
	ds_read_b128 v[158:161], v237
	ds_read_b128 v[170:173], v237 offset:1024
	ds_read_b128 v[174:177], v237 offset:2048
	ds_read_b128 v[178:181], v237 offset:3072
	ds_read_b128 v[182:185], v237 offset:4096
	ds_read_b128 v[186:189], v237 offset:5120
	ds_read_b128 v[210:213], v237 offset:6144
	ds_read_b128 v[214:217], v237 offset:7168
	global_load_lds_dwordx4 v206, s[8:9]
	s_add_i32 m0, s29, 0xe000
	s_nop 0
	global_load_lds_dwordx4 v208, s[8:9]
	s_waitcnt vmcnt(8)
	s_waitcnt lgkmcnt(0)
	s_barrier
	v_mfma_f32_16x16x32_bf16 v[166:169], v[70:73], v[158:161], 0
	v_mfma_f32_16x16x32_bf16 v[166:169], v[82:85], v[170:173], v[166:169]
	v_mfma_f32_16x16x32_bf16 v[162:165], v[106:109], v[170:173], 0
	v_mfma_f32_16x16x32_bf16 v[162:165], v[94:97], v[158:161], v[162:165]
	v_mfma_f32_16x16x32_bf16 v[150:153], v[118:121], v[158:161], 0
	v_mfma_f32_16x16x32_bf16 v[150:153], v[130:133], v[170:173], v[150:153]
	v_mfma_f32_16x16x32_bf16 v[146:149], v[154:157], v[170:173], 0
	v_mfma_f32_16x16x32_bf16 v[146:149], v[142:145], v[158:161], v[146:149]
	v_mfma_f32_16x16x32_bf16 v[122:125], v[142:145], v[174:177], 0
	v_mfma_f32_16x16x32_bf16 v[122:125], v[154:157], v[178:181], v[122:125]
	v_mfma_f32_16x16x32_bf16 v[126:129], v[130:133], v[178:181], 0
	v_mfma_f32_16x16x32_bf16 v[126:129], v[118:121], v[174:177], v[126:129]
	v_mfma_f32_16x16x32_bf16 v[134:137], v[94:97], v[174:177], 0
	v_mfma_f32_16x16x32_bf16 v[134:137], v[106:109], v[178:181], v[134:137]
	v_mfma_f32_16x16x32_bf16 v[138:141], v[82:85], v[178:181], 0
	v_mfma_f32_16x16x32_bf16 v[138:141], v[70:73], v[174:177], v[138:141]
	v_mfma_f32_16x16x32_bf16 v[114:117], v[70:73], v[182:185], 0
	v_mfma_f32_16x16x32_bf16 v[114:117], v[82:85], v[186:189], v[114:117]
	v_mfma_f32_16x16x32_bf16 v[110:113], v[106:109], v[186:189], 0
	v_mfma_f32_16x16x32_bf16 v[110:113], v[94:97], v[182:185], v[110:113]
	v_mfma_f32_16x16x32_bf16 v[102:105], v[118:121], v[182:185], 0
	v_mfma_f32_16x16x32_bf16 v[102:105], v[130:133], v[186:189], v[102:105]
	v_mfma_f32_16x16x32_bf16 v[98:101], v[154:157], v[186:189], 0
	v_mfma_f32_16x16x32_bf16 v[98:101], v[142:145], v[182:185], v[98:101]
	v_mfma_f32_16x16x32_bf16 v[74:77], v[142:145], v[210:213], 0
	v_mfma_f32_16x16x32_bf16 v[74:77], v[154:157], v[214:217], v[74:77]
	v_mfma_f32_16x16x32_bf16 v[78:81], v[130:133], v[214:217], 0
	v_mfma_f32_16x16x32_bf16 v[78:81], v[118:121], v[210:213], v[78:81]
	v_mfma_f32_16x16x32_bf16 v[86:89], v[94:97], v[210:213], 0
	v_mfma_f32_16x16x32_bf16 v[86:89], v[106:109], v[214:217], v[86:89]
	v_mfma_f32_16x16x32_bf16 v[90:93], v[82:85], v[214:217], 0
	v_mfma_f32_16x16x32_bf16 v[90:93], v[70:73], v[210:213], v[90:93]
	s_barrier
	s_add_i32 s0, s0, s28
	s_mov_b32 m0, s0
	ds_read_b128 v[158:161], v237 offset:16384
	ds_read_b128 v[170:173], v237 offset:17408
	ds_read_b128 v[174:177], v237 offset:18432
	ds_read_b128 v[178:181], v237 offset:19456
	ds_read_b128 v[182:185], v237 offset:20480
	ds_read_b128 v[186:189], v237 offset:21504
	ds_read_b128 v[210:213], v237 offset:22528
	ds_read_b128 v[214:217], v237 offset:23552
	global_load_lds_dwordx4 v192, s[70:71]
	s_add_i32 m0, s0, 0x2000
	s_add_u32 s0, s70, 0x160000
	s_addc_u32 s1, s71, 0
	s_add_i32 s8, s18, s28
	global_load_lds_dwordx4 v190, s[70:71]
	s_mov_b32 m0, s8
	s_nop 0
	global_load_lds_dwordx4 v192, s[0:1]
	s_add_i32 m0, s8, 0x2000
	s_nop 0
	global_load_lds_dwordx4 v190, s[0:1]
	s_mov_b32 m0, s29
	s_nop 0
	global_load_lds_dwordx4 v192, s[76:77]
	s_mov_b32 m0, s31
	s_nop 0
	global_load_lds_dwordx4 v190, s[76:77]
	s_waitcnt vmcnt(8)
	s_waitcnt lgkmcnt(0)
	s_barrier
	v_mfma_f32_16x16x32_bf16 v[62:65], v[70:73], v[158:161], 0
	v_mfma_f32_16x16x32_bf16 v[62:65], v[82:85], v[170:173], v[62:65]
	v_mfma_f32_16x16x32_bf16 v[58:61], v[106:109], v[170:173], 0
	v_mfma_f32_16x16x32_bf16 v[58:61], v[94:97], v[158:161], v[58:61]
	v_mfma_f32_16x16x32_bf16 v[54:57], v[118:121], v[158:161], 0
	v_mfma_f32_16x16x32_bf16 v[54:57], v[130:133], v[170:173], v[54:57]
	v_mfma_f32_16x16x32_bf16 v[50:53], v[154:157], v[170:173], 0
	v_mfma_f32_16x16x32_bf16 v[50:53], v[142:145], v[158:161], v[50:53]
	v_mfma_f32_16x16x32_bf16 v[34:37], v[142:145], v[174:177], 0
	v_mfma_f32_16x16x32_bf16 v[34:37], v[154:157], v[178:181], v[34:37]
	v_mfma_f32_16x16x32_bf16 v[38:41], v[130:133], v[178:181], 0
	v_mfma_f32_16x16x32_bf16 v[38:41], v[118:121], v[174:177], v[38:41]
	v_mfma_f32_16x16x32_bf16 v[42:45], v[94:97], v[174:177], 0
	v_mfma_f32_16x16x32_bf16 v[42:45], v[106:109], v[178:181], v[42:45]
	v_mfma_f32_16x16x32_bf16 v[46:49], v[82:85], v[178:181], 0
	v_mfma_f32_16x16x32_bf16 v[46:49], v[70:73], v[174:177], v[46:49]
	v_mfma_f32_16x16x32_bf16 v[30:33], v[70:73], v[182:185], 0
	v_mfma_f32_16x16x32_bf16 v[30:33], v[82:85], v[186:189], v[30:33]
	v_mfma_f32_16x16x32_bf16 v[26:29], v[106:109], v[186:189], 0
	v_mfma_f32_16x16x32_bf16 v[26:29], v[94:97], v[182:185], v[26:29]
	v_mfma_f32_16x16x32_bf16 v[22:25], v[118:121], v[182:185], 0
	v_mfma_f32_16x16x32_bf16 v[22:25], v[130:133], v[186:189], v[22:25]
	v_mfma_f32_16x16x32_bf16 v[18:21], v[154:157], v[186:189], 0
	v_mfma_f32_16x16x32_bf16 v[18:21], v[142:145], v[182:185], v[18:21]
	v_mfma_f32_16x16x32_bf16 v[2:5], v[142:145], v[210:213], 0
	v_mfma_f32_16x16x32_bf16 v[2:5], v[154:157], v[214:217], v[2:5]
	v_mfma_f32_16x16x32_bf16 v[6:9], v[130:133], v[214:217], 0
	v_mfma_f32_16x16x32_bf16 v[6:9], v[118:121], v[210:213], v[6:9]
	v_mfma_f32_16x16x32_bf16 v[10:13], v[94:97], v[210:213], 0
	v_mfma_f32_16x16x32_bf16 v[10:13], v[106:109], v[214:217], v[10:13]
	v_mfma_f32_16x16x32_bf16 v[14:17], v[82:85], v[214:217], 0
	v_mfma_f32_16x16x32_bf16 v[14:17], v[70:73], v[210:213], v[14:17]
	s_barrier
	s_add_i32 s8, 0, 0x18000
	s_add_i32 s9, 0, 0x1c000
	v_add_u32_e32 v106, s8, v1
	v_add_u32_e32 v154, s9, v1
	ds_read_b128 v[70:73], v106
	ds_read_b128 v[82:85], v106 offset:1024
	ds_read_b128 v[94:97], v106 offset:2048
	ds_read_b128 v[106:109], v106 offset:3072
	ds_read_b128 v[118:121], v154
	ds_read_b128 v[130:133], v154 offset:1024
	ds_read_b128 v[142:145], v154 offset:2048
	ds_read_b128 v[154:157], v154 offset:3072
	s_add_u32 s0, s76, 0x160000
	s_addc_u32 s1, s77, 0
	s_mov_b32 m0, s33
	ds_read_b128 v[158:161], v237 offset:32768
	ds_read_b128 v[170:173], v237 offset:33792
	ds_read_b128 v[174:177], v237 offset:34816
	ds_read_b128 v[178:181], v237 offset:35840
	ds_read_b128 v[182:185], v237 offset:36864
	ds_read_b128 v[186:189], v237 offset:37888
	ds_read_b128 v[210:213], v237 offset:38912
	ds_read_b128 v[214:217], v237 offset:39936
	global_load_lds_dwordx4 v192, s[0:1]
	s_mov_b32 m0, s43
	s_nop 0
	global_load_lds_dwordx4 v190, s[0:1]
	s_waitcnt vmcnt(8)
	s_waitcnt lgkmcnt(0)
	s_barrier
	v_mfma_f32_16x16x32_bf16 v[166:169], v[70:73], v[158:161], v[166:169]
	v_mfma_f32_16x16x32_bf16 v[166:169], v[82:85], v[170:173], v[166:169]
	v_mfma_f32_16x16x32_bf16 v[162:165], v[106:109], v[170:173], v[162:165]
	v_mfma_f32_16x16x32_bf16 v[162:165], v[94:97], v[158:161], v[162:165]
	v_mfma_f32_16x16x32_bf16 v[150:153], v[118:121], v[158:161], v[150:153]
	v_mfma_f32_16x16x32_bf16 v[150:153], v[130:133], v[170:173], v[150:153]
	v_mfma_f32_16x16x32_bf16 v[146:149], v[154:157], v[170:173], v[146:149]
	v_mfma_f32_16x16x32_bf16 v[146:149], v[142:145], v[158:161], v[146:149]
	v_mfma_f32_16x16x32_bf16 v[122:125], v[142:145], v[174:177], v[122:125]
	v_mfma_f32_16x16x32_bf16 v[122:125], v[154:157], v[178:181], v[122:125]
	v_mfma_f32_16x16x32_bf16 v[126:129], v[130:133], v[178:181], v[126:129]
	v_mfma_f32_16x16x32_bf16 v[126:129], v[118:121], v[174:177], v[126:129]
	v_mfma_f32_16x16x32_bf16 v[134:137], v[94:97], v[174:177], v[134:137]
	v_mfma_f32_16x16x32_bf16 v[134:137], v[106:109], v[178:181], v[134:137]
	v_mfma_f32_16x16x32_bf16 v[138:141], v[82:85], v[178:181], v[138:141]
	v_mfma_f32_16x16x32_bf16 v[138:141], v[70:73], v[174:177], v[138:141]
	v_mfma_f32_16x16x32_bf16 v[114:117], v[70:73], v[182:185], v[114:117]
	v_mfma_f32_16x16x32_bf16 v[114:117], v[82:85], v[186:189], v[114:117]
	v_mfma_f32_16x16x32_bf16 v[110:113], v[106:109], v[186:189], v[110:113]
	v_mfma_f32_16x16x32_bf16 v[110:113], v[94:97], v[182:185], v[110:113]
	v_mfma_f32_16x16x32_bf16 v[102:105], v[118:121], v[182:185], v[102:105]
	v_mfma_f32_16x16x32_bf16 v[102:105], v[130:133], v[186:189], v[102:105]
	v_mfma_f32_16x16x32_bf16 v[98:101], v[154:157], v[186:189], v[98:101]
	v_mfma_f32_16x16x32_bf16 v[98:101], v[142:145], v[182:185], v[98:101]
	v_mfma_f32_16x16x32_bf16 v[74:77], v[142:145], v[210:213], v[74:77]
	v_mfma_f32_16x16x32_bf16 v[74:77], v[154:157], v[214:217], v[74:77]
	v_mfma_f32_16x16x32_bf16 v[78:81], v[130:133], v[214:217], v[78:81]
	v_mfma_f32_16x16x32_bf16 v[78:81], v[118:121], v[210:213], v[78:81]
	v_mfma_f32_16x16x32_bf16 v[86:89], v[94:97], v[210:213], v[86:89]
	v_mfma_f32_16x16x32_bf16 v[86:89], v[106:109], v[214:217], v[86:89]
	v_mfma_f32_16x16x32_bf16 v[90:93], v[82:85], v[214:217], v[90:93]
	v_mfma_f32_16x16x32_bf16 v[90:93], v[70:73], v[210:213], v[90:93]
	s_barrier
	s_add_u32 s98, s70, 0x80
	s_addc_u32 s99, s71, 0
	s_add_u32 s100, s76, 0x80
	s_addc_u32 s101, s77, 0
	s_add_i32 s0, s8, s28
	s_mov_b32 m0, s0
	ds_read_b128 v[158:161], v237 offset:49152
	ds_read_b128 v[170:173], v237 offset:50176
	ds_read_b128 v[174:177], v237 offset:51200
	ds_read_b128 v[178:181], v237 offset:52224
	ds_read_b128 v[182:185], v237 offset:53248
	ds_read_b128 v[186:189], v237 offset:54272
	ds_read_b128 v[210:213], v237 offset:55296
	ds_read_b128 v[214:217], v237 offset:56320
	global_load_lds_dwordx4 v192, s[98:99]
	s_add_i32 m0, s0, 0x2000
	s_add_u32 s0, s70, 0x160080
	s_addc_u32 s1, s71, 0
	s_add_i32 s8, s9, s28
	global_load_lds_dwordx4 v190, s[98:99]
	s_mov_b32 m0, s8
	s_nop 0
	global_load_lds_dwordx4 v192, s[0:1]
	s_add_i32 m0, s8, 0x2000
	s_nop 0
	global_load_lds_dwordx4 v190, s[0:1]
	s_mov_b32 m0, s68
	s_nop 0
	global_load_lds_dwordx4 v192, s[100:101]
	s_mov_b32 m0, s79
	s_nop 0
	global_load_lds_dwordx4 v190, s[100:101]
	s_waitcnt vmcnt(8)
	s_waitcnt lgkmcnt(0)
	s_barrier
	v_mfma_f32_16x16x32_bf16 v[62:65], v[70:73], v[158:161], v[62:65]
	v_mfma_f32_16x16x32_bf16 v[62:65], v[82:85], v[170:173], v[62:65]
	v_mfma_f32_16x16x32_bf16 v[58:61], v[106:109], v[170:173], v[58:61]
	v_mfma_f32_16x16x32_bf16 v[58:61], v[94:97], v[158:161], v[58:61]
	v_mfma_f32_16x16x32_bf16 v[54:57], v[118:121], v[158:161], v[54:57]
	v_mfma_f32_16x16x32_bf16 v[54:57], v[130:133], v[170:173], v[54:57]
	v_mfma_f32_16x16x32_bf16 v[50:53], v[154:157], v[170:173], v[50:53]
	v_mfma_f32_16x16x32_bf16 v[50:53], v[142:145], v[158:161], v[50:53]
	v_mfma_f32_16x16x32_bf16 v[34:37], v[142:145], v[174:177], v[34:37]
	v_mfma_f32_16x16x32_bf16 v[34:37], v[154:157], v[178:181], v[34:37]
	v_mfma_f32_16x16x32_bf16 v[38:41], v[130:133], v[178:181], v[38:41]
	v_mfma_f32_16x16x32_bf16 v[38:41], v[118:121], v[174:177], v[38:41]
	v_mfma_f32_16x16x32_bf16 v[42:45], v[94:97], v[174:177], v[42:45]
	v_mfma_f32_16x16x32_bf16 v[42:45], v[106:109], v[178:181], v[42:45]
	v_mfma_f32_16x16x32_bf16 v[46:49], v[82:85], v[178:181], v[46:49]
	v_mfma_f32_16x16x32_bf16 v[46:49], v[70:73], v[174:177], v[46:49]
	v_mfma_f32_16x16x32_bf16 v[30:33], v[70:73], v[182:185], v[30:33]
	v_mfma_f32_16x16x32_bf16 v[30:33], v[82:85], v[186:189], v[30:33]
	v_mfma_f32_16x16x32_bf16 v[26:29], v[106:109], v[186:189], v[26:29]
	v_mfma_f32_16x16x32_bf16 v[26:29], v[94:97], v[182:185], v[26:29]
	v_mfma_f32_16x16x32_bf16 v[22:25], v[118:121], v[182:185], v[22:25]
	v_mfma_f32_16x16x32_bf16 v[22:25], v[130:133], v[186:189], v[22:25]
	v_mfma_f32_16x16x32_bf16 v[18:21], v[154:157], v[186:189], v[18:21]
	v_mfma_f32_16x16x32_bf16 v[18:21], v[142:145], v[182:185], v[18:21]
	v_mfma_f32_16x16x32_bf16 v[2:5], v[142:145], v[210:213], v[2:5]
	v_mfma_f32_16x16x32_bf16 v[2:5], v[154:157], v[214:217], v[2:5]
	v_mfma_f32_16x16x32_bf16 v[6:9], v[130:133], v[214:217], v[6:9]
	v_mfma_f32_16x16x32_bf16 v[6:9], v[118:121], v[210:213], v[6:9]
	v_mfma_f32_16x16x32_bf16 v[10:13], v[94:97], v[210:213], v[10:13]
	v_mfma_f32_16x16x32_bf16 v[10:13], v[106:109], v[214:217], v[10:13]
	v_mfma_f32_16x16x32_bf16 v[14:17], v[82:85], v[214:217], v[14:17]
	v_mfma_f32_16x16x32_bf16 v[14:17], v[70:73], v[210:213], v[14:17]
	s_barrier
	s_add_i32 s41, s41, 2
	s_add_u32 s7, s7, 0x100
	s_addc_u32 s23, s23, 0
	s_cmpk_gt_u32 s41, 0x55
	s_mov_b64 s[8:9], s[64:65]
	s_cbranch_scc1 .LBB0_648
	s_branch .LBB0_646
